# s5_pass2 scan fully unrolled: immediate LDS offsets, accumulator pairs swap roles, exact lgkmcnt, no address/copy VALU per iteration
# baseline (speedup 1.0000x reference)
; __device__ __forceinline__ bf f2bf(float f) { return (bf)(pk2(f, 0.f) & 0xFFFFu); }
; __device__ __forceinline__ void s5_pass2(const Params& p, int layer, int task, char* sm) {
;     ...
;     for (int sub = 0; sub < 4; sub++) {
;       __builtin_amdgcn_wave_barrier();
;       if (lane < 32) s5_st_u(sU + lane * 16, ua, ub);
;       {
;         const int nsub = (sub + 1) & 3; const int ng = g + (sub == 3 ? 1 : 0);
;         if (sub < 3 || gi < 7) s5_ld_u(p, tok0 + nsub * 32 + (lane & 31), ng, ua, ub);
;       }
;       __builtin_amdgcn_wave_barrier();
;       for (int l = 0; l < 32; l++) {
;         S5_STEP(sU + l * 16)
;         sS[l * 136 + lane] = f2bf(sr); sS[l * 136 + 64 + lane] = f2bf(si);
.LBB0_1796:
	v_add_u32_e32 v103, v79, v40
	ds_read_b128 v[104:107], v79
	ds_read_b128 v[108:111], v79 offset:16
	ds_read_b128 v[112:115], v79 offset:32
	ds_read_b128 v[116:119], v79 offset:48
	ds_read_b128 v[120:123], v79 offset:64
	ds_read_b128 v[124:127], v79 offset:80
	ds_read_b128 v[128:131], v79 offset:96
	ds_read_b128 v[132:135], v79 offset:112
	s_waitcnt lgkmcnt(7)
	s_waitcnt lgkmcnt(3)
	v_pk_mul_f32 v[140:141], v[20:21], v[104:105] op_sel:[0,1]
	v_pk_mul_f32 v[142:143], v[20:21], v[120:121] op_sel:[0,1]
	v_pk_fma_f32 v[140:141], v[52:53], v[104:105], v[140:141] op_sel_hi:[1,0,1]
	v_pk_fma_f32 v[142:143], v[52:53], v[120:121], v[142:143] op_sel_hi:[1,0,1]
	v_pk_fma_f32 v[140:141], v[54:55], v[106:107], v[140:141] op_sel_hi:[1,0,1]
	v_pk_fma_f32 v[142:143], v[54:55], v[122:123], v[142:143] op_sel_hi:[1,0,1]
	v_pk_fma_f32 v[140:141], v[22:23], v[106:107], v[140:141] op_sel:[0,1,0]
	v_pk_fma_f32 v[142:143], v[22:23], v[122:123], v[142:143] op_sel:[0,1,0]
	ds_read_b128 v[104:107], v79 offset:128
	ds_read_b128 v[120:123], v79 offset:192
	s_waitcnt lgkmcnt(8)
	s_waitcnt lgkmcnt(4)
	v_pk_fma_f32 v[140:141], v[56:57], v[108:109], v[140:141] op_sel_hi:[1,0,1]
	v_pk_fma_f32 v[142:143], v[56:57], v[124:125], v[142:143] op_sel_hi:[1,0,1]
	v_pk_fma_f32 v[140:141], v[16:17], v[108:109], v[140:141] op_sel:[0,1,0]
	v_pk_fma_f32 v[142:143], v[16:17], v[124:125], v[142:143] op_sel:[0,1,0]
	v_pk_fma_f32 v[140:141], v[58:59], v[110:111], v[140:141] op_sel_hi:[1,0,1]
	v_pk_fma_f32 v[142:143], v[58:59], v[126:127], v[142:143] op_sel_hi:[1,0,1]
	v_pk_fma_f32 v[140:141], v[18:19], v[110:111], v[140:141] op_sel:[0,1,0]
	v_pk_fma_f32 v[142:143], v[18:19], v[126:127], v[142:143] op_sel:[0,1,0]
	ds_read_b128 v[108:111], v79 offset:144
	ds_read_b128 v[124:127], v79 offset:208
	s_waitcnt lgkmcnt(9)
	s_waitcnt lgkmcnt(5)
	v_pk_fma_f32 v[140:141], v[60:61], v[112:113], v[140:141] op_sel_hi:[1,0,1]
	v_pk_fma_f32 v[142:143], v[60:61], v[128:129], v[142:143] op_sel_hi:[1,0,1]
	v_pk_fma_f32 v[140:141], v[12:13], v[112:113], v[140:141] op_sel:[0,1,0]
	v_pk_fma_f32 v[142:143], v[12:13], v[128:129], v[142:143] op_sel:[0,1,0]
	v_pk_fma_f32 v[140:141], v[62:63], v[114:115], v[140:141] op_sel_hi:[1,0,1]
	v_pk_fma_f32 v[142:143], v[62:63], v[130:131], v[142:143] op_sel_hi:[1,0,1]
	v_pk_fma_f32 v[140:141], v[14:15], v[114:115], v[140:141] op_sel:[0,1,0]
	v_pk_fma_f32 v[142:143], v[14:15], v[130:131], v[142:143] op_sel:[0,1,0]
	ds_read_b128 v[112:115], v79 offset:160
	ds_read_b128 v[128:131], v79 offset:224
	s_waitcnt lgkmcnt(10)
	s_waitcnt lgkmcnt(6)
	v_pk_fma_f32 v[140:141], v[64:65], v[116:117], v[140:141] op_sel_hi:[1,0,1]
	v_pk_fma_f32 v[142:143], v[64:65], v[132:133], v[142:143] op_sel_hi:[1,0,1]
	v_pk_fma_f32 v[140:141], v[8:9], v[116:117], v[140:141] op_sel:[0,1,0]
	v_pk_fma_f32 v[142:143], v[8:9], v[132:133], v[142:143] op_sel:[0,1,0]
	v_pk_fma_f32 v[140:141], v[66:67], v[118:119], v[140:141] op_sel_hi:[1,0,1]
	v_pk_fma_f32 v[142:143], v[66:67], v[134:135], v[142:143] op_sel_hi:[1,0,1]
	v_pk_fma_f32 v[140:141], v[10:11], v[118:119], v[140:141] op_sel:[0,1,0]
	v_pk_fma_f32 v[142:143], v[10:11], v[134:135], v[142:143] op_sel:[0,1,0]
	ds_read_b128 v[116:119], v79 offset:176
	ds_read_b128 v[132:135], v79 offset:240
	s_waitcnt vmcnt(5)
	s_waitcnt lgkmcnt(7)
	s_waitcnt lgkmcnt(6)
	v_pk_mul_f32 v[136:137], v[20:21], v[104:105] op_sel:[0,1]
	v_pk_mul_f32 v[138:139], v[20:21], v[120:121] op_sel:[0,1]
	v_pk_mul_f32 v[76:77], v[74:75], v[70:71] op_sel:[0,1]
	v_pk_fma_f32 v[136:137], v[52:53], v[104:105], v[136:137] op_sel_hi:[1,0,1]
	v_pk_fma_f32 v[138:139], v[52:53], v[120:121], v[138:139] op_sel_hi:[1,0,1]
	v_pk_fma_f32 v[146:147], v[68:69], v[70:71], v[76:77] op_sel_hi:[1,0,1] neg_lo:[0,0,1]
	v_pk_fma_f32 v[136:137], v[54:55], v[106:107], v[136:137] op_sel_hi:[1,0,1]
	v_pk_fma_f32 v[138:139], v[54:55], v[122:123], v[138:139] op_sel_hi:[1,0,1]
	v_pk_add_f32 v[42:43], v[146:147], v[140:141]
	v_pk_fma_f32 v[136:137], v[22:23], v[106:107], v[136:137] op_sel:[0,1,0]
	v_pk_fma_f32 v[138:139], v[22:23], v[122:123], v[138:139] op_sel:[0,1,0]
	v_cvt_pk_bf16_f32 v150, v42, v43
	ds_write_b16 v103, v150
	ds_write_b16_d16_hi v103, v150 offset:128
	ds_read_b128 v[104:107], v79 offset:256
	ds_read_b128 v[120:123], v79 offset:320
	s_waitcnt lgkmcnt(9)
	s_waitcnt lgkmcnt(8)
	v_pk_fma_f32 v[136:137], v[56:57], v[108:109], v[136:137] op_sel_hi:[1,0,1]
	v_pk_fma_f32 v[138:139], v[56:57], v[124:125], v[138:139] op_sel_hi:[1,0,1]
	v_pk_mul_f32 v[76:77], v[74:75], v[42:43] op_sel:[0,1]
	v_pk_fma_f32 v[136:137], v[16:17], v[108:109], v[136:137] op_sel:[0,1,0]
	v_pk_fma_f32 v[138:139], v[16:17], v[124:125], v[138:139] op_sel:[0,1,0]
	v_pk_fma_f32 v[146:147], v[68:69], v[42:43], v[76:77] op_sel_hi:[1,0,1] neg_lo:[0,0,1]
	v_pk_fma_f32 v[136:137], v[58:59], v[110:111], v[136:137] op_sel_hi:[1,0,1]
	v_pk_fma_f32 v[138:139], v[58:59], v[126:127], v[138:139] op_sel_hi:[1,0,1]
	v_pk_add_f32 v[70:71], v[146:147], v[142:143]
	v_pk_fma_f32 v[136:137], v[18:19], v[110:111], v[136:137] op_sel:[0,1,0]
	v_pk_fma_f32 v[138:139], v[18:19], v[126:127], v[138:139] op_sel:[0,1,0]
	v_cvt_pk_bf16_f32 v150, v70, v71
	ds_write_b16 v103, v150 offset:272
	ds_write_b16_d16_hi v103, v150 offset:400
	ds_read_b128 v[108:111], v79 offset:272
	ds_read_b128 v[124:127], v79 offset:336
	s_waitcnt lgkmcnt(11)
	s_waitcnt lgkmcnt(10)
; __device__ __forceinline__ bf f2bf(float f) { return (bf)(pk2(f, 0.f) & 0xFFFFu); }
; __device__ __forceinline__ void s5_pass2(const Params& p, int layer, int task, char* sm) {
;     ...
;       for (int l = 0; l < 32; l++) {
;         S5_STEP(sU + l * 16)
;         sS[l * 136 + lane] = f2bf(sr); sS[l * 136 + 64 + lane] = f2bf(si);
	v_pk_fma_f32 v[136:137], v[60:61], v[112:113], v[136:137] op_sel_hi:[1,0,1]
	v_pk_fma_f32 v[138:139], v[60:61], v[128:129], v[138:139] op_sel_hi:[1,0,1]
	v_pk_fma_f32 v[136:137], v[12:13], v[112:113], v[136:137] op_sel:[0,1,0]
	v_pk_fma_f32 v[138:139], v[12:13], v[128:129], v[138:139] op_sel:[0,1,0]
	v_pk_fma_f32 v[136:137], v[62:63], v[114:115], v[136:137] op_sel_hi:[1,0,1]
	v_pk_fma_f32 v[138:139], v[62:63], v[130:131], v[138:139] op_sel_hi:[1,0,1]
	v_pk_fma_f32 v[136:137], v[14:15], v[114:115], v[136:137] op_sel:[0,1,0]
	v_pk_fma_f32 v[138:139], v[14:15], v[130:131], v[138:139] op_sel:[0,1,0]
	ds_read_b128 v[112:115], v79 offset:288
	ds_read_b128 v[128:131], v79 offset:352
	s_waitcnt lgkmcnt(11)
	s_waitcnt lgkmcnt(10)
	v_pk_fma_f32 v[136:137], v[64:65], v[116:117], v[136:137] op_sel_hi:[1,0,1]
	v_pk_fma_f32 v[138:139], v[64:65], v[132:133], v[138:139] op_sel_hi:[1,0,1]
	v_pk_fma_f32 v[136:137], v[8:9], v[116:117], v[136:137] op_sel:[0,1,0]
	v_pk_fma_f32 v[138:139], v[8:9], v[132:133], v[138:139] op_sel:[0,1,0]
	v_pk_fma_f32 v[136:137], v[66:67], v[118:119], v[136:137] op_sel_hi:[1,0,1]
	v_pk_fma_f32 v[138:139], v[66:67], v[134:135], v[138:139] op_sel_hi:[1,0,1]
	v_pk_fma_f32 v[136:137], v[10:11], v[118:119], v[136:137] op_sel:[0,1,0]
	v_pk_fma_f32 v[138:139], v[10:11], v[134:135], v[138:139] op_sel:[0,1,0]
	ds_read_b128 v[116:119], v79 offset:304
	ds_read_b128 v[132:135], v79 offset:368
	s_waitcnt lgkmcnt(9)
	s_waitcnt lgkmcnt(8)
	v_pk_mul_f32 v[140:141], v[20:21], v[104:105] op_sel:[0,1]
	v_pk_mul_f32 v[142:143], v[20:21], v[120:121] op_sel:[0,1]
	v_pk_mul_f32 v[76:77], v[74:75], v[70:71] op_sel:[0,1]
	v_pk_fma_f32 v[140:141], v[52:53], v[104:105], v[140:141] op_sel_hi:[1,0,1]
	v_pk_fma_f32 v[142:143], v[52:53], v[120:121], v[142:143] op_sel_hi:[1,0,1]
	v_pk_fma_f32 v[146:147], v[68:69], v[70:71], v[76:77] op_sel_hi:[1,0,1] neg_lo:[0,0,1]
	v_pk_fma_f32 v[140:141], v[54:55], v[106:107], v[140:141] op_sel_hi:[1,0,1]
	v_pk_fma_f32 v[142:143], v[54:55], v[122:123], v[142:143] op_sel_hi:[1,0,1]
	v_pk_add_f32 v[42:43], v[146:147], v[136:137]
	v_pk_fma_f32 v[140:141], v[22:23], v[106:107], v[140:141] op_sel:[0,1,0]
	v_pk_fma_f32 v[142:143], v[22:23], v[122:123], v[142:143] op_sel:[0,1,0]
	v_cvt_pk_bf16_f32 v150, v42, v43
	ds_write_b16 v103, v150 offset:544
	ds_write_b16_d16_hi v103, v150 offset:672
	ds_read_b128 v[104:107], v79 offset:384
	ds_read_b128 v[120:123], v79 offset:448
	s_waitcnt lgkmcnt(9)
	s_waitcnt lgkmcnt(8)
	v_pk_fma_f32 v[140:141], v[56:57], v[108:109], v[140:141] op_sel_hi:[1,0,1]
	v_pk_fma_f32 v[142:143], v[56:57], v[124:125], v[142:143] op_sel_hi:[1,0,1]
	v_pk_mul_f32 v[76:77], v[74:75], v[42:43] op_sel:[0,1]
	v_pk_fma_f32 v[140:141], v[16:17], v[108:109], v[140:141] op_sel:[0,1,0]
	v_pk_fma_f32 v[142:143], v[16:17], v[124:125], v[142:143] op_sel:[0,1,0]
	v_pk_fma_f32 v[146:147], v[68:69], v[42:43], v[76:77] op_sel_hi:[1,0,1] neg_lo:[0,0,1]
	v_pk_fma_f32 v[140:141], v[58:59], v[110:111], v[140:141] op_sel_hi:[1,0,1]
	v_pk_fma_f32 v[142:143], v[58:59], v[126:127], v[142:143] op_sel_hi:[1,0,1]
	v_pk_add_f32 v[70:71], v[146:147], v[138:139]
	v_pk_fma_f32 v[140:141], v[18:19], v[110:111], v[140:141] op_sel:[0,1,0]
	v_pk_fma_f32 v[142:143], v[18:19], v[126:127], v[142:143] op_sel:[0,1,0]
	v_cvt_pk_bf16_f32 v150, v70, v71
	ds_write_b16 v103, v150 offset:816
	ds_write_b16_d16_hi v103, v150 offset:944
	ds_read_b128 v[108:111], v79 offset:400
	ds_read_b128 v[124:127], v79 offset:464
	s_waitcnt lgkmcnt(11)
	s_waitcnt lgkmcnt(10)
	v_pk_fma_f32 v[140:141], v[60:61], v[112:113], v[140:141] op_sel_hi:[1,0,1]
	v_pk_fma_f32 v[142:143], v[60:61], v[128:129], v[142:143] op_sel_hi:[1,0,1]
	v_pk_fma_f32 v[140:141], v[12:13], v[112:113], v[140:141] op_sel:[0,1,0]
	v_pk_fma_f32 v[142:143], v[12:13], v[128:129], v[142:143] op_sel:[0,1,0]
	v_pk_fma_f32 v[140:141], v[62:63], v[114:115], v[140:141] op_sel_hi:[1,0,1]
	v_pk_fma_f32 v[142:143], v[62:63], v[130:131], v[142:143] op_sel_hi:[1,0,1]
	v_pk_fma_f32 v[140:141], v[14:15], v[114:115], v[140:141] op_sel:[0,1,0]
	v_pk_fma_f32 v[142:143], v[14:15], v[130:131], v[142:143] op_sel:[0,1,0]
	ds_read_b128 v[112:115], v79 offset:416
	ds_read_b128 v[128:131], v79 offset:480
	s_waitcnt lgkmcnt(11)
	s_waitcnt lgkmcnt(10)
	v_pk_fma_f32 v[140:141], v[64:65], v[116:117], v[140:141] op_sel_hi:[1,0,1]
	v_pk_fma_f32 v[142:143], v[64:65], v[132:133], v[142:143] op_sel_hi:[1,0,1]
	v_pk_fma_f32 v[140:141], v[8:9], v[116:117], v[140:141] op_sel:[0,1,0]
	v_pk_fma_f32 v[142:143], v[8:9], v[132:133], v[142:143] op_sel:[0,1,0]
	v_pk_fma_f32 v[140:141], v[66:67], v[118:119], v[140:141] op_sel_hi:[1,0,1]
	v_pk_fma_f32 v[142:143], v[66:67], v[134:135], v[142:143] op_sel_hi:[1,0,1]
	v_pk_fma_f32 v[140:141], v[10:11], v[118:119], v[140:141] op_sel:[0,1,0]
	v_pk_fma_f32 v[142:143], v[10:11], v[134:135], v[142:143] op_sel:[0,1,0]
	ds_read_b128 v[116:119], v79 offset:432
	ds_read_b128 v[132:135], v79 offset:496
	s_waitcnt lgkmcnt(9)
	s_waitcnt lgkmcnt(8)
	v_pk_mul_f32 v[136:137], v[20:21], v[104:105] op_sel:[0,1]
	v_pk_mul_f32 v[138:139], v[20:21], v[120:121] op_sel:[0,1]
	v_pk_mul_f32 v[76:77], v[74:75], v[70:71] op_sel:[0,1]
	v_pk_fma_f32 v[136:137], v[52:53], v[104:105], v[136:137] op_sel_hi:[1,0,1]
	v_pk_fma_f32 v[138:139], v[52:53], v[120:121], v[138:139] op_sel_hi:[1,0,1]
	v_pk_fma_f32 v[146:147], v[68:69], v[70:71], v[76:77] op_sel_hi:[1,0,1] neg_lo:[0,0,1]
	v_pk_fma_f32 v[136:137], v[54:55], v[106:107], v[136:137] op_sel_hi:[1,0,1]
	v_pk_fma_f32 v[138:139], v[54:55], v[122:123], v[138:139] op_sel_hi:[1,0,1]
	v_pk_add_f32 v[42:43], v[146:147], v[140:141]
	v_pk_fma_f32 v[136:137], v[22:23], v[106:107], v[136:137] op_sel:[0,1,0]
	v_pk_fma_f32 v[138:139], v[22:23], v[122:123], v[138:139] op_sel:[0,1,0]
	v_cvt_pk_bf16_f32 v150, v42, v43
	ds_write_b16 v103, v150 offset:1088
	ds_write_b16_d16_hi v103, v150 offset:1216
	ds_read_b128 v[104:107], v79 offset:512
	ds_read_b128 v[120:123], v79 offset:576
	s_waitcnt lgkmcnt(9)
; __device__ __forceinline__ bf f2bf(float f) { return (bf)(pk2(f, 0.f) & 0xFFFFu); }
; __device__ __forceinline__ void s5_pass2(const Params& p, int layer, int task, char* sm) {
;     ...
;       for (int l = 0; l < 32; l++) {
;         S5_STEP(sU + l * 16)
;         sS[l * 136 + lane] = f2bf(sr); sS[l * 136 + 64 + lane] = f2bf(si);
	s_waitcnt lgkmcnt(8)
	v_pk_fma_f32 v[136:137], v[56:57], v[108:109], v[136:137] op_sel_hi:[1,0,1]
	v_pk_fma_f32 v[138:139], v[56:57], v[124:125], v[138:139] op_sel_hi:[1,0,1]
	v_pk_mul_f32 v[76:77], v[74:75], v[42:43] op_sel:[0,1]
	v_pk_fma_f32 v[136:137], v[16:17], v[108:109], v[136:137] op_sel:[0,1,0]
	v_pk_fma_f32 v[138:139], v[16:17], v[124:125], v[138:139] op_sel:[0,1,0]
	v_pk_fma_f32 v[146:147], v[68:69], v[42:43], v[76:77] op_sel_hi:[1,0,1] neg_lo:[0,0,1]
	v_pk_fma_f32 v[136:137], v[58:59], v[110:111], v[136:137] op_sel_hi:[1,0,1]
	v_pk_fma_f32 v[138:139], v[58:59], v[126:127], v[138:139] op_sel_hi:[1,0,1]
	v_pk_add_f32 v[70:71], v[146:147], v[142:143]
	v_pk_fma_f32 v[136:137], v[18:19], v[110:111], v[136:137] op_sel:[0,1,0]
	v_pk_fma_f32 v[138:139], v[18:19], v[126:127], v[138:139] op_sel:[0,1,0]
	v_cvt_pk_bf16_f32 v150, v70, v71
	ds_write_b16 v103, v150 offset:1360
	ds_write_b16_d16_hi v103, v150 offset:1488
	ds_read_b128 v[108:111], v79 offset:528
	ds_read_b128 v[124:127], v79 offset:592
	s_waitcnt lgkmcnt(11)
	s_waitcnt lgkmcnt(10)
	v_pk_fma_f32 v[136:137], v[60:61], v[112:113], v[136:137] op_sel_hi:[1,0,1]
	v_pk_fma_f32 v[138:139], v[60:61], v[128:129], v[138:139] op_sel_hi:[1,0,1]
	v_pk_fma_f32 v[136:137], v[12:13], v[112:113], v[136:137] op_sel:[0,1,0]
	v_pk_fma_f32 v[138:139], v[12:13], v[128:129], v[138:139] op_sel:[0,1,0]
	v_pk_fma_f32 v[136:137], v[62:63], v[114:115], v[136:137] op_sel_hi:[1,0,1]
	v_pk_fma_f32 v[138:139], v[62:63], v[130:131], v[138:139] op_sel_hi:[1,0,1]
	v_pk_fma_f32 v[136:137], v[14:15], v[114:115], v[136:137] op_sel:[0,1,0]
	v_pk_fma_f32 v[138:139], v[14:15], v[130:131], v[138:139] op_sel:[0,1,0]
	ds_read_b128 v[112:115], v79 offset:544
	ds_read_b128 v[128:131], v79 offset:608
	s_waitcnt lgkmcnt(11)
	s_waitcnt lgkmcnt(10)
	v_pk_fma_f32 v[136:137], v[64:65], v[116:117], v[136:137] op_sel_hi:[1,0,1]
	v_pk_fma_f32 v[138:139], v[64:65], v[132:133], v[138:139] op_sel_hi:[1,0,1]
	v_pk_fma_f32 v[136:137], v[8:9], v[116:117], v[136:137] op_sel:[0,1,0]
	v_pk_fma_f32 v[138:139], v[8:9], v[132:133], v[138:139] op_sel:[0,1,0]
	v_pk_fma_f32 v[136:137], v[66:67], v[118:119], v[136:137] op_sel_hi:[1,0,1]
	v_pk_fma_f32 v[138:139], v[66:67], v[134:135], v[138:139] op_sel_hi:[1,0,1]
	v_pk_fma_f32 v[136:137], v[10:11], v[118:119], v[136:137] op_sel:[0,1,0]
	v_pk_fma_f32 v[138:139], v[10:11], v[134:135], v[138:139] op_sel:[0,1,0]
	ds_read_b128 v[116:119], v79 offset:560
	ds_read_b128 v[132:135], v79 offset:624
	s_waitcnt lgkmcnt(9)
	s_waitcnt lgkmcnt(8)
	v_pk_mul_f32 v[140:141], v[20:21], v[104:105] op_sel:[0,1]
	v_pk_mul_f32 v[142:143], v[20:21], v[120:121] op_sel:[0,1]
	v_pk_mul_f32 v[76:77], v[74:75], v[70:71] op_sel:[0,1]
	v_pk_fma_f32 v[140:141], v[52:53], v[104:105], v[140:141] op_sel_hi:[1,0,1]
	v_pk_fma_f32 v[142:143], v[52:53], v[120:121], v[142:143] op_sel_hi:[1,0,1]
	v_pk_fma_f32 v[146:147], v[68:69], v[70:71], v[76:77] op_sel_hi:[1,0,1] neg_lo:[0,0,1]
	v_pk_fma_f32 v[140:141], v[54:55], v[106:107], v[140:141] op_sel_hi:[1,0,1]
	v_pk_fma_f32 v[142:143], v[54:55], v[122:123], v[142:143] op_sel_hi:[1,0,1]
	v_pk_add_f32 v[42:43], v[146:147], v[136:137]
	v_pk_fma_f32 v[140:141], v[22:23], v[106:107], v[140:141] op_sel:[0,1,0]
	v_pk_fma_f32 v[142:143], v[22:23], v[122:123], v[142:143] op_sel:[0,1,0]
	v_cvt_pk_bf16_f32 v150, v42, v43
	ds_write_b16 v103, v150 offset:1632
	ds_write_b16_d16_hi v103, v150 offset:1760
	ds_read_b128 v[104:107], v79 offset:640
	ds_read_b128 v[120:123], v79 offset:704
	s_waitcnt lgkmcnt(9)
	s_waitcnt lgkmcnt(8)
	v_pk_fma_f32 v[140:141], v[56:57], v[108:109], v[140:141] op_sel_hi:[1,0,1]
	v_pk_fma_f32 v[142:143], v[56:57], v[124:125], v[142:143] op_sel_hi:[1,0,1]
	v_pk_mul_f32 v[76:77], v[74:75], v[42:43] op_sel:[0,1]
	v_pk_fma_f32 v[140:141], v[16:17], v[108:109], v[140:141] op_sel:[0,1,0]
	v_pk_fma_f32 v[142:143], v[16:17], v[124:125], v[142:143] op_sel:[0,1,0]
	v_pk_fma_f32 v[146:147], v[68:69], v[42:43], v[76:77] op_sel_hi:[1,0,1] neg_lo:[0,0,1]
	v_pk_fma_f32 v[140:141], v[58:59], v[110:111], v[140:141] op_sel_hi:[1,0,1]
	v_pk_fma_f32 v[142:143], v[58:59], v[126:127], v[142:143] op_sel_hi:[1,0,1]
	v_pk_add_f32 v[70:71], v[146:147], v[138:139]
	v_pk_fma_f32 v[140:141], v[18:19], v[110:111], v[140:141] op_sel:[0,1,0]
	v_pk_fma_f32 v[142:143], v[18:19], v[126:127], v[142:143] op_sel:[0,1,0]
	v_cvt_pk_bf16_f32 v150, v70, v71
	ds_write_b16 v103, v150 offset:1904
	ds_write_b16_d16_hi v103, v150 offset:2032
	ds_read_b128 v[108:111], v79 offset:656
	ds_read_b128 v[124:127], v79 offset:720
	s_waitcnt lgkmcnt(11)
	s_waitcnt lgkmcnt(10)
	v_pk_fma_f32 v[140:141], v[60:61], v[112:113], v[140:141] op_sel_hi:[1,0,1]
	v_pk_fma_f32 v[142:143], v[60:61], v[128:129], v[142:143] op_sel_hi:[1,0,1]
	v_pk_fma_f32 v[140:141], v[12:13], v[112:113], v[140:141] op_sel:[0,1,0]
	v_pk_fma_f32 v[142:143], v[12:13], v[128:129], v[142:143] op_sel:[0,1,0]
	v_pk_fma_f32 v[140:141], v[62:63], v[114:115], v[140:141] op_sel_hi:[1,0,1]
	v_pk_fma_f32 v[142:143], v[62:63], v[130:131], v[142:143] op_sel_hi:[1,0,1]
	v_pk_fma_f32 v[140:141], v[14:15], v[114:115], v[140:141] op_sel:[0,1,0]
	v_pk_fma_f32 v[142:143], v[14:15], v[130:131], v[142:143] op_sel:[0,1,0]
	ds_read_b128 v[112:115], v79 offset:672
	ds_read_b128 v[128:131], v79 offset:736
	s_waitcnt lgkmcnt(11)
	s_waitcnt lgkmcnt(10)
; __device__ __forceinline__ bf f2bf(float f) { return (bf)(pk2(f, 0.f) & 0xFFFFu); }
; __device__ __forceinline__ void s5_pass2(const Params& p, int layer, int task, char* sm) {
;     ...
;       for (int l = 0; l < 32; l++) {
;         S5_STEP(sU + l * 16)
;         sS[l * 136 + lane] = f2bf(sr); sS[l * 136 + 64 + lane] = f2bf(si);
	v_pk_fma_f32 v[140:141], v[64:65], v[116:117], v[140:141] op_sel_hi:[1,0,1]
	v_pk_fma_f32 v[142:143], v[64:65], v[132:133], v[142:143] op_sel_hi:[1,0,1]
	v_pk_fma_f32 v[140:141], v[8:9], v[116:117], v[140:141] op_sel:[0,1,0]
	v_pk_fma_f32 v[142:143], v[8:9], v[132:133], v[142:143] op_sel:[0,1,0]
	v_pk_fma_f32 v[140:141], v[66:67], v[118:119], v[140:141] op_sel_hi:[1,0,1]
	v_pk_fma_f32 v[142:143], v[66:67], v[134:135], v[142:143] op_sel_hi:[1,0,1]
	v_pk_fma_f32 v[140:141], v[10:11], v[118:119], v[140:141] op_sel:[0,1,0]
	v_pk_fma_f32 v[142:143], v[10:11], v[134:135], v[142:143] op_sel:[0,1,0]
	ds_read_b128 v[116:119], v79 offset:688
	ds_read_b128 v[132:135], v79 offset:752
	s_waitcnt lgkmcnt(9)
	s_waitcnt lgkmcnt(8)
	v_pk_mul_f32 v[136:137], v[20:21], v[104:105] op_sel:[0,1]
	v_pk_mul_f32 v[138:139], v[20:21], v[120:121] op_sel:[0,1]
	v_pk_mul_f32 v[76:77], v[74:75], v[70:71] op_sel:[0,1]
	v_pk_fma_f32 v[136:137], v[52:53], v[104:105], v[136:137] op_sel_hi:[1,0,1]
	v_pk_fma_f32 v[138:139], v[52:53], v[120:121], v[138:139] op_sel_hi:[1,0,1]
	v_pk_fma_f32 v[146:147], v[68:69], v[70:71], v[76:77] op_sel_hi:[1,0,1] neg_lo:[0,0,1]
	v_pk_fma_f32 v[136:137], v[54:55], v[106:107], v[136:137] op_sel_hi:[1,0,1]
	v_pk_fma_f32 v[138:139], v[54:55], v[122:123], v[138:139] op_sel_hi:[1,0,1]
	v_pk_add_f32 v[42:43], v[146:147], v[140:141]
	v_pk_fma_f32 v[136:137], v[22:23], v[106:107], v[136:137] op_sel:[0,1,0]
	v_pk_fma_f32 v[138:139], v[22:23], v[122:123], v[138:139] op_sel:[0,1,0]
	v_cvt_pk_bf16_f32 v150, v42, v43
	ds_write_b16 v103, v150 offset:2176
	ds_write_b16_d16_hi v103, v150 offset:2304
	ds_read_b128 v[104:107], v79 offset:768
	ds_read_b128 v[120:123], v79 offset:832
	s_waitcnt lgkmcnt(9)
	s_waitcnt lgkmcnt(8)
	v_pk_fma_f32 v[136:137], v[56:57], v[108:109], v[136:137] op_sel_hi:[1,0,1]
	v_pk_fma_f32 v[138:139], v[56:57], v[124:125], v[138:139] op_sel_hi:[1,0,1]
	v_pk_mul_f32 v[76:77], v[74:75], v[42:43] op_sel:[0,1]
	v_pk_fma_f32 v[136:137], v[16:17], v[108:109], v[136:137] op_sel:[0,1,0]
	v_pk_fma_f32 v[138:139], v[16:17], v[124:125], v[138:139] op_sel:[0,1,0]
	v_pk_fma_f32 v[146:147], v[68:69], v[42:43], v[76:77] op_sel_hi:[1,0,1] neg_lo:[0,0,1]
	v_pk_fma_f32 v[136:137], v[58:59], v[110:111], v[136:137] op_sel_hi:[1,0,1]
	v_pk_fma_f32 v[138:139], v[58:59], v[126:127], v[138:139] op_sel_hi:[1,0,1]
	v_pk_add_f32 v[70:71], v[146:147], v[142:143]
	v_pk_fma_f32 v[136:137], v[18:19], v[110:111], v[136:137] op_sel:[0,1,0]
	v_pk_fma_f32 v[138:139], v[18:19], v[126:127], v[138:139] op_sel:[0,1,0]
	v_cvt_pk_bf16_f32 v150, v70, v71
	ds_write_b16 v103, v150 offset:2448
	ds_write_b16_d16_hi v103, v150 offset:2576
	ds_read_b128 v[108:111], v79 offset:784
	ds_read_b128 v[124:127], v79 offset:848
	s_waitcnt lgkmcnt(11)
	s_waitcnt lgkmcnt(10)
	v_pk_fma_f32 v[136:137], v[60:61], v[112:113], v[136:137] op_sel_hi:[1,0,1]
	v_pk_fma_f32 v[138:139], v[60:61], v[128:129], v[138:139] op_sel_hi:[1,0,1]
	v_pk_fma_f32 v[136:137], v[12:13], v[112:113], v[136:137] op_sel:[0,1,0]
	v_pk_fma_f32 v[138:139], v[12:13], v[128:129], v[138:139] op_sel:[0,1,0]
	v_pk_fma_f32 v[136:137], v[62:63], v[114:115], v[136:137] op_sel_hi:[1,0,1]
	v_pk_fma_f32 v[138:139], v[62:63], v[130:131], v[138:139] op_sel_hi:[1,0,1]
	v_pk_fma_f32 v[136:137], v[14:15], v[114:115], v[136:137] op_sel:[0,1,0]
	v_pk_fma_f32 v[138:139], v[14:15], v[130:131], v[138:139] op_sel:[0,1,0]
	ds_read_b128 v[112:115], v79 offset:800
	ds_read_b128 v[128:131], v79 offset:864
	s_waitcnt lgkmcnt(11)
	s_waitcnt lgkmcnt(10)
	v_pk_fma_f32 v[136:137], v[64:65], v[116:117], v[136:137] op_sel_hi:[1,0,1]
	v_pk_fma_f32 v[138:139], v[64:65], v[132:133], v[138:139] op_sel_hi:[1,0,1]
	v_pk_fma_f32 v[136:137], v[8:9], v[116:117], v[136:137] op_sel:[0,1,0]
	v_pk_fma_f32 v[138:139], v[8:9], v[132:133], v[138:139] op_sel:[0,1,0]
	v_pk_fma_f32 v[136:137], v[66:67], v[118:119], v[136:137] op_sel_hi:[1,0,1]
	v_pk_fma_f32 v[138:139], v[66:67], v[134:135], v[138:139] op_sel_hi:[1,0,1]
	v_pk_fma_f32 v[136:137], v[10:11], v[118:119], v[136:137] op_sel:[0,1,0]
	v_pk_fma_f32 v[138:139], v[10:11], v[134:135], v[138:139] op_sel:[0,1,0]
	ds_read_b128 v[116:119], v79 offset:816
	ds_read_b128 v[132:135], v79 offset:880
	s_waitcnt lgkmcnt(9)
	s_waitcnt lgkmcnt(8)
	v_pk_mul_f32 v[140:141], v[20:21], v[104:105] op_sel:[0,1]
	v_pk_mul_f32 v[142:143], v[20:21], v[120:121] op_sel:[0,1]
	v_pk_mul_f32 v[76:77], v[74:75], v[70:71] op_sel:[0,1]
	v_pk_fma_f32 v[140:141], v[52:53], v[104:105], v[140:141] op_sel_hi:[1,0,1]
	v_pk_fma_f32 v[142:143], v[52:53], v[120:121], v[142:143] op_sel_hi:[1,0,1]
	v_pk_fma_f32 v[146:147], v[68:69], v[70:71], v[76:77] op_sel_hi:[1,0,1] neg_lo:[0,0,1]
	v_pk_fma_f32 v[140:141], v[54:55], v[106:107], v[140:141] op_sel_hi:[1,0,1]
	v_pk_fma_f32 v[142:143], v[54:55], v[122:123], v[142:143] op_sel_hi:[1,0,1]
	v_pk_add_f32 v[42:43], v[146:147], v[136:137]
	v_pk_fma_f32 v[140:141], v[22:23], v[106:107], v[140:141] op_sel:[0,1,0]
	v_pk_fma_f32 v[142:143], v[22:23], v[122:123], v[142:143] op_sel:[0,1,0]
	v_cvt_pk_bf16_f32 v150, v42, v43
	ds_write_b16 v103, v150 offset:2720
	ds_write_b16_d16_hi v103, v150 offset:2848
	ds_read_b128 v[104:107], v79 offset:896
	ds_read_b128 v[120:123], v79 offset:960
	s_waitcnt lgkmcnt(9)
	s_waitcnt lgkmcnt(8)
; __device__ __forceinline__ bf f2bf(float f) { return (bf)(pk2(f, 0.f) & 0xFFFFu); }
; __device__ __forceinline__ void s5_pass2(const Params& p, int layer, int task, char* sm) {
;     ...
;       for (int l = 0; l < 32; l++) {
;         S5_STEP(sU + l * 16)
;         sS[l * 136 + lane] = f2bf(sr); sS[l * 136 + 64 + lane] = f2bf(si);
	v_pk_fma_f32 v[140:141], v[56:57], v[108:109], v[140:141] op_sel_hi:[1,0,1]
	v_pk_fma_f32 v[142:143], v[56:57], v[124:125], v[142:143] op_sel_hi:[1,0,1]
	v_pk_mul_f32 v[76:77], v[74:75], v[42:43] op_sel:[0,1]
	v_pk_fma_f32 v[140:141], v[16:17], v[108:109], v[140:141] op_sel:[0,1,0]
	v_pk_fma_f32 v[142:143], v[16:17], v[124:125], v[142:143] op_sel:[0,1,0]
	v_pk_fma_f32 v[146:147], v[68:69], v[42:43], v[76:77] op_sel_hi:[1,0,1] neg_lo:[0,0,1]
	v_pk_fma_f32 v[140:141], v[58:59], v[110:111], v[140:141] op_sel_hi:[1,0,1]
	v_pk_fma_f32 v[142:143], v[58:59], v[126:127], v[142:143] op_sel_hi:[1,0,1]
	v_pk_add_f32 v[70:71], v[146:147], v[138:139]
	v_pk_fma_f32 v[140:141], v[18:19], v[110:111], v[140:141] op_sel:[0,1,0]
	v_pk_fma_f32 v[142:143], v[18:19], v[126:127], v[142:143] op_sel:[0,1,0]
	v_cvt_pk_bf16_f32 v150, v70, v71
	ds_write_b16 v103, v150 offset:2992
	ds_write_b16_d16_hi v103, v150 offset:3120
	ds_read_b128 v[108:111], v79 offset:912
	ds_read_b128 v[124:127], v79 offset:976
	s_waitcnt lgkmcnt(11)
	s_waitcnt lgkmcnt(10)
	v_pk_fma_f32 v[140:141], v[60:61], v[112:113], v[140:141] op_sel_hi:[1,0,1]
	v_pk_fma_f32 v[142:143], v[60:61], v[128:129], v[142:143] op_sel_hi:[1,0,1]
	v_pk_fma_f32 v[140:141], v[12:13], v[112:113], v[140:141] op_sel:[0,1,0]
	v_pk_fma_f32 v[142:143], v[12:13], v[128:129], v[142:143] op_sel:[0,1,0]
	v_pk_fma_f32 v[140:141], v[62:63], v[114:115], v[140:141] op_sel_hi:[1,0,1]
	v_pk_fma_f32 v[142:143], v[62:63], v[130:131], v[142:143] op_sel_hi:[1,0,1]
	v_pk_fma_f32 v[140:141], v[14:15], v[114:115], v[140:141] op_sel:[0,1,0]
	v_pk_fma_f32 v[142:143], v[14:15], v[130:131], v[142:143] op_sel:[0,1,0]
	ds_read_b128 v[112:115], v79 offset:928
	ds_read_b128 v[128:131], v79 offset:992
	s_waitcnt lgkmcnt(11)
	s_waitcnt lgkmcnt(10)
	v_pk_fma_f32 v[140:141], v[64:65], v[116:117], v[140:141] op_sel_hi:[1,0,1]
	v_pk_fma_f32 v[142:143], v[64:65], v[132:133], v[142:143] op_sel_hi:[1,0,1]
	v_pk_fma_f32 v[140:141], v[8:9], v[116:117], v[140:141] op_sel:[0,1,0]
	v_pk_fma_f32 v[142:143], v[8:9], v[132:133], v[142:143] op_sel:[0,1,0]
	v_pk_fma_f32 v[140:141], v[66:67], v[118:119], v[140:141] op_sel_hi:[1,0,1]
	v_pk_fma_f32 v[142:143], v[66:67], v[134:135], v[142:143] op_sel_hi:[1,0,1]
	v_pk_fma_f32 v[140:141], v[10:11], v[118:119], v[140:141] op_sel:[0,1,0]
	v_pk_fma_f32 v[142:143], v[10:11], v[134:135], v[142:143] op_sel:[0,1,0]
	ds_read_b128 v[116:119], v79 offset:944
	ds_read_b128 v[132:135], v79 offset:1008
	s_waitcnt lgkmcnt(9)
	s_waitcnt lgkmcnt(8)
	v_pk_mul_f32 v[136:137], v[20:21], v[104:105] op_sel:[0,1]
	v_pk_mul_f32 v[138:139], v[20:21], v[120:121] op_sel:[0,1]
	v_pk_mul_f32 v[76:77], v[74:75], v[70:71] op_sel:[0,1]
	v_pk_fma_f32 v[136:137], v[52:53], v[104:105], v[136:137] op_sel_hi:[1,0,1]
	v_pk_fma_f32 v[138:139], v[52:53], v[120:121], v[138:139] op_sel_hi:[1,0,1]
	v_pk_fma_f32 v[146:147], v[68:69], v[70:71], v[76:77] op_sel_hi:[1,0,1] neg_lo:[0,0,1]
	v_pk_fma_f32 v[136:137], v[54:55], v[106:107], v[136:137] op_sel_hi:[1,0,1]
	v_pk_fma_f32 v[138:139], v[54:55], v[122:123], v[138:139] op_sel_hi:[1,0,1]
	v_pk_add_f32 v[42:43], v[146:147], v[140:141]
	v_pk_fma_f32 v[136:137], v[22:23], v[106:107], v[136:137] op_sel:[0,1,0]
	v_pk_fma_f32 v[138:139], v[22:23], v[122:123], v[138:139] op_sel:[0,1,0]
	v_cvt_pk_bf16_f32 v150, v42, v43
	ds_write_b16 v103, v150 offset:3264
	ds_write_b16_d16_hi v103, v150 offset:3392
	ds_read_b128 v[104:107], v79 offset:1024
	ds_read_b128 v[120:123], v79 offset:1088
	s_waitcnt lgkmcnt(9)
	s_waitcnt lgkmcnt(8)
	v_pk_fma_f32 v[136:137], v[56:57], v[108:109], v[136:137] op_sel_hi:[1,0,1]
	v_pk_fma_f32 v[138:139], v[56:57], v[124:125], v[138:139] op_sel_hi:[1,0,1]
	v_pk_mul_f32 v[76:77], v[74:75], v[42:43] op_sel:[0,1]
	v_pk_fma_f32 v[136:137], v[16:17], v[108:109], v[136:137] op_sel:[0,1,0]
	v_pk_fma_f32 v[138:139], v[16:17], v[124:125], v[138:139] op_sel:[0,1,0]
	v_pk_fma_f32 v[146:147], v[68:69], v[42:43], v[76:77] op_sel_hi:[1,0,1] neg_lo:[0,0,1]
	v_pk_fma_f32 v[136:137], v[58:59], v[110:111], v[136:137] op_sel_hi:[1,0,1]
	v_pk_fma_f32 v[138:139], v[58:59], v[126:127], v[138:139] op_sel_hi:[1,0,1]
	v_pk_add_f32 v[70:71], v[146:147], v[142:143]
	v_pk_fma_f32 v[136:137], v[18:19], v[110:111], v[136:137] op_sel:[0,1,0]
	v_pk_fma_f32 v[138:139], v[18:19], v[126:127], v[138:139] op_sel:[0,1,0]
	v_cvt_pk_bf16_f32 v150, v70, v71
	ds_write_b16 v103, v150 offset:3536
	ds_write_b16_d16_hi v103, v150 offset:3664
	ds_read_b128 v[108:111], v79 offset:1040
	ds_read_b128 v[124:127], v79 offset:1104
	s_waitcnt lgkmcnt(11)
	s_waitcnt lgkmcnt(10)
	v_pk_fma_f32 v[136:137], v[60:61], v[112:113], v[136:137] op_sel_hi:[1,0,1]
	v_pk_fma_f32 v[138:139], v[60:61], v[128:129], v[138:139] op_sel_hi:[1,0,1]
	v_pk_fma_f32 v[136:137], v[12:13], v[112:113], v[136:137] op_sel:[0,1,0]
	v_pk_fma_f32 v[138:139], v[12:13], v[128:129], v[138:139] op_sel:[0,1,0]
	v_pk_fma_f32 v[136:137], v[62:63], v[114:115], v[136:137] op_sel_hi:[1,0,1]
	v_pk_fma_f32 v[138:139], v[62:63], v[130:131], v[138:139] op_sel_hi:[1,0,1]
	v_pk_fma_f32 v[136:137], v[14:15], v[114:115], v[136:137] op_sel:[0,1,0]
	v_pk_fma_f32 v[138:139], v[14:15], v[130:131], v[138:139] op_sel:[0,1,0]
	ds_read_b128 v[112:115], v79 offset:1056
	ds_read_b128 v[128:131], v79 offset:1120
	s_waitcnt lgkmcnt(11)
	s_waitcnt lgkmcnt(10)
	v_pk_fma_f32 v[136:137], v[64:65], v[116:117], v[136:137] op_sel_hi:[1,0,1]
	v_pk_fma_f32 v[138:139], v[64:65], v[132:133], v[138:139] op_sel_hi:[1,0,1]
	v_pk_fma_f32 v[136:137], v[8:9], v[116:117], v[136:137] op_sel:[0,1,0]
	v_pk_fma_f32 v[138:139], v[8:9], v[132:133], v[138:139] op_sel:[0,1,0]
	v_pk_fma_f32 v[136:137], v[66:67], v[118:119], v[136:137] op_sel_hi:[1,0,1]
	v_pk_fma_f32 v[138:139], v[66:67], v[134:135], v[138:139] op_sel_hi:[1,0,1]
	v_pk_fma_f32 v[136:137], v[10:11], v[118:119], v[136:137] op_sel:[0,1,0]
	v_pk_fma_f32 v[138:139], v[10:11], v[134:135], v[138:139] op_sel:[0,1,0]
	ds_read_b128 v[116:119], v79 offset:1072
	ds_read_b128 v[132:135], v79 offset:1136
	s_waitcnt lgkmcnt(9)
; __device__ __forceinline__ bf f2bf(float f) { return (bf)(pk2(f, 0.f) & 0xFFFFu); }
; __device__ __forceinline__ void s5_pass2(const Params& p, int layer, int task, char* sm) {
;     ...
;       for (int l = 0; l < 32; l++) {
;         S5_STEP(sU + l * 16)
;         sS[l * 136 + lane] = f2bf(sr); sS[l * 136 + 64 + lane] = f2bf(si);
	s_waitcnt lgkmcnt(8)
	v_pk_mul_f32 v[140:141], v[20:21], v[104:105] op_sel:[0,1]
	v_pk_mul_f32 v[142:143], v[20:21], v[120:121] op_sel:[0,1]
	v_pk_mul_f32 v[76:77], v[74:75], v[70:71] op_sel:[0,1]
	v_pk_fma_f32 v[140:141], v[52:53], v[104:105], v[140:141] op_sel_hi:[1,0,1]
	v_pk_fma_f32 v[142:143], v[52:53], v[120:121], v[142:143] op_sel_hi:[1,0,1]
	v_pk_fma_f32 v[146:147], v[68:69], v[70:71], v[76:77] op_sel_hi:[1,0,1] neg_lo:[0,0,1]
	v_pk_fma_f32 v[140:141], v[54:55], v[106:107], v[140:141] op_sel_hi:[1,0,1]
	v_pk_fma_f32 v[142:143], v[54:55], v[122:123], v[142:143] op_sel_hi:[1,0,1]
	v_pk_add_f32 v[42:43], v[146:147], v[136:137]
	v_pk_fma_f32 v[140:141], v[22:23], v[106:107], v[140:141] op_sel:[0,1,0]
	v_pk_fma_f32 v[142:143], v[22:23], v[122:123], v[142:143] op_sel:[0,1,0]
	v_cvt_pk_bf16_f32 v150, v42, v43
	ds_write_b16 v103, v150 offset:3808
	ds_write_b16_d16_hi v103, v150 offset:3936
	ds_read_b128 v[104:107], v79 offset:1152
	ds_read_b128 v[120:123], v79 offset:1216
	s_waitcnt lgkmcnt(9)
	s_waitcnt lgkmcnt(8)
	v_pk_fma_f32 v[140:141], v[56:57], v[108:109], v[140:141] op_sel_hi:[1,0,1]
	v_pk_fma_f32 v[142:143], v[56:57], v[124:125], v[142:143] op_sel_hi:[1,0,1]
	v_pk_mul_f32 v[76:77], v[74:75], v[42:43] op_sel:[0,1]
	v_pk_fma_f32 v[140:141], v[16:17], v[108:109], v[140:141] op_sel:[0,1,0]
	v_pk_fma_f32 v[142:143], v[16:17], v[124:125], v[142:143] op_sel:[0,1,0]
	v_pk_fma_f32 v[146:147], v[68:69], v[42:43], v[76:77] op_sel_hi:[1,0,1] neg_lo:[0,0,1]
	v_pk_fma_f32 v[140:141], v[58:59], v[110:111], v[140:141] op_sel_hi:[1,0,1]
	v_pk_fma_f32 v[142:143], v[58:59], v[126:127], v[142:143] op_sel_hi:[1,0,1]
	v_pk_add_f32 v[70:71], v[146:147], v[138:139]
	v_pk_fma_f32 v[140:141], v[18:19], v[110:111], v[140:141] op_sel:[0,1,0]
	v_pk_fma_f32 v[142:143], v[18:19], v[126:127], v[142:143] op_sel:[0,1,0]
	v_cvt_pk_bf16_f32 v150, v70, v71
	ds_write_b16 v103, v150 offset:4080
	ds_write_b16_d16_hi v103, v150 offset:4208
	ds_read_b128 v[108:111], v79 offset:1168
	ds_read_b128 v[124:127], v79 offset:1232
	s_waitcnt lgkmcnt(11)
	s_waitcnt lgkmcnt(10)
	v_pk_fma_f32 v[140:141], v[60:61], v[112:113], v[140:141] op_sel_hi:[1,0,1]
	v_pk_fma_f32 v[142:143], v[60:61], v[128:129], v[142:143] op_sel_hi:[1,0,1]
	v_pk_fma_f32 v[140:141], v[12:13], v[112:113], v[140:141] op_sel:[0,1,0]
	v_pk_fma_f32 v[142:143], v[12:13], v[128:129], v[142:143] op_sel:[0,1,0]
	v_pk_fma_f32 v[140:141], v[62:63], v[114:115], v[140:141] op_sel_hi:[1,0,1]
	v_pk_fma_f32 v[142:143], v[62:63], v[130:131], v[142:143] op_sel_hi:[1,0,1]
	v_pk_fma_f32 v[140:141], v[14:15], v[114:115], v[140:141] op_sel:[0,1,0]
	v_pk_fma_f32 v[142:143], v[14:15], v[130:131], v[142:143] op_sel:[0,1,0]
	ds_read_b128 v[112:115], v79 offset:1184
	ds_read_b128 v[128:131], v79 offset:1248
	s_waitcnt lgkmcnt(11)
	s_waitcnt lgkmcnt(10)
	v_pk_fma_f32 v[140:141], v[64:65], v[116:117], v[140:141] op_sel_hi:[1,0,1]
	v_pk_fma_f32 v[142:143], v[64:65], v[132:133], v[142:143] op_sel_hi:[1,0,1]
	v_pk_fma_f32 v[140:141], v[8:9], v[116:117], v[140:141] op_sel:[0,1,0]
	v_pk_fma_f32 v[142:143], v[8:9], v[132:133], v[142:143] op_sel:[0,1,0]
	v_pk_fma_f32 v[140:141], v[66:67], v[118:119], v[140:141] op_sel_hi:[1,0,1]
	v_pk_fma_f32 v[142:143], v[66:67], v[134:135], v[142:143] op_sel_hi:[1,0,1]
	v_pk_fma_f32 v[140:141], v[10:11], v[118:119], v[140:141] op_sel:[0,1,0]
	v_pk_fma_f32 v[142:143], v[10:11], v[134:135], v[142:143] op_sel:[0,1,0]
	ds_read_b128 v[116:119], v79 offset:1200
	ds_read_b128 v[132:135], v79 offset:1264
	s_waitcnt lgkmcnt(9)
	s_waitcnt lgkmcnt(8)
	v_pk_mul_f32 v[136:137], v[20:21], v[104:105] op_sel:[0,1]
	v_pk_mul_f32 v[138:139], v[20:21], v[120:121] op_sel:[0,1]
	v_pk_mul_f32 v[76:77], v[74:75], v[70:71] op_sel:[0,1]
	v_pk_fma_f32 v[136:137], v[52:53], v[104:105], v[136:137] op_sel_hi:[1,0,1]
	v_pk_fma_f32 v[138:139], v[52:53], v[120:121], v[138:139] op_sel_hi:[1,0,1]
	v_pk_fma_f32 v[146:147], v[68:69], v[70:71], v[76:77] op_sel_hi:[1,0,1] neg_lo:[0,0,1]
	v_pk_fma_f32 v[136:137], v[54:55], v[106:107], v[136:137] op_sel_hi:[1,0,1]
	v_pk_fma_f32 v[138:139], v[54:55], v[122:123], v[138:139] op_sel_hi:[1,0,1]
	v_pk_add_f32 v[42:43], v[146:147], v[140:141]
	v_pk_fma_f32 v[136:137], v[22:23], v[106:107], v[136:137] op_sel:[0,1,0]
	v_pk_fma_f32 v[138:139], v[22:23], v[122:123], v[138:139] op_sel:[0,1,0]
	v_cvt_pk_bf16_f32 v150, v42, v43
	ds_write_b16 v103, v150 offset:4352
	ds_write_b16_d16_hi v103, v150 offset:4480
	ds_read_b128 v[104:107], v79 offset:1280
	ds_read_b128 v[120:123], v79 offset:1344
	s_waitcnt lgkmcnt(9)
	s_waitcnt lgkmcnt(8)
	v_pk_fma_f32 v[136:137], v[56:57], v[108:109], v[136:137] op_sel_hi:[1,0,1]
	v_pk_fma_f32 v[138:139], v[56:57], v[124:125], v[138:139] op_sel_hi:[1,0,1]
	v_pk_mul_f32 v[76:77], v[74:75], v[42:43] op_sel:[0,1]
	v_pk_fma_f32 v[136:137], v[16:17], v[108:109], v[136:137] op_sel:[0,1,0]
	v_pk_fma_f32 v[138:139], v[16:17], v[124:125], v[138:139] op_sel:[0,1,0]
	v_pk_fma_f32 v[146:147], v[68:69], v[42:43], v[76:77] op_sel_hi:[1,0,1] neg_lo:[0,0,1]
	v_pk_fma_f32 v[136:137], v[58:59], v[110:111], v[136:137] op_sel_hi:[1,0,1]
	v_pk_fma_f32 v[138:139], v[58:59], v[126:127], v[138:139] op_sel_hi:[1,0,1]
	v_pk_add_f32 v[70:71], v[146:147], v[142:143]
	v_pk_fma_f32 v[136:137], v[18:19], v[110:111], v[136:137] op_sel:[0,1,0]
	v_pk_fma_f32 v[138:139], v[18:19], v[126:127], v[138:139] op_sel:[0,1,0]
	v_cvt_pk_bf16_f32 v150, v70, v71
	ds_write_b16 v103, v150 offset:4624
	ds_write_b16_d16_hi v103, v150 offset:4752
	ds_read_b128 v[108:111], v79 offset:1296
	ds_read_b128 v[124:127], v79 offset:1360
	s_waitcnt lgkmcnt(11)
	s_waitcnt lgkmcnt(10)
; __device__ __forceinline__ bf f2bf(float f) { return (bf)(pk2(f, 0.f) & 0xFFFFu); }
; __device__ __forceinline__ void s5_pass2(const Params& p, int layer, int task, char* sm) {
;     ...
;       for (int l = 0; l < 32; l++) {
;         S5_STEP(sU + l * 16)
;         sS[l * 136 + lane] = f2bf(sr); sS[l * 136 + 64 + lane] = f2bf(si);
	v_pk_fma_f32 v[136:137], v[60:61], v[112:113], v[136:137] op_sel_hi:[1,0,1]
	v_pk_fma_f32 v[138:139], v[60:61], v[128:129], v[138:139] op_sel_hi:[1,0,1]
	v_pk_fma_f32 v[136:137], v[12:13], v[112:113], v[136:137] op_sel:[0,1,0]
	v_pk_fma_f32 v[138:139], v[12:13], v[128:129], v[138:139] op_sel:[0,1,0]
	v_pk_fma_f32 v[136:137], v[62:63], v[114:115], v[136:137] op_sel_hi:[1,0,1]
	v_pk_fma_f32 v[138:139], v[62:63], v[130:131], v[138:139] op_sel_hi:[1,0,1]
	v_pk_fma_f32 v[136:137], v[14:15], v[114:115], v[136:137] op_sel:[0,1,0]
	v_pk_fma_f32 v[138:139], v[14:15], v[130:131], v[138:139] op_sel:[0,1,0]
	ds_read_b128 v[112:115], v79 offset:1312
	ds_read_b128 v[128:131], v79 offset:1376
	s_waitcnt lgkmcnt(11)
	s_waitcnt lgkmcnt(10)
	v_pk_fma_f32 v[136:137], v[64:65], v[116:117], v[136:137] op_sel_hi:[1,0,1]
	v_pk_fma_f32 v[138:139], v[64:65], v[132:133], v[138:139] op_sel_hi:[1,0,1]
	v_pk_fma_f32 v[136:137], v[8:9], v[116:117], v[136:137] op_sel:[0,1,0]
	v_pk_fma_f32 v[138:139], v[8:9], v[132:133], v[138:139] op_sel:[0,1,0]
	v_pk_fma_f32 v[136:137], v[66:67], v[118:119], v[136:137] op_sel_hi:[1,0,1]
	v_pk_fma_f32 v[138:139], v[66:67], v[134:135], v[138:139] op_sel_hi:[1,0,1]
	v_pk_fma_f32 v[136:137], v[10:11], v[118:119], v[136:137] op_sel:[0,1,0]
	v_pk_fma_f32 v[138:139], v[10:11], v[134:135], v[138:139] op_sel:[0,1,0]
	ds_read_b128 v[116:119], v79 offset:1328
	ds_read_b128 v[132:135], v79 offset:1392
	s_waitcnt lgkmcnt(9)
	s_waitcnt lgkmcnt(8)
	v_pk_mul_f32 v[140:141], v[20:21], v[104:105] op_sel:[0,1]
	v_pk_mul_f32 v[142:143], v[20:21], v[120:121] op_sel:[0,1]
	v_pk_mul_f32 v[76:77], v[74:75], v[70:71] op_sel:[0,1]
	v_pk_fma_f32 v[140:141], v[52:53], v[104:105], v[140:141] op_sel_hi:[1,0,1]
	v_pk_fma_f32 v[142:143], v[52:53], v[120:121], v[142:143] op_sel_hi:[1,0,1]
	v_pk_fma_f32 v[146:147], v[68:69], v[70:71], v[76:77] op_sel_hi:[1,0,1] neg_lo:[0,0,1]
	v_pk_fma_f32 v[140:141], v[54:55], v[106:107], v[140:141] op_sel_hi:[1,0,1]
	v_pk_fma_f32 v[142:143], v[54:55], v[122:123], v[142:143] op_sel_hi:[1,0,1]
	v_pk_add_f32 v[42:43], v[146:147], v[136:137]
	v_pk_fma_f32 v[140:141], v[22:23], v[106:107], v[140:141] op_sel:[0,1,0]
	v_pk_fma_f32 v[142:143], v[22:23], v[122:123], v[142:143] op_sel:[0,1,0]
	v_cvt_pk_bf16_f32 v150, v42, v43
	ds_write_b16 v103, v150 offset:4896
	ds_write_b16_d16_hi v103, v150 offset:5024
	ds_read_b128 v[104:107], v79 offset:1408
	ds_read_b128 v[120:123], v79 offset:1472
	s_waitcnt lgkmcnt(9)
	s_waitcnt lgkmcnt(8)
	v_pk_fma_f32 v[140:141], v[56:57], v[108:109], v[140:141] op_sel_hi:[1,0,1]
	v_pk_fma_f32 v[142:143], v[56:57], v[124:125], v[142:143] op_sel_hi:[1,0,1]
	v_pk_mul_f32 v[76:77], v[74:75], v[42:43] op_sel:[0,1]
	v_pk_fma_f32 v[140:141], v[16:17], v[108:109], v[140:141] op_sel:[0,1,0]
	v_pk_fma_f32 v[142:143], v[16:17], v[124:125], v[142:143] op_sel:[0,1,0]
	v_pk_fma_f32 v[146:147], v[68:69], v[42:43], v[76:77] op_sel_hi:[1,0,1] neg_lo:[0,0,1]
	v_pk_fma_f32 v[140:141], v[58:59], v[110:111], v[140:141] op_sel_hi:[1,0,1]
	v_pk_fma_f32 v[142:143], v[58:59], v[126:127], v[142:143] op_sel_hi:[1,0,1]
	v_pk_add_f32 v[70:71], v[146:147], v[138:139]
	v_pk_fma_f32 v[140:141], v[18:19], v[110:111], v[140:141] op_sel:[0,1,0]
	v_pk_fma_f32 v[142:143], v[18:19], v[126:127], v[142:143] op_sel:[0,1,0]
	v_cvt_pk_bf16_f32 v150, v70, v71
	ds_write_b16 v103, v150 offset:5168
	ds_write_b16_d16_hi v103, v150 offset:5296
	ds_read_b128 v[108:111], v79 offset:1424
	ds_read_b128 v[124:127], v79 offset:1488
	s_waitcnt lgkmcnt(11)
	s_waitcnt lgkmcnt(10)
	v_pk_fma_f32 v[140:141], v[60:61], v[112:113], v[140:141] op_sel_hi:[1,0,1]
	v_pk_fma_f32 v[142:143], v[60:61], v[128:129], v[142:143] op_sel_hi:[1,0,1]
	v_pk_fma_f32 v[140:141], v[12:13], v[112:113], v[140:141] op_sel:[0,1,0]
	v_pk_fma_f32 v[142:143], v[12:13], v[128:129], v[142:143] op_sel:[0,1,0]
	v_pk_fma_f32 v[140:141], v[62:63], v[114:115], v[140:141] op_sel_hi:[1,0,1]
	v_pk_fma_f32 v[142:143], v[62:63], v[130:131], v[142:143] op_sel_hi:[1,0,1]
	v_pk_fma_f32 v[140:141], v[14:15], v[114:115], v[140:141] op_sel:[0,1,0]
	v_pk_fma_f32 v[142:143], v[14:15], v[130:131], v[142:143] op_sel:[0,1,0]
	ds_read_b128 v[112:115], v79 offset:1440
	ds_read_b128 v[128:131], v79 offset:1504
	s_waitcnt lgkmcnt(11)
	s_waitcnt lgkmcnt(10)
	v_pk_fma_f32 v[140:141], v[64:65], v[116:117], v[140:141] op_sel_hi:[1,0,1]
	v_pk_fma_f32 v[142:143], v[64:65], v[132:133], v[142:143] op_sel_hi:[1,0,1]
	v_pk_fma_f32 v[140:141], v[8:9], v[116:117], v[140:141] op_sel:[0,1,0]
	v_pk_fma_f32 v[142:143], v[8:9], v[132:133], v[142:143] op_sel:[0,1,0]
	v_pk_fma_f32 v[140:141], v[66:67], v[118:119], v[140:141] op_sel_hi:[1,0,1]
	v_pk_fma_f32 v[142:143], v[66:67], v[134:135], v[142:143] op_sel_hi:[1,0,1]
	v_pk_fma_f32 v[140:141], v[10:11], v[118:119], v[140:141] op_sel:[0,1,0]
	v_pk_fma_f32 v[142:143], v[10:11], v[134:135], v[142:143] op_sel:[0,1,0]
	ds_read_b128 v[116:119], v79 offset:1456
	ds_read_b128 v[132:135], v79 offset:1520
	s_waitcnt lgkmcnt(9)
	s_waitcnt lgkmcnt(8)
	v_pk_mul_f32 v[136:137], v[20:21], v[104:105] op_sel:[0,1]
	v_pk_mul_f32 v[138:139], v[20:21], v[120:121] op_sel:[0,1]
	v_pk_mul_f32 v[76:77], v[74:75], v[70:71] op_sel:[0,1]
	v_pk_fma_f32 v[136:137], v[52:53], v[104:105], v[136:137] op_sel_hi:[1,0,1]
	v_pk_fma_f32 v[138:139], v[52:53], v[120:121], v[138:139] op_sel_hi:[1,0,1]
	v_pk_fma_f32 v[146:147], v[68:69], v[70:71], v[76:77] op_sel_hi:[1,0,1] neg_lo:[0,0,1]
	v_pk_fma_f32 v[136:137], v[54:55], v[106:107], v[136:137] op_sel_hi:[1,0,1]
	v_pk_fma_f32 v[138:139], v[54:55], v[122:123], v[138:139] op_sel_hi:[1,0,1]
	v_pk_add_f32 v[42:43], v[146:147], v[140:141]
	v_pk_fma_f32 v[136:137], v[22:23], v[106:107], v[136:137] op_sel:[0,1,0]
	v_pk_fma_f32 v[138:139], v[22:23], v[122:123], v[138:139] op_sel:[0,1,0]
	v_cvt_pk_bf16_f32 v150, v42, v43
	ds_write_b16 v103, v150 offset:5440
	ds_write_b16_d16_hi v103, v150 offset:5568
	ds_read_b128 v[104:107], v79 offset:1536
	ds_read_b128 v[120:123], v79 offset:1600
	s_waitcnt lgkmcnt(9)
; __device__ __forceinline__ bf f2bf(float f) { return (bf)(pk2(f, 0.f) & 0xFFFFu); }
; __device__ __forceinline__ void s5_pass2(const Params& p, int layer, int task, char* sm) {
;     ...
;       for (int l = 0; l < 32; l++) {
;         S5_STEP(sU + l * 16)
;         sS[l * 136 + lane] = f2bf(sr); sS[l * 136 + 64 + lane] = f2bf(si);
	s_waitcnt lgkmcnt(8)
	v_pk_fma_f32 v[136:137], v[56:57], v[108:109], v[136:137] op_sel_hi:[1,0,1]
	v_pk_fma_f32 v[138:139], v[56:57], v[124:125], v[138:139] op_sel_hi:[1,0,1]
	v_pk_mul_f32 v[76:77], v[74:75], v[42:43] op_sel:[0,1]
	v_pk_fma_f32 v[136:137], v[16:17], v[108:109], v[136:137] op_sel:[0,1,0]
	v_pk_fma_f32 v[138:139], v[16:17], v[124:125], v[138:139] op_sel:[0,1,0]
	v_pk_fma_f32 v[146:147], v[68:69], v[42:43], v[76:77] op_sel_hi:[1,0,1] neg_lo:[0,0,1]
	v_pk_fma_f32 v[136:137], v[58:59], v[110:111], v[136:137] op_sel_hi:[1,0,1]
	v_pk_fma_f32 v[138:139], v[58:59], v[126:127], v[138:139] op_sel_hi:[1,0,1]
	v_pk_add_f32 v[70:71], v[146:147], v[142:143]
	v_pk_fma_f32 v[136:137], v[18:19], v[110:111], v[136:137] op_sel:[0,1,0]
	v_pk_fma_f32 v[138:139], v[18:19], v[126:127], v[138:139] op_sel:[0,1,0]
	v_cvt_pk_bf16_f32 v150, v70, v71
	ds_write_b16 v103, v150 offset:5712
	ds_write_b16_d16_hi v103, v150 offset:5840
	ds_read_b128 v[108:111], v79 offset:1552
	ds_read_b128 v[124:127], v79 offset:1616
	s_waitcnt lgkmcnt(11)
	s_waitcnt lgkmcnt(10)
	v_pk_fma_f32 v[136:137], v[60:61], v[112:113], v[136:137] op_sel_hi:[1,0,1]
	v_pk_fma_f32 v[138:139], v[60:61], v[128:129], v[138:139] op_sel_hi:[1,0,1]
	v_pk_fma_f32 v[136:137], v[12:13], v[112:113], v[136:137] op_sel:[0,1,0]
	v_pk_fma_f32 v[138:139], v[12:13], v[128:129], v[138:139] op_sel:[0,1,0]
	v_pk_fma_f32 v[136:137], v[62:63], v[114:115], v[136:137] op_sel_hi:[1,0,1]
	v_pk_fma_f32 v[138:139], v[62:63], v[130:131], v[138:139] op_sel_hi:[1,0,1]
	v_pk_fma_f32 v[136:137], v[14:15], v[114:115], v[136:137] op_sel:[0,1,0]
	v_pk_fma_f32 v[138:139], v[14:15], v[130:131], v[138:139] op_sel:[0,1,0]
	ds_read_b128 v[112:115], v79 offset:1568
	ds_read_b128 v[128:131], v79 offset:1632
	s_waitcnt lgkmcnt(11)
	s_waitcnt lgkmcnt(10)
	v_pk_fma_f32 v[136:137], v[64:65], v[116:117], v[136:137] op_sel_hi:[1,0,1]
	v_pk_fma_f32 v[138:139], v[64:65], v[132:133], v[138:139] op_sel_hi:[1,0,1]
	v_pk_fma_f32 v[136:137], v[8:9], v[116:117], v[136:137] op_sel:[0,1,0]
	v_pk_fma_f32 v[138:139], v[8:9], v[132:133], v[138:139] op_sel:[0,1,0]
	v_pk_fma_f32 v[136:137], v[66:67], v[118:119], v[136:137] op_sel_hi:[1,0,1]
	v_pk_fma_f32 v[138:139], v[66:67], v[134:135], v[138:139] op_sel_hi:[1,0,1]
	v_pk_fma_f32 v[136:137], v[10:11], v[118:119], v[136:137] op_sel:[0,1,0]
	v_pk_fma_f32 v[138:139], v[10:11], v[134:135], v[138:139] op_sel:[0,1,0]
	ds_read_b128 v[116:119], v79 offset:1584
	ds_read_b128 v[132:135], v79 offset:1648
	s_waitcnt lgkmcnt(9)
	s_waitcnt lgkmcnt(8)
	v_pk_mul_f32 v[140:141], v[20:21], v[104:105] op_sel:[0,1]
	v_pk_mul_f32 v[142:143], v[20:21], v[120:121] op_sel:[0,1]
	v_pk_mul_f32 v[76:77], v[74:75], v[70:71] op_sel:[0,1]
	v_pk_fma_f32 v[140:141], v[52:53], v[104:105], v[140:141] op_sel_hi:[1,0,1]
	v_pk_fma_f32 v[142:143], v[52:53], v[120:121], v[142:143] op_sel_hi:[1,0,1]
	v_pk_fma_f32 v[146:147], v[68:69], v[70:71], v[76:77] op_sel_hi:[1,0,1] neg_lo:[0,0,1]
	v_pk_fma_f32 v[140:141], v[54:55], v[106:107], v[140:141] op_sel_hi:[1,0,1]
	v_pk_fma_f32 v[142:143], v[54:55], v[122:123], v[142:143] op_sel_hi:[1,0,1]
	v_pk_add_f32 v[42:43], v[146:147], v[136:137]
	v_pk_fma_f32 v[140:141], v[22:23], v[106:107], v[140:141] op_sel:[0,1,0]
	v_pk_fma_f32 v[142:143], v[22:23], v[122:123], v[142:143] op_sel:[0,1,0]
	v_cvt_pk_bf16_f32 v150, v42, v43
	ds_write_b16 v103, v150 offset:5984
	ds_write_b16_d16_hi v103, v150 offset:6112
	ds_read_b128 v[104:107], v79 offset:1664
	ds_read_b128 v[120:123], v79 offset:1728
	s_waitcnt lgkmcnt(9)
	s_waitcnt lgkmcnt(8)
	v_pk_fma_f32 v[140:141], v[56:57], v[108:109], v[140:141] op_sel_hi:[1,0,1]
	v_pk_fma_f32 v[142:143], v[56:57], v[124:125], v[142:143] op_sel_hi:[1,0,1]
	v_pk_mul_f32 v[76:77], v[74:75], v[42:43] op_sel:[0,1]
	v_pk_fma_f32 v[140:141], v[16:17], v[108:109], v[140:141] op_sel:[0,1,0]
	v_pk_fma_f32 v[142:143], v[16:17], v[124:125], v[142:143] op_sel:[0,1,0]
	v_pk_fma_f32 v[146:147], v[68:69], v[42:43], v[76:77] op_sel_hi:[1,0,1] neg_lo:[0,0,1]
	v_pk_fma_f32 v[140:141], v[58:59], v[110:111], v[140:141] op_sel_hi:[1,0,1]
	v_pk_fma_f32 v[142:143], v[58:59], v[126:127], v[142:143] op_sel_hi:[1,0,1]
	v_pk_add_f32 v[70:71], v[146:147], v[138:139]
	v_pk_fma_f32 v[140:141], v[18:19], v[110:111], v[140:141] op_sel:[0,1,0]
	v_pk_fma_f32 v[142:143], v[18:19], v[126:127], v[142:143] op_sel:[0,1,0]
	v_cvt_pk_bf16_f32 v150, v70, v71
	ds_write_b16 v103, v150 offset:6256
	ds_write_b16_d16_hi v103, v150 offset:6384
	ds_read_b128 v[108:111], v79 offset:1680
	ds_read_b128 v[124:127], v79 offset:1744
	s_waitcnt lgkmcnt(11)
	s_waitcnt lgkmcnt(10)
	v_pk_fma_f32 v[140:141], v[60:61], v[112:113], v[140:141] op_sel_hi:[1,0,1]
	v_pk_fma_f32 v[142:143], v[60:61], v[128:129], v[142:143] op_sel_hi:[1,0,1]
	v_pk_fma_f32 v[140:141], v[12:13], v[112:113], v[140:141] op_sel:[0,1,0]
	v_pk_fma_f32 v[142:143], v[12:13], v[128:129], v[142:143] op_sel:[0,1,0]
	v_pk_fma_f32 v[140:141], v[62:63], v[114:115], v[140:141] op_sel_hi:[1,0,1]
	v_pk_fma_f32 v[142:143], v[62:63], v[130:131], v[142:143] op_sel_hi:[1,0,1]
	v_pk_fma_f32 v[140:141], v[14:15], v[114:115], v[140:141] op_sel:[0,1,0]
	v_pk_fma_f32 v[142:143], v[14:15], v[130:131], v[142:143] op_sel:[0,1,0]
	ds_read_b128 v[112:115], v79 offset:1696
	ds_read_b128 v[128:131], v79 offset:1760
	s_waitcnt lgkmcnt(11)
	s_waitcnt lgkmcnt(10)
; __device__ __forceinline__ bf f2bf(float f) { return (bf)(pk2(f, 0.f) & 0xFFFFu); }
; __device__ __forceinline__ void s5_pass2(const Params& p, int layer, int task, char* sm) {
;     ...
;       for (int l = 0; l < 32; l++) {
;         S5_STEP(sU + l * 16)
;         sS[l * 136 + lane] = f2bf(sr); sS[l * 136 + 64 + lane] = f2bf(si);
	v_pk_fma_f32 v[140:141], v[64:65], v[116:117], v[140:141] op_sel_hi:[1,0,1]
	v_pk_fma_f32 v[142:143], v[64:65], v[132:133], v[142:143] op_sel_hi:[1,0,1]
	v_pk_fma_f32 v[140:141], v[8:9], v[116:117], v[140:141] op_sel:[0,1,0]
	v_pk_fma_f32 v[142:143], v[8:9], v[132:133], v[142:143] op_sel:[0,1,0]
	v_pk_fma_f32 v[140:141], v[66:67], v[118:119], v[140:141] op_sel_hi:[1,0,1]
	v_pk_fma_f32 v[142:143], v[66:67], v[134:135], v[142:143] op_sel_hi:[1,0,1]
	v_pk_fma_f32 v[140:141], v[10:11], v[118:119], v[140:141] op_sel:[0,1,0]
	v_pk_fma_f32 v[142:143], v[10:11], v[134:135], v[142:143] op_sel:[0,1,0]
	ds_read_b128 v[116:119], v79 offset:1712
	ds_read_b128 v[132:135], v79 offset:1776
	s_waitcnt lgkmcnt(9)
	s_waitcnt lgkmcnt(8)
	v_pk_mul_f32 v[136:137], v[20:21], v[104:105] op_sel:[0,1]
	v_pk_mul_f32 v[138:139], v[20:21], v[120:121] op_sel:[0,1]
	v_pk_mul_f32 v[76:77], v[74:75], v[70:71] op_sel:[0,1]
	v_pk_fma_f32 v[136:137], v[52:53], v[104:105], v[136:137] op_sel_hi:[1,0,1]
	v_pk_fma_f32 v[138:139], v[52:53], v[120:121], v[138:139] op_sel_hi:[1,0,1]
	v_pk_fma_f32 v[146:147], v[68:69], v[70:71], v[76:77] op_sel_hi:[1,0,1] neg_lo:[0,0,1]
	v_pk_fma_f32 v[136:137], v[54:55], v[106:107], v[136:137] op_sel_hi:[1,0,1]
	v_pk_fma_f32 v[138:139], v[54:55], v[122:123], v[138:139] op_sel_hi:[1,0,1]
	v_pk_add_f32 v[42:43], v[146:147], v[140:141]
	v_pk_fma_f32 v[136:137], v[22:23], v[106:107], v[136:137] op_sel:[0,1,0]
	v_pk_fma_f32 v[138:139], v[22:23], v[122:123], v[138:139] op_sel:[0,1,0]
	v_cvt_pk_bf16_f32 v150, v42, v43
	ds_write_b16 v103, v150 offset:6528
	ds_write_b16_d16_hi v103, v150 offset:6656
	ds_read_b128 v[104:107], v79 offset:1792
	ds_read_b128 v[120:123], v79 offset:1856
	s_waitcnt lgkmcnt(9)
	s_waitcnt lgkmcnt(8)
	v_pk_fma_f32 v[136:137], v[56:57], v[108:109], v[136:137] op_sel_hi:[1,0,1]
	v_pk_fma_f32 v[138:139], v[56:57], v[124:125], v[138:139] op_sel_hi:[1,0,1]
	v_pk_mul_f32 v[76:77], v[74:75], v[42:43] op_sel:[0,1]
	v_pk_fma_f32 v[136:137], v[16:17], v[108:109], v[136:137] op_sel:[0,1,0]
	v_pk_fma_f32 v[138:139], v[16:17], v[124:125], v[138:139] op_sel:[0,1,0]
	v_pk_fma_f32 v[146:147], v[68:69], v[42:43], v[76:77] op_sel_hi:[1,0,1] neg_lo:[0,0,1]
	v_pk_fma_f32 v[136:137], v[58:59], v[110:111], v[136:137] op_sel_hi:[1,0,1]
	v_pk_fma_f32 v[138:139], v[58:59], v[126:127], v[138:139] op_sel_hi:[1,0,1]
	v_pk_add_f32 v[70:71], v[146:147], v[142:143]
	v_pk_fma_f32 v[136:137], v[18:19], v[110:111], v[136:137] op_sel:[0,1,0]
	v_pk_fma_f32 v[138:139], v[18:19], v[126:127], v[138:139] op_sel:[0,1,0]
	v_cvt_pk_bf16_f32 v150, v70, v71
	ds_write_b16 v103, v150 offset:6800
	ds_write_b16_d16_hi v103, v150 offset:6928
	ds_read_b128 v[108:111], v79 offset:1808
	ds_read_b128 v[124:127], v79 offset:1872
	s_waitcnt lgkmcnt(11)
	s_waitcnt lgkmcnt(10)
	v_pk_fma_f32 v[136:137], v[60:61], v[112:113], v[136:137] op_sel_hi:[1,0,1]
	v_pk_fma_f32 v[138:139], v[60:61], v[128:129], v[138:139] op_sel_hi:[1,0,1]
	v_pk_fma_f32 v[136:137], v[12:13], v[112:113], v[136:137] op_sel:[0,1,0]
	v_pk_fma_f32 v[138:139], v[12:13], v[128:129], v[138:139] op_sel:[0,1,0]
	v_pk_fma_f32 v[136:137], v[62:63], v[114:115], v[136:137] op_sel_hi:[1,0,1]
	v_pk_fma_f32 v[138:139], v[62:63], v[130:131], v[138:139] op_sel_hi:[1,0,1]
	v_pk_fma_f32 v[136:137], v[14:15], v[114:115], v[136:137] op_sel:[0,1,0]
	v_pk_fma_f32 v[138:139], v[14:15], v[130:131], v[138:139] op_sel:[0,1,0]
	ds_read_b128 v[112:115], v79 offset:1824
	ds_read_b128 v[128:131], v79 offset:1888
	s_waitcnt lgkmcnt(11)
	s_waitcnt lgkmcnt(10)
	v_pk_fma_f32 v[136:137], v[64:65], v[116:117], v[136:137] op_sel_hi:[1,0,1]
	v_pk_fma_f32 v[138:139], v[64:65], v[132:133], v[138:139] op_sel_hi:[1,0,1]
	v_pk_fma_f32 v[136:137], v[8:9], v[116:117], v[136:137] op_sel:[0,1,0]
	v_pk_fma_f32 v[138:139], v[8:9], v[132:133], v[138:139] op_sel:[0,1,0]
	v_pk_fma_f32 v[136:137], v[66:67], v[118:119], v[136:137] op_sel_hi:[1,0,1]
	v_pk_fma_f32 v[138:139], v[66:67], v[134:135], v[138:139] op_sel_hi:[1,0,1]
	v_pk_fma_f32 v[136:137], v[10:11], v[118:119], v[136:137] op_sel:[0,1,0]
	v_pk_fma_f32 v[138:139], v[10:11], v[134:135], v[138:139] op_sel:[0,1,0]
	ds_read_b128 v[116:119], v79 offset:1840
	ds_read_b128 v[132:135], v79 offset:1904
	s_waitcnt lgkmcnt(9)
	s_waitcnt lgkmcnt(8)
	v_pk_mul_f32 v[140:141], v[20:21], v[104:105] op_sel:[0,1]
	v_pk_mul_f32 v[142:143], v[20:21], v[120:121] op_sel:[0,1]
	v_pk_mul_f32 v[76:77], v[74:75], v[70:71] op_sel:[0,1]
	v_pk_fma_f32 v[140:141], v[52:53], v[104:105], v[140:141] op_sel_hi:[1,0,1]
	v_pk_fma_f32 v[142:143], v[52:53], v[120:121], v[142:143] op_sel_hi:[1,0,1]
	v_pk_fma_f32 v[146:147], v[68:69], v[70:71], v[76:77] op_sel_hi:[1,0,1] neg_lo:[0,0,1]
	v_pk_fma_f32 v[140:141], v[54:55], v[106:107], v[140:141] op_sel_hi:[1,0,1]
	v_pk_fma_f32 v[142:143], v[54:55], v[122:123], v[142:143] op_sel_hi:[1,0,1]
	v_pk_add_f32 v[42:43], v[146:147], v[136:137]
	v_pk_fma_f32 v[140:141], v[22:23], v[106:107], v[140:141] op_sel:[0,1,0]
	v_pk_fma_f32 v[142:143], v[22:23], v[122:123], v[142:143] op_sel:[0,1,0]
	v_cvt_pk_bf16_f32 v150, v42, v43
	ds_write_b16 v103, v150 offset:7072
	ds_write_b16_d16_hi v103, v150 offset:7200
	ds_read_b128 v[104:107], v79 offset:1920
	ds_read_b128 v[120:123], v79 offset:1984
	s_waitcnt lgkmcnt(9)
	s_waitcnt lgkmcnt(8)
; __device__ __forceinline__ bf f2bf(float f) { return (bf)(pk2(f, 0.f) & 0xFFFFu); }
; __device__ __forceinline__ void s5_pass2(const Params& p, int layer, int task, char* sm) {
;     ...
;       for (int l = 0; l < 32; l++) {
;         S5_STEP(sU + l * 16)
;         sS[l * 136 + lane] = f2bf(sr); sS[l * 136 + 64 + lane] = f2bf(si);
	v_pk_fma_f32 v[140:141], v[56:57], v[108:109], v[140:141] op_sel_hi:[1,0,1]
	v_pk_fma_f32 v[142:143], v[56:57], v[124:125], v[142:143] op_sel_hi:[1,0,1]
	v_pk_mul_f32 v[76:77], v[74:75], v[42:43] op_sel:[0,1]
	v_pk_fma_f32 v[140:141], v[16:17], v[108:109], v[140:141] op_sel:[0,1,0]
	v_pk_fma_f32 v[142:143], v[16:17], v[124:125], v[142:143] op_sel:[0,1,0]
	v_pk_fma_f32 v[146:147], v[68:69], v[42:43], v[76:77] op_sel_hi:[1,0,1] neg_lo:[0,0,1]
	v_pk_fma_f32 v[140:141], v[58:59], v[110:111], v[140:141] op_sel_hi:[1,0,1]
	v_pk_fma_f32 v[142:143], v[58:59], v[126:127], v[142:143] op_sel_hi:[1,0,1]
	v_pk_add_f32 v[70:71], v[146:147], v[138:139]
	v_pk_fma_f32 v[140:141], v[18:19], v[110:111], v[140:141] op_sel:[0,1,0]
	v_pk_fma_f32 v[142:143], v[18:19], v[126:127], v[142:143] op_sel:[0,1,0]
	v_cvt_pk_bf16_f32 v150, v70, v71
	ds_write_b16 v103, v150 offset:7344
	ds_write_b16_d16_hi v103, v150 offset:7472
	ds_read_b128 v[108:111], v79 offset:1936
	ds_read_b128 v[124:127], v79 offset:2000
	s_waitcnt lgkmcnt(11)
	s_waitcnt lgkmcnt(10)
	v_pk_fma_f32 v[140:141], v[60:61], v[112:113], v[140:141] op_sel_hi:[1,0,1]
	v_pk_fma_f32 v[142:143], v[60:61], v[128:129], v[142:143] op_sel_hi:[1,0,1]
	v_pk_fma_f32 v[140:141], v[12:13], v[112:113], v[140:141] op_sel:[0,1,0]
	v_pk_fma_f32 v[142:143], v[12:13], v[128:129], v[142:143] op_sel:[0,1,0]
	v_pk_fma_f32 v[140:141], v[62:63], v[114:115], v[140:141] op_sel_hi:[1,0,1]
	v_pk_fma_f32 v[142:143], v[62:63], v[130:131], v[142:143] op_sel_hi:[1,0,1]
	v_pk_fma_f32 v[140:141], v[14:15], v[114:115], v[140:141] op_sel:[0,1,0]
	v_pk_fma_f32 v[142:143], v[14:15], v[130:131], v[142:143] op_sel:[0,1,0]
	ds_read_b128 v[112:115], v79 offset:1952
	ds_read_b128 v[128:131], v79 offset:2016
	s_waitcnt lgkmcnt(11)
	s_waitcnt lgkmcnt(10)
	v_pk_fma_f32 v[140:141], v[64:65], v[116:117], v[140:141] op_sel_hi:[1,0,1]
	v_pk_fma_f32 v[142:143], v[64:65], v[132:133], v[142:143] op_sel_hi:[1,0,1]
	v_pk_fma_f32 v[140:141], v[8:9], v[116:117], v[140:141] op_sel:[0,1,0]
	v_pk_fma_f32 v[142:143], v[8:9], v[132:133], v[142:143] op_sel:[0,1,0]
	v_pk_fma_f32 v[140:141], v[66:67], v[118:119], v[140:141] op_sel_hi:[1,0,1]
	v_pk_fma_f32 v[142:143], v[66:67], v[134:135], v[142:143] op_sel_hi:[1,0,1]
	v_pk_fma_f32 v[140:141], v[10:11], v[118:119], v[140:141] op_sel:[0,1,0]
	v_pk_fma_f32 v[142:143], v[10:11], v[134:135], v[142:143] op_sel:[0,1,0]
	ds_read_b128 v[116:119], v79 offset:1968
	ds_read_b128 v[132:135], v79 offset:2032
	s_waitcnt lgkmcnt(9)
	s_waitcnt lgkmcnt(8)
	v_pk_mul_f32 v[136:137], v[20:21], v[104:105] op_sel:[0,1]
	v_pk_mul_f32 v[138:139], v[20:21], v[120:121] op_sel:[0,1]
	v_pk_mul_f32 v[76:77], v[74:75], v[70:71] op_sel:[0,1]
	v_pk_fma_f32 v[136:137], v[52:53], v[104:105], v[136:137] op_sel_hi:[1,0,1]
	v_pk_fma_f32 v[138:139], v[52:53], v[120:121], v[138:139] op_sel_hi:[1,0,1]
	v_pk_fma_f32 v[146:147], v[68:69], v[70:71], v[76:77] op_sel_hi:[1,0,1] neg_lo:[0,0,1]
	v_pk_fma_f32 v[136:137], v[54:55], v[106:107], v[136:137] op_sel_hi:[1,0,1]
	v_pk_fma_f32 v[138:139], v[54:55], v[122:123], v[138:139] op_sel_hi:[1,0,1]
	v_pk_add_f32 v[42:43], v[146:147], v[140:141]
	v_pk_fma_f32 v[136:137], v[22:23], v[106:107], v[136:137] op_sel:[0,1,0]
	v_pk_fma_f32 v[138:139], v[22:23], v[122:123], v[138:139] op_sel:[0,1,0]
	v_cvt_pk_bf16_f32 v150, v42, v43
	ds_write_b16 v103, v150 offset:7616
	ds_write_b16_d16_hi v103, v150 offset:7744
	s_waitcnt lgkmcnt(7)
	s_waitcnt lgkmcnt(6)
	v_pk_fma_f32 v[136:137], v[56:57], v[108:109], v[136:137] op_sel_hi:[1,0,1]
	v_pk_fma_f32 v[138:139], v[56:57], v[124:125], v[138:139] op_sel_hi:[1,0,1]
	v_pk_mul_f32 v[76:77], v[74:75], v[42:43] op_sel:[0,1]
	v_pk_fma_f32 v[136:137], v[16:17], v[108:109], v[136:137] op_sel:[0,1,0]
	v_pk_fma_f32 v[138:139], v[16:17], v[124:125], v[138:139] op_sel:[0,1,0]
	v_pk_fma_f32 v[146:147], v[68:69], v[42:43], v[76:77] op_sel_hi:[1,0,1] neg_lo:[0,0,1]
	v_pk_fma_f32 v[136:137], v[58:59], v[110:111], v[136:137] op_sel_hi:[1,0,1]
	v_pk_fma_f32 v[138:139], v[58:59], v[126:127], v[138:139] op_sel_hi:[1,0,1]
	v_pk_add_f32 v[70:71], v[146:147], v[142:143]
	v_pk_fma_f32 v[136:137], v[18:19], v[110:111], v[136:137] op_sel:[0,1,0]
	v_pk_fma_f32 v[138:139], v[18:19], v[126:127], v[138:139] op_sel:[0,1,0]
	v_cvt_pk_bf16_f32 v150, v70, v71
	ds_write_b16 v103, v150 offset:7888
	ds_write_b16_d16_hi v103, v150 offset:8016
	s_waitcnt lgkmcnt(7)
	s_waitcnt lgkmcnt(6)
	v_pk_fma_f32 v[136:137], v[60:61], v[112:113], v[136:137] op_sel_hi:[1,0,1]
	v_pk_fma_f32 v[138:139], v[60:61], v[128:129], v[138:139] op_sel_hi:[1,0,1]
	v_pk_fma_f32 v[136:137], v[12:13], v[112:113], v[136:137] op_sel:[0,1,0]
	v_pk_fma_f32 v[138:139], v[12:13], v[128:129], v[138:139] op_sel:[0,1,0]
	v_pk_fma_f32 v[136:137], v[62:63], v[114:115], v[136:137] op_sel_hi:[1,0,1]
	v_pk_fma_f32 v[138:139], v[62:63], v[130:131], v[138:139] op_sel_hi:[1,0,1]
	v_pk_fma_f32 v[136:137], v[14:15], v[114:115], v[136:137] op_sel:[0,1,0]
	v_pk_fma_f32 v[138:139], v[14:15], v[130:131], v[138:139] op_sel:[0,1,0]
	s_waitcnt lgkmcnt(5)
	s_waitcnt lgkmcnt(4)
; __device__ __forceinline__ float ozero() { float z = 0.f; asm volatile("" : "+v"(z)); return z; }
; __device__ __forceinline__ bf f2bf(float f) { return (bf)(pk2(f, 0.f) & 0xFFFFu); }
; __device__ __forceinline__ f32x4 mfma16(bf16x8 a, bf16x8 b, f32x4 c) { return __builtin_amdgcn_mfma_f32_16x16x32_bf16(a, b, c, 0, 0, 0); }
; __device__ __forceinline__ void s5_pass2(const Params& p, int layer, int task, char* sm) {
;     ...
; #pragma unroll
;       for (int mb = 0; mb < 2; mb++) {
;         const float z_ = ozero(); f32x4 acc = {z_, z_, z_, z_};
; #pragma unroll
;         for (int ks = 0; ks < 4; ks++) {
;           bf16x8 af = *(const bf16x8*)(sS + (16 * mb + (lane & 15)) * 136 + ks * 32 + 8 * (lane >> 4));
;           acc = mfma16(af, cf[ks], acc);
;         }
; #pragma unroll
;         for (int r = 0; r < 4; r++) {
;           const int l = 16 * mb + 4 * (lane >> 4) + r;
;           float y = acc[r] + dsk * sU[l * 16 + (lane & 15)];
;           p.YG[(tok0 + sub * 32 + l) * 512 + g * 16 + (lane & 15)] = f2bf(geluf_(y));
	v_pk_fma_f32 v[136:137], v[64:65], v[116:117], v[136:137] op_sel_hi:[1,0,1]
	v_pk_fma_f32 v[138:139], v[64:65], v[132:133], v[138:139] op_sel_hi:[1,0,1]
	v_pk_fma_f32 v[136:137], v[8:9], v[116:117], v[136:137] op_sel:[0,1,0]
	v_pk_fma_f32 v[138:139], v[8:9], v[132:133], v[138:139] op_sel:[0,1,0]
	v_pk_fma_f32 v[136:137], v[66:67], v[118:119], v[136:137] op_sel_hi:[1,0,1]
	v_pk_fma_f32 v[138:139], v[66:67], v[134:135], v[138:139] op_sel_hi:[1,0,1]
	v_pk_fma_f32 v[136:137], v[10:11], v[118:119], v[136:137] op_sel:[0,1,0]
	v_pk_fma_f32 v[138:139], v[10:11], v[134:135], v[138:139] op_sel:[0,1,0]
	v_pk_mul_f32 v[76:77], v[74:75], v[70:71] op_sel:[0,1]
	s_nop 0
	v_pk_fma_f32 v[146:147], v[68:69], v[70:71], v[76:77] op_sel_hi:[1,0,1] neg_lo:[0,0,1]
	s_nop 0
	v_pk_add_f32 v[42:43], v[146:147], v[136:137]
	s_nop 0
	v_cvt_pk_bf16_f32 v150, v42, v43
	s_nop 0
	ds_write_b16 v103, v150 offset:8160
	ds_write_b16_d16_hi v103, v150 offset:8288
	v_pk_mul_f32 v[76:77], v[74:75], v[42:43] op_sel:[0,1]
	s_nop 0
	v_pk_fma_f32 v[146:147], v[68:69], v[42:43], v[76:77] op_sel_hi:[1,0,1] neg_lo:[0,0,1]
	s_nop 0
	v_pk_add_f32 v[70:71], v[146:147], v[138:139]
	s_nop 0
	v_cvt_pk_bf16_f32 v150, v70, v71
	s_nop 0
	ds_write_b16 v103, v150 offset:8432
	ds_write_b16_d16_hi v103, v150 offset:8560
	s_waitcnt lgkmcnt(0)
	v_mov_b32_e32 v40, v145
	ds_read_b128 v[104:107], v100 offset:2048
	ds_read_b32 v76, v83
	v_mov_b32_e32 v41, v40
	v_mov_b32_e32 v42, v40
	v_mov_b32_e32 v43, v40
	s_lshl_b32 s9, s11, 5
	v_mov_b32_e32 v77, s5
	s_cmp_eq_u32 s8, 4
	s_waitcnt vmcnt(4) lgkmcnt(1)
	v_mfma_f32_16x16x32_bf16 v[40:43], v[104:107], v[24:27], v[40:43]
	ds_read_b128 v[104:107], v100 offset:2112
	s_waitcnt vmcnt(3) lgkmcnt(0)
	v_mfma_f32_16x16x32_bf16 v[40:43], v[104:107], v[28:31], v[40:43]
	ds_read_b128 v[104:107], v100 offset:2176
	s_waitcnt vmcnt(2) lgkmcnt(0)
	v_mfma_f32_16x16x32_bf16 v[40:43], v[104:107], v[32:35], v[40:43]
	ds_read_b128 v[104:107], v100 offset:2240
	s_waitcnt vmcnt(1) lgkmcnt(0)
	v_mfma_f32_16x16x32_bf16 v[40:43], v[104:107], v[36:39], v[40:43]
	s_waitcnt vmcnt(0)
	s_nop 6
	v_fma_f32 v40, v102, v76, v40
	v_mul_f32_e32 v76, 0x3d372713, v40
	v_mul_f32_e32 v76, v40, v76
	v_fma_f32 v76, v40, v76, v40
	v_mul_f32_e32 v76, 0x3f4c422a, v76
	v_add_f32_e32 v76, v76, v76
	v_mul_f32_e32 v76, 0x3fb8aa3b, v76
	v_exp_f32_e32 v76, v76
	v_mul_f32_e32 v40, 0.5, v40
	v_add_f32_e32 v76, 1.0, v76
	v_rcp_f32_e32 v76, v76
	s_nop 0
	v_fma_f32 v76, v76, -2.0, 1.0
	v_add_f32_e32 v76, 1.0, v76
	v_mul_f32_e32 v40, v40, v76
	v_or_b32_e32 v76, s9, v82
	v_or_b32_e32 v76, s4, v76
	v_lshlrev_b64 v[104:105], 10, v[76:77]
	v_cvt_pk_bf16_f32 v40, v40, s0
	v_lshl_add_u64 v[104:105], v[72:73], 0, v[104:105]
	global_store_short v[104:105], v40, off
	ds_read_b32 v40, v85
	s_waitcnt lgkmcnt(0)
	v_fma_f32 v40, v102, v40, v41
	v_mul_f32_e32 v41, 0x3d372713, v40
	v_mul_f32_e32 v41, v40, v41
	v_fma_f32 v41, v40, v41, v40
	v_mul_f32_e32 v41, 0x3f4c422a, v41
	v_add_f32_e32 v41, v41, v41
	v_mul_f32_e32 v41, 0x3fb8aa3b, v41
	v_exp_f32_e32 v41, v41
	v_mul_f32_e32 v40, 0.5, v40
	v_add_f32_e32 v41, 1.0, v41
	v_rcp_f32_e32 v41, v41
	s_nop 0
	v_fma_f32 v41, v41, -2.0, 1.0
	v_add_f32_e32 v41, 1.0, v41
	v_mul_f32_e32 v40, v40, v41
	v_cvt_pk_bf16_f32 v103, v40, s0
	v_or_b32_e32 v40, s9, v84
	v_or_b32_e32 v76, s4, v40
	v_lshlrev_b64 v[40:41], 10, v[76:77]
	v_lshl_add_u64 v[40:41], v[72:73], 0, v[40:41]
	global_store_short v[40:41], v103, off
	ds_read_b32 v40, v87
	s_waitcnt lgkmcnt(0)
	v_fma_f32 v40, v102, v40, v42
	v_mul_f32_e32 v41, 0x3d372713, v40
	v_mul_f32_e32 v41, v40, v41
	v_fma_f32 v41, v40, v41, v40
	v_mul_f32_e32 v41, 0x3f4c422a, v41
	v_add_f32_e32 v41, v41, v41
	v_mul_f32_e32 v41, 0x3fb8aa3b, v41
	v_exp_f32_e32 v41, v41
	v_mul_f32_e32 v40, 0.5, v40
	v_add_f32_e32 v41, 1.0, v41
	v_rcp_f32_e32 v41, v41
	s_nop 0
	v_fma_f32 v41, v41, -2.0, 1.0
	v_add_f32_e32 v41, 1.0, v41
	v_mul_f32_e32 v40, v40, v41
	v_cvt_pk_bf16_f32 v42, v40, s0
	v_or_b32_e32 v40, s9, v86
	v_or_b32_e32 v76, s4, v40
	v_lshlrev_b64 v[40:41], 10, v[76:77]
	v_lshl_add_u64 v[40:41], v[72:73], 0, v[40:41]
	global_store_short v[40:41], v42, off
	ds_read_b32 v40, v89
	s_waitcnt lgkmcnt(0)
; __device__ __forceinline__ float ozero() { float z = 0.f; asm volatile("" : "+v"(z)); return z; }
; __device__ __forceinline__ bf f2bf(float f) { return (bf)(pk2(f, 0.f) & 0xFFFFu); }
; __device__ __forceinline__ f32x4 mfma16(bf16x8 a, bf16x8 b, f32x4 c) { return __builtin_amdgcn_mfma_f32_16x16x32_bf16(a, b, c, 0, 0, 0); }
; __device__ __forceinline__ void s5_pass2(const Params& p, int layer, int task, char* sm) {
;     ...
; #pragma unroll
;       for (int mb = 0; mb < 2; mb++) {
;         const float z_ = ozero(); f32x4 acc = {z_, z_, z_, z_};
; #pragma unroll
;         for (int ks = 0; ks < 4; ks++) {
;           bf16x8 af = *(const bf16x8*)(sS + (16 * mb + (lane & 15)) * 136 + ks * 32 + 8 * (lane >> 4));
;           acc = mfma16(af, cf[ks], acc);
;         }
; #pragma unroll
;         for (int r = 0; r < 4; r++) {
;           const int l = 16 * mb + 4 * (lane >> 4) + r;
;           float y = acc[r] + dsk * sU[l * 16 + (lane & 15)];
;           p.YG[(tok0 + sub * 32 + l) * 512 + g * 16 + (lane & 15)] = f2bf(geluf_(y));
;         }
;       }
	v_fmac_f32_e32 v43, v102, v40
	v_mul_f32_e32 v40, 0x3d372713, v43
	v_mul_f32_e32 v40, v43, v40
	v_fma_f32 v40, v43, v40, v43
	v_mul_f32_e32 v40, 0x3f4c422a, v40
	v_add_f32_e32 v40, v40, v40
	v_mul_f32_e32 v40, 0x3fb8aa3b, v40
	v_exp_f32_e32 v40, v40
	v_mul_f32_e32 v41, 0.5, v43
	v_add_f32_e32 v40, 1.0, v40
	v_rcp_f32_e32 v40, v40
	s_nop 0
	v_fma_f32 v40, v40, -2.0, 1.0
	v_add_f32_e32 v40, 1.0, v40
	v_mul_f32_e32 v40, v41, v40
	v_cvt_pk_bf16_f32 v42, v40, s0
	v_or_b32_e32 v40, s9, v88
	v_or_b32_e32 v76, s4, v40
	v_lshlrev_b64 v[40:41], 10, v[76:77]
	v_lshl_add_u64 v[40:41], v[72:73], 0, v[40:41]
	global_store_short v[40:41], v42, off
	v_mov_b32_e32 v40, v145
	ds_read_b128 v[104:107], v100 offset:6400
	ds_read_b32 v76, v91
	v_mov_b32_e32 v41, v40
	v_mov_b32_e32 v42, v40
	v_mov_b32_e32 v43, v40
	s_waitcnt lgkmcnt(1)
	s_nop 0
	v_mfma_f32_16x16x32_bf16 v[40:43], v[104:107], v[24:27], v[40:43]
	ds_read_b128 v[104:107], v100 offset:6464
	s_waitcnt lgkmcnt(0)
	v_mfma_f32_16x16x32_bf16 v[40:43], v[104:107], v[28:31], v[40:43]
	ds_read_b128 v[104:107], v100 offset:6528
	s_waitcnt lgkmcnt(0)
	v_mfma_f32_16x16x32_bf16 v[40:43], v[104:107], v[32:35], v[40:43]
	ds_read_b128 v[104:107], v100 offset:6592
	s_waitcnt lgkmcnt(0)
	v_mfma_f32_16x16x32_bf16 v[40:43], v[104:107], v[36:39], v[40:43]
	s_nop 7
	v_fma_f32 v40, v102, v76, v40
	v_mul_f32_e32 v76, 0x3d372713, v40
	v_mul_f32_e32 v76, v40, v76
	v_fma_f32 v76, v40, v76, v40
	v_mul_f32_e32 v76, 0x3f4c422a, v76
	v_add_f32_e32 v76, v76, v76
	v_mul_f32_e32 v76, 0x3fb8aa3b, v76
	v_exp_f32_e32 v76, v76
	v_mul_f32_e32 v40, 0.5, v40
	v_add_f32_e32 v76, 1.0, v76
	v_rcp_f32_e32 v76, v76
	s_nop 0
	v_fma_f32 v76, v76, -2.0, 1.0
	v_add_f32_e32 v76, 1.0, v76
	v_mul_f32_e32 v40, v40, v76
	v_or_b32_e32 v76, s9, v90
	v_or_b32_e32 v76, s4, v76
	v_lshlrev_b64 v[104:105], 10, v[76:77]
	v_cvt_pk_bf16_f32 v40, v40, s0
	v_lshl_add_u64 v[104:105], v[72:73], 0, v[104:105]
	global_store_short v[104:105], v40, off
	ds_read_b32 v40, v93
	s_waitcnt lgkmcnt(0)
	v_fma_f32 v40, v102, v40, v41
	v_mul_f32_e32 v41, 0x3d372713, v40
	v_mul_f32_e32 v41, v40, v41
	v_fma_f32 v41, v40, v41, v40
	v_mul_f32_e32 v41, 0x3f4c422a, v41
	v_add_f32_e32 v41, v41, v41
	v_mul_f32_e32 v41, 0x3fb8aa3b, v41
	v_exp_f32_e32 v41, v41
	v_mul_f32_e32 v40, 0.5, v40
	v_add_f32_e32 v41, 1.0, v41
	v_rcp_f32_e32 v41, v41
	s_nop 0
	v_fma_f32 v41, v41, -2.0, 1.0
	v_add_f32_e32 v41, 1.0, v41
	v_mul_f32_e32 v40, v40, v41
	v_cvt_pk_bf16_f32 v103, v40, s0
	v_or_b32_e32 v40, s9, v92
	v_or_b32_e32 v76, s4, v40
	v_lshlrev_b64 v[40:41], 10, v[76:77]
	v_lshl_add_u64 v[40:41], v[72:73], 0, v[40:41]
	global_store_short v[40:41], v103, off
	ds_read_b32 v40, v95
	s_waitcnt lgkmcnt(0)
	v_fma_f32 v40, v102, v40, v42
	v_mul_f32_e32 v41, 0x3d372713, v40
	v_mul_f32_e32 v41, v40, v41
	v_fma_f32 v41, v40, v41, v40
	v_mul_f32_e32 v41, 0x3f4c422a, v41
	v_add_f32_e32 v41, v41, v41
	v_mul_f32_e32 v41, 0x3fb8aa3b, v41
	v_exp_f32_e32 v41, v41
	v_mul_f32_e32 v40, 0.5, v40
	v_add_f32_e32 v41, 1.0, v41
	v_rcp_f32_e32 v41, v41
	s_nop 0
	v_fma_f32 v41, v41, -2.0, 1.0
	v_add_f32_e32 v41, 1.0, v41
	v_mul_f32_e32 v40, v40, v41
	v_cvt_pk_bf16_f32 v42, v40, s0
	v_or_b32_e32 v40, s9, v94
	v_or_b32_e32 v76, s4, v40
	v_lshlrev_b64 v[40:41], 10, v[76:77]
	v_lshl_add_u64 v[40:41], v[72:73], 0, v[40:41]
	global_store_short v[40:41], v42, off
	ds_read_b32 v40, v97
	s_waitcnt lgkmcnt(0)
	v_fmac_f32_e32 v43, v102, v40
	v_mul_f32_e32 v40, 0x3d372713, v43
	v_mul_f32_e32 v40, v43, v40
	v_fma_f32 v40, v43, v40, v43
	v_mul_f32_e32 v40, 0x3f4c422a, v40
	v_add_f32_e32 v40, v40, v40
	v_mul_f32_e32 v40, 0x3fb8aa3b, v40
	v_exp_f32_e32 v40, v40
	v_mul_f32_e32 v41, 0.5, v43
	v_add_f32_e32 v40, 1.0, v40
	v_rcp_f32_e32 v40, v40
	s_nop 0
	v_fma_f32 v40, v40, -2.0, 1.0
	v_add_f32_e32 v40, 1.0, v40
	v_mul_f32_e32 v40, v41, v40
	v_cvt_pk_bf16_f32 v42, v40, s0
	v_or_b32_e32 v40, s9, v96
	v_or_b32_e32 v76, s4, v40
	v_lshlrev_b64 v[40:41], 10, v[76:77]
	v_lshl_add_u64 v[40:41], v[72:73], 0, v[40:41]
	global_store_short v[40:41], v42, off
	s_cbranch_scc1 .LBB0_1789
	s_mov_b32 s11, s8
	s_branch .LBB0_1791

; __device__ __forceinline__ bf f2bf(float f) { return (bf)(pk2(f, 0.f) & 0xFFFFu); }
; __device__ __forceinline__ void s5_pass2(const Params& p, int layer, int task, char* sm) {
;     ...
;     for (int sub = 0; sub < 4; sub++) {
;       __builtin_amdgcn_wave_barrier();
;       if (lane < 32) s5_st_u(sU + lane * 16, ua, ub);
;       {
;         const int nsub = (sub + 1) & 3; const int ng = g + (sub == 3 ? 1 : 0);
;         if (sub < 3 || gi < 7) s5_ld_u(p, tok0 + nsub * 32 + (lane & 31), ng, ua, ub);
;       }
;       __builtin_amdgcn_wave_barrier();
;       for (int l = 0; l < 32; l++) {
;         S5_STEP(sU + l * 16)
;         sS[l * 136 + lane] = f2bf(sr); sS[l * 136 + 64 + lane] = f2bf(si);
.LBB0_2060:
	v_add_u32_e32 v103, v79, v40
	ds_read_b128 v[104:107], v79
	ds_read_b128 v[108:111], v79 offset:16
	ds_read_b128 v[112:115], v79 offset:32
	ds_read_b128 v[116:119], v79 offset:48
	ds_read_b128 v[120:123], v79 offset:64
	ds_read_b128 v[124:127], v79 offset:80
	ds_read_b128 v[128:131], v79 offset:96
	ds_read_b128 v[132:135], v79 offset:112
	s_waitcnt lgkmcnt(7)
	s_waitcnt lgkmcnt(3)
	v_pk_mul_f32 v[140:141], v[20:21], v[104:105] op_sel:[0,1]
	v_pk_mul_f32 v[142:143], v[20:21], v[120:121] op_sel:[0,1]
	v_pk_fma_f32 v[140:141], v[52:53], v[104:105], v[140:141] op_sel_hi:[1,0,1]
	v_pk_fma_f32 v[142:143], v[52:53], v[120:121], v[142:143] op_sel_hi:[1,0,1]
	v_pk_fma_f32 v[140:141], v[54:55], v[106:107], v[140:141] op_sel_hi:[1,0,1]
	v_pk_fma_f32 v[142:143], v[54:55], v[122:123], v[142:143] op_sel_hi:[1,0,1]
	v_pk_fma_f32 v[140:141], v[22:23], v[106:107], v[140:141] op_sel:[0,1,0]
	v_pk_fma_f32 v[142:143], v[22:23], v[122:123], v[142:143] op_sel:[0,1,0]
	ds_read_b128 v[104:107], v79 offset:128
	ds_read_b128 v[120:123], v79 offset:192
	s_waitcnt lgkmcnt(8)
	s_waitcnt lgkmcnt(4)
	v_pk_fma_f32 v[140:141], v[56:57], v[108:109], v[140:141] op_sel_hi:[1,0,1]
	v_pk_fma_f32 v[142:143], v[56:57], v[124:125], v[142:143] op_sel_hi:[1,0,1]
	v_pk_fma_f32 v[140:141], v[16:17], v[108:109], v[140:141] op_sel:[0,1,0]
	v_pk_fma_f32 v[142:143], v[16:17], v[124:125], v[142:143] op_sel:[0,1,0]
	v_pk_fma_f32 v[140:141], v[58:59], v[110:111], v[140:141] op_sel_hi:[1,0,1]
	v_pk_fma_f32 v[142:143], v[58:59], v[126:127], v[142:143] op_sel_hi:[1,0,1]
	v_pk_fma_f32 v[140:141], v[18:19], v[110:111], v[140:141] op_sel:[0,1,0]
	v_pk_fma_f32 v[142:143], v[18:19], v[126:127], v[142:143] op_sel:[0,1,0]
	ds_read_b128 v[108:111], v79 offset:144
	ds_read_b128 v[124:127], v79 offset:208
	s_waitcnt lgkmcnt(9)
	s_waitcnt lgkmcnt(5)
	v_pk_fma_f32 v[140:141], v[60:61], v[112:113], v[140:141] op_sel_hi:[1,0,1]
	v_pk_fma_f32 v[142:143], v[60:61], v[128:129], v[142:143] op_sel_hi:[1,0,1]
	v_pk_fma_f32 v[140:141], v[12:13], v[112:113], v[140:141] op_sel:[0,1,0]
	v_pk_fma_f32 v[142:143], v[12:13], v[128:129], v[142:143] op_sel:[0,1,0]
	v_pk_fma_f32 v[140:141], v[62:63], v[114:115], v[140:141] op_sel_hi:[1,0,1]
	v_pk_fma_f32 v[142:143], v[62:63], v[130:131], v[142:143] op_sel_hi:[1,0,1]
	v_pk_fma_f32 v[140:141], v[14:15], v[114:115], v[140:141] op_sel:[0,1,0]
	v_pk_fma_f32 v[142:143], v[14:15], v[130:131], v[142:143] op_sel:[0,1,0]
	ds_read_b128 v[112:115], v79 offset:160
	ds_read_b128 v[128:131], v79 offset:224
	s_waitcnt lgkmcnt(10)
	s_waitcnt lgkmcnt(6)
	v_pk_fma_f32 v[140:141], v[64:65], v[116:117], v[140:141] op_sel_hi:[1,0,1]
	v_pk_fma_f32 v[142:143], v[64:65], v[132:133], v[142:143] op_sel_hi:[1,0,1]
	v_pk_fma_f32 v[140:141], v[8:9], v[116:117], v[140:141] op_sel:[0,1,0]
	v_pk_fma_f32 v[142:143], v[8:9], v[132:133], v[142:143] op_sel:[0,1,0]
	v_pk_fma_f32 v[140:141], v[66:67], v[118:119], v[140:141] op_sel_hi:[1,0,1]
	v_pk_fma_f32 v[142:143], v[66:67], v[134:135], v[142:143] op_sel_hi:[1,0,1]
	v_pk_fma_f32 v[140:141], v[10:11], v[118:119], v[140:141] op_sel:[0,1,0]
	v_pk_fma_f32 v[142:143], v[10:11], v[134:135], v[142:143] op_sel:[0,1,0]
	ds_read_b128 v[116:119], v79 offset:176
	ds_read_b128 v[132:135], v79 offset:240
	s_waitcnt vmcnt(5)
	s_waitcnt lgkmcnt(7)
	s_waitcnt lgkmcnt(6)
	v_pk_mul_f32 v[136:137], v[20:21], v[104:105] op_sel:[0,1]
	v_pk_mul_f32 v[138:139], v[20:21], v[120:121] op_sel:[0,1]
	v_pk_mul_f32 v[76:77], v[74:75], v[70:71] op_sel:[0,1]
	v_pk_fma_f32 v[136:137], v[52:53], v[104:105], v[136:137] op_sel_hi:[1,0,1]
	v_pk_fma_f32 v[138:139], v[52:53], v[120:121], v[138:139] op_sel_hi:[1,0,1]
	v_pk_fma_f32 v[146:147], v[68:69], v[70:71], v[76:77] op_sel_hi:[1,0,1] neg_lo:[0,0,1]
	v_pk_fma_f32 v[136:137], v[54:55], v[106:107], v[136:137] op_sel_hi:[1,0,1]
	v_pk_fma_f32 v[138:139], v[54:55], v[122:123], v[138:139] op_sel_hi:[1,0,1]
	v_pk_add_f32 v[42:43], v[146:147], v[140:141]
	v_pk_fma_f32 v[136:137], v[22:23], v[106:107], v[136:137] op_sel:[0,1,0]
	v_pk_fma_f32 v[138:139], v[22:23], v[122:123], v[138:139] op_sel:[0,1,0]
	v_cvt_pk_bf16_f32 v150, v42, v43
	ds_write_b16 v103, v150
	ds_write_b16_d16_hi v103, v150 offset:128
	ds_read_b128 v[104:107], v79 offset:256
	ds_read_b128 v[120:123], v79 offset:320
	s_waitcnt lgkmcnt(9)
	s_waitcnt lgkmcnt(8)
	v_pk_fma_f32 v[136:137], v[56:57], v[108:109], v[136:137] op_sel_hi:[1,0,1]
	v_pk_fma_f32 v[138:139], v[56:57], v[124:125], v[138:139] op_sel_hi:[1,0,1]
	v_pk_mul_f32 v[76:77], v[74:75], v[42:43] op_sel:[0,1]
	v_pk_fma_f32 v[136:137], v[16:17], v[108:109], v[136:137] op_sel:[0,1,0]
	v_pk_fma_f32 v[138:139], v[16:17], v[124:125], v[138:139] op_sel:[0,1,0]
	v_pk_fma_f32 v[146:147], v[68:69], v[42:43], v[76:77] op_sel_hi:[1,0,1] neg_lo:[0,0,1]
	v_pk_fma_f32 v[136:137], v[58:59], v[110:111], v[136:137] op_sel_hi:[1,0,1]
	v_pk_fma_f32 v[138:139], v[58:59], v[126:127], v[138:139] op_sel_hi:[1,0,1]
	v_pk_add_f32 v[70:71], v[146:147], v[142:143]
	v_pk_fma_f32 v[136:137], v[18:19], v[110:111], v[136:137] op_sel:[0,1,0]
	v_pk_fma_f32 v[138:139], v[18:19], v[126:127], v[138:139] op_sel:[0,1,0]
	v_cvt_pk_bf16_f32 v150, v70, v71
	ds_write_b16 v103, v150 offset:272
	ds_write_b16_d16_hi v103, v150 offset:400
	ds_read_b128 v[108:111], v79 offset:272
	ds_read_b128 v[124:127], v79 offset:336
	s_waitcnt lgkmcnt(11)
	s_waitcnt lgkmcnt(10)
; __device__ __forceinline__ bf f2bf(float f) { return (bf)(pk2(f, 0.f) & 0xFFFFu); }
; __device__ __forceinline__ void s5_pass2(const Params& p, int layer, int task, char* sm) {
;     ...
;       for (int l = 0; l < 32; l++) {
;         S5_STEP(sU + l * 16)
;         sS[l * 136 + lane] = f2bf(sr); sS[l * 136 + 64 + lane] = f2bf(si);
	v_pk_fma_f32 v[136:137], v[60:61], v[112:113], v[136:137] op_sel_hi:[1,0,1]
	v_pk_fma_f32 v[138:139], v[60:61], v[128:129], v[138:139] op_sel_hi:[1,0,1]
	v_pk_fma_f32 v[136:137], v[12:13], v[112:113], v[136:137] op_sel:[0,1,0]
	v_pk_fma_f32 v[138:139], v[12:13], v[128:129], v[138:139] op_sel:[0,1,0]
	v_pk_fma_f32 v[136:137], v[62:63], v[114:115], v[136:137] op_sel_hi:[1,0,1]
	v_pk_fma_f32 v[138:139], v[62:63], v[130:131], v[138:139] op_sel_hi:[1,0,1]
	v_pk_fma_f32 v[136:137], v[14:15], v[114:115], v[136:137] op_sel:[0,1,0]
	v_pk_fma_f32 v[138:139], v[14:15], v[130:131], v[138:139] op_sel:[0,1,0]
	ds_read_b128 v[112:115], v79 offset:288
	ds_read_b128 v[128:131], v79 offset:352
	s_waitcnt lgkmcnt(11)
	s_waitcnt lgkmcnt(10)
	v_pk_fma_f32 v[136:137], v[64:65], v[116:117], v[136:137] op_sel_hi:[1,0,1]
	v_pk_fma_f32 v[138:139], v[64:65], v[132:133], v[138:139] op_sel_hi:[1,0,1]
	v_pk_fma_f32 v[136:137], v[8:9], v[116:117], v[136:137] op_sel:[0,1,0]
	v_pk_fma_f32 v[138:139], v[8:9], v[132:133], v[138:139] op_sel:[0,1,0]
	v_pk_fma_f32 v[136:137], v[66:67], v[118:119], v[136:137] op_sel_hi:[1,0,1]
	v_pk_fma_f32 v[138:139], v[66:67], v[134:135], v[138:139] op_sel_hi:[1,0,1]
	v_pk_fma_f32 v[136:137], v[10:11], v[118:119], v[136:137] op_sel:[0,1,0]
	v_pk_fma_f32 v[138:139], v[10:11], v[134:135], v[138:139] op_sel:[0,1,0]
	ds_read_b128 v[116:119], v79 offset:304
	ds_read_b128 v[132:135], v79 offset:368
	s_waitcnt lgkmcnt(9)
	s_waitcnt lgkmcnt(8)
	v_pk_mul_f32 v[140:141], v[20:21], v[104:105] op_sel:[0,1]
	v_pk_mul_f32 v[142:143], v[20:21], v[120:121] op_sel:[0,1]
	v_pk_mul_f32 v[76:77], v[74:75], v[70:71] op_sel:[0,1]
	v_pk_fma_f32 v[140:141], v[52:53], v[104:105], v[140:141] op_sel_hi:[1,0,1]
	v_pk_fma_f32 v[142:143], v[52:53], v[120:121], v[142:143] op_sel_hi:[1,0,1]
	v_pk_fma_f32 v[146:147], v[68:69], v[70:71], v[76:77] op_sel_hi:[1,0,1] neg_lo:[0,0,1]
	v_pk_fma_f32 v[140:141], v[54:55], v[106:107], v[140:141] op_sel_hi:[1,0,1]
	v_pk_fma_f32 v[142:143], v[54:55], v[122:123], v[142:143] op_sel_hi:[1,0,1]
	v_pk_add_f32 v[42:43], v[146:147], v[136:137]
	v_pk_fma_f32 v[140:141], v[22:23], v[106:107], v[140:141] op_sel:[0,1,0]
	v_pk_fma_f32 v[142:143], v[22:23], v[122:123], v[142:143] op_sel:[0,1,0]
	v_cvt_pk_bf16_f32 v150, v42, v43
	ds_write_b16 v103, v150 offset:544
	ds_write_b16_d16_hi v103, v150 offset:672
	ds_read_b128 v[104:107], v79 offset:384
	ds_read_b128 v[120:123], v79 offset:448
	s_waitcnt lgkmcnt(9)
	s_waitcnt lgkmcnt(8)
	v_pk_fma_f32 v[140:141], v[56:57], v[108:109], v[140:141] op_sel_hi:[1,0,1]
	v_pk_fma_f32 v[142:143], v[56:57], v[124:125], v[142:143] op_sel_hi:[1,0,1]
	v_pk_mul_f32 v[76:77], v[74:75], v[42:43] op_sel:[0,1]
	v_pk_fma_f32 v[140:141], v[16:17], v[108:109], v[140:141] op_sel:[0,1,0]
	v_pk_fma_f32 v[142:143], v[16:17], v[124:125], v[142:143] op_sel:[0,1,0]
	v_pk_fma_f32 v[146:147], v[68:69], v[42:43], v[76:77] op_sel_hi:[1,0,1] neg_lo:[0,0,1]
	v_pk_fma_f32 v[140:141], v[58:59], v[110:111], v[140:141] op_sel_hi:[1,0,1]
	v_pk_fma_f32 v[142:143], v[58:59], v[126:127], v[142:143] op_sel_hi:[1,0,1]
	v_pk_add_f32 v[70:71], v[146:147], v[138:139]
	v_pk_fma_f32 v[140:141], v[18:19], v[110:111], v[140:141] op_sel:[0,1,0]
	v_pk_fma_f32 v[142:143], v[18:19], v[126:127], v[142:143] op_sel:[0,1,0]
	v_cvt_pk_bf16_f32 v150, v70, v71
	ds_write_b16 v103, v150 offset:816
	ds_write_b16_d16_hi v103, v150 offset:944
	ds_read_b128 v[108:111], v79 offset:400
	ds_read_b128 v[124:127], v79 offset:464
	s_waitcnt lgkmcnt(11)
	s_waitcnt lgkmcnt(10)
	v_pk_fma_f32 v[140:141], v[60:61], v[112:113], v[140:141] op_sel_hi:[1,0,1]
	v_pk_fma_f32 v[142:143], v[60:61], v[128:129], v[142:143] op_sel_hi:[1,0,1]
	v_pk_fma_f32 v[140:141], v[12:13], v[112:113], v[140:141] op_sel:[0,1,0]
	v_pk_fma_f32 v[142:143], v[12:13], v[128:129], v[142:143] op_sel:[0,1,0]
	v_pk_fma_f32 v[140:141], v[62:63], v[114:115], v[140:141] op_sel_hi:[1,0,1]
	v_pk_fma_f32 v[142:143], v[62:63], v[130:131], v[142:143] op_sel_hi:[1,0,1]
	v_pk_fma_f32 v[140:141], v[14:15], v[114:115], v[140:141] op_sel:[0,1,0]
	v_pk_fma_f32 v[142:143], v[14:15], v[130:131], v[142:143] op_sel:[0,1,0]
	ds_read_b128 v[112:115], v79 offset:416
	ds_read_b128 v[128:131], v79 offset:480
	s_waitcnt lgkmcnt(11)
	s_waitcnt lgkmcnt(10)
	v_pk_fma_f32 v[140:141], v[64:65], v[116:117], v[140:141] op_sel_hi:[1,0,1]
	v_pk_fma_f32 v[142:143], v[64:65], v[132:133], v[142:143] op_sel_hi:[1,0,1]
	v_pk_fma_f32 v[140:141], v[8:9], v[116:117], v[140:141] op_sel:[0,1,0]
	v_pk_fma_f32 v[142:143], v[8:9], v[132:133], v[142:143] op_sel:[0,1,0]
	v_pk_fma_f32 v[140:141], v[66:67], v[118:119], v[140:141] op_sel_hi:[1,0,1]
	v_pk_fma_f32 v[142:143], v[66:67], v[134:135], v[142:143] op_sel_hi:[1,0,1]
	v_pk_fma_f32 v[140:141], v[10:11], v[118:119], v[140:141] op_sel:[0,1,0]
	v_pk_fma_f32 v[142:143], v[10:11], v[134:135], v[142:143] op_sel:[0,1,0]
	ds_read_b128 v[116:119], v79 offset:432
	ds_read_b128 v[132:135], v79 offset:496
	s_waitcnt lgkmcnt(9)
	s_waitcnt lgkmcnt(8)
	v_pk_mul_f32 v[136:137], v[20:21], v[104:105] op_sel:[0,1]
	v_pk_mul_f32 v[138:139], v[20:21], v[120:121] op_sel:[0,1]
	v_pk_mul_f32 v[76:77], v[74:75], v[70:71] op_sel:[0,1]
	v_pk_fma_f32 v[136:137], v[52:53], v[104:105], v[136:137] op_sel_hi:[1,0,1]
	v_pk_fma_f32 v[138:139], v[52:53], v[120:121], v[138:139] op_sel_hi:[1,0,1]
	v_pk_fma_f32 v[146:147], v[68:69], v[70:71], v[76:77] op_sel_hi:[1,0,1] neg_lo:[0,0,1]
	v_pk_fma_f32 v[136:137], v[54:55], v[106:107], v[136:137] op_sel_hi:[1,0,1]
	v_pk_fma_f32 v[138:139], v[54:55], v[122:123], v[138:139] op_sel_hi:[1,0,1]
	v_pk_add_f32 v[42:43], v[146:147], v[140:141]
	v_pk_fma_f32 v[136:137], v[22:23], v[106:107], v[136:137] op_sel:[0,1,0]
	v_pk_fma_f32 v[138:139], v[22:23], v[122:123], v[138:139] op_sel:[0,1,0]
	v_cvt_pk_bf16_f32 v150, v42, v43
	ds_write_b16 v103, v150 offset:1088
	ds_write_b16_d16_hi v103, v150 offset:1216
	ds_read_b128 v[104:107], v79 offset:512
	ds_read_b128 v[120:123], v79 offset:576
	s_waitcnt lgkmcnt(9)
; __device__ __forceinline__ bf f2bf(float f) { return (bf)(pk2(f, 0.f) & 0xFFFFu); }
; __device__ __forceinline__ void s5_pass2(const Params& p, int layer, int task, char* sm) {
;     ...
;       for (int l = 0; l < 32; l++) {
;         S5_STEP(sU + l * 16)
;         sS[l * 136 + lane] = f2bf(sr); sS[l * 136 + 64 + lane] = f2bf(si);
	s_waitcnt lgkmcnt(8)
	v_pk_fma_f32 v[136:137], v[56:57], v[108:109], v[136:137] op_sel_hi:[1,0,1]
	v_pk_fma_f32 v[138:139], v[56:57], v[124:125], v[138:139] op_sel_hi:[1,0,1]
	v_pk_mul_f32 v[76:77], v[74:75], v[42:43] op_sel:[0,1]
	v_pk_fma_f32 v[136:137], v[16:17], v[108:109], v[136:137] op_sel:[0,1,0]
	v_pk_fma_f32 v[138:139], v[16:17], v[124:125], v[138:139] op_sel:[0,1,0]
	v_pk_fma_f32 v[146:147], v[68:69], v[42:43], v[76:77] op_sel_hi:[1,0,1] neg_lo:[0,0,1]
	v_pk_fma_f32 v[136:137], v[58:59], v[110:111], v[136:137] op_sel_hi:[1,0,1]
	v_pk_fma_f32 v[138:139], v[58:59], v[126:127], v[138:139] op_sel_hi:[1,0,1]
	v_pk_add_f32 v[70:71], v[146:147], v[142:143]
	v_pk_fma_f32 v[136:137], v[18:19], v[110:111], v[136:137] op_sel:[0,1,0]
	v_pk_fma_f32 v[138:139], v[18:19], v[126:127], v[138:139] op_sel:[0,1,0]
	v_cvt_pk_bf16_f32 v150, v70, v71
	ds_write_b16 v103, v150 offset:1360
	ds_write_b16_d16_hi v103, v150 offset:1488
	ds_read_b128 v[108:111], v79 offset:528
	ds_read_b128 v[124:127], v79 offset:592
	s_waitcnt lgkmcnt(11)
	s_waitcnt lgkmcnt(10)
	v_pk_fma_f32 v[136:137], v[60:61], v[112:113], v[136:137] op_sel_hi:[1,0,1]
	v_pk_fma_f32 v[138:139], v[60:61], v[128:129], v[138:139] op_sel_hi:[1,0,1]
	v_pk_fma_f32 v[136:137], v[12:13], v[112:113], v[136:137] op_sel:[0,1,0]
	v_pk_fma_f32 v[138:139], v[12:13], v[128:129], v[138:139] op_sel:[0,1,0]
	v_pk_fma_f32 v[136:137], v[62:63], v[114:115], v[136:137] op_sel_hi:[1,0,1]
	v_pk_fma_f32 v[138:139], v[62:63], v[130:131], v[138:139] op_sel_hi:[1,0,1]
	v_pk_fma_f32 v[136:137], v[14:15], v[114:115], v[136:137] op_sel:[0,1,0]
	v_pk_fma_f32 v[138:139], v[14:15], v[130:131], v[138:139] op_sel:[0,1,0]
	ds_read_b128 v[112:115], v79 offset:544
	ds_read_b128 v[128:131], v79 offset:608
	s_waitcnt lgkmcnt(11)
	s_waitcnt lgkmcnt(10)
	v_pk_fma_f32 v[136:137], v[64:65], v[116:117], v[136:137] op_sel_hi:[1,0,1]
	v_pk_fma_f32 v[138:139], v[64:65], v[132:133], v[138:139] op_sel_hi:[1,0,1]
	v_pk_fma_f32 v[136:137], v[8:9], v[116:117], v[136:137] op_sel:[0,1,0]
	v_pk_fma_f32 v[138:139], v[8:9], v[132:133], v[138:139] op_sel:[0,1,0]
	v_pk_fma_f32 v[136:137], v[66:67], v[118:119], v[136:137] op_sel_hi:[1,0,1]
	v_pk_fma_f32 v[138:139], v[66:67], v[134:135], v[138:139] op_sel_hi:[1,0,1]
	v_pk_fma_f32 v[136:137], v[10:11], v[118:119], v[136:137] op_sel:[0,1,0]
	v_pk_fma_f32 v[138:139], v[10:11], v[134:135], v[138:139] op_sel:[0,1,0]
	ds_read_b128 v[116:119], v79 offset:560
	ds_read_b128 v[132:135], v79 offset:624
	s_waitcnt lgkmcnt(9)
	s_waitcnt lgkmcnt(8)
	v_pk_mul_f32 v[140:141], v[20:21], v[104:105] op_sel:[0,1]
	v_pk_mul_f32 v[142:143], v[20:21], v[120:121] op_sel:[0,1]
	v_pk_mul_f32 v[76:77], v[74:75], v[70:71] op_sel:[0,1]
	v_pk_fma_f32 v[140:141], v[52:53], v[104:105], v[140:141] op_sel_hi:[1,0,1]
	v_pk_fma_f32 v[142:143], v[52:53], v[120:121], v[142:143] op_sel_hi:[1,0,1]
	v_pk_fma_f32 v[146:147], v[68:69], v[70:71], v[76:77] op_sel_hi:[1,0,1] neg_lo:[0,0,1]
	v_pk_fma_f32 v[140:141], v[54:55], v[106:107], v[140:141] op_sel_hi:[1,0,1]
	v_pk_fma_f32 v[142:143], v[54:55], v[122:123], v[142:143] op_sel_hi:[1,0,1]
	v_pk_add_f32 v[42:43], v[146:147], v[136:137]
	v_pk_fma_f32 v[140:141], v[22:23], v[106:107], v[140:141] op_sel:[0,1,0]
	v_pk_fma_f32 v[142:143], v[22:23], v[122:123], v[142:143] op_sel:[0,1,0]
	v_cvt_pk_bf16_f32 v150, v42, v43
	ds_write_b16 v103, v150 offset:1632
	ds_write_b16_d16_hi v103, v150 offset:1760
	ds_read_b128 v[104:107], v79 offset:640
	ds_read_b128 v[120:123], v79 offset:704
	s_waitcnt lgkmcnt(9)
	s_waitcnt lgkmcnt(8)
	v_pk_fma_f32 v[140:141], v[56:57], v[108:109], v[140:141] op_sel_hi:[1,0,1]
	v_pk_fma_f32 v[142:143], v[56:57], v[124:125], v[142:143] op_sel_hi:[1,0,1]
	v_pk_mul_f32 v[76:77], v[74:75], v[42:43] op_sel:[0,1]
	v_pk_fma_f32 v[140:141], v[16:17], v[108:109], v[140:141] op_sel:[0,1,0]
	v_pk_fma_f32 v[142:143], v[16:17], v[124:125], v[142:143] op_sel:[0,1,0]
	v_pk_fma_f32 v[146:147], v[68:69], v[42:43], v[76:77] op_sel_hi:[1,0,1] neg_lo:[0,0,1]
	v_pk_fma_f32 v[140:141], v[58:59], v[110:111], v[140:141] op_sel_hi:[1,0,1]
	v_pk_fma_f32 v[142:143], v[58:59], v[126:127], v[142:143] op_sel_hi:[1,0,1]
	v_pk_add_f32 v[70:71], v[146:147], v[138:139]
	v_pk_fma_f32 v[140:141], v[18:19], v[110:111], v[140:141] op_sel:[0,1,0]
	v_pk_fma_f32 v[142:143], v[18:19], v[126:127], v[142:143] op_sel:[0,1,0]
	v_cvt_pk_bf16_f32 v150, v70, v71
	ds_write_b16 v103, v150 offset:1904
	ds_write_b16_d16_hi v103, v150 offset:2032
	ds_read_b128 v[108:111], v79 offset:656
	ds_read_b128 v[124:127], v79 offset:720
	s_waitcnt lgkmcnt(11)
	s_waitcnt lgkmcnt(10)
	v_pk_fma_f32 v[140:141], v[60:61], v[112:113], v[140:141] op_sel_hi:[1,0,1]
	v_pk_fma_f32 v[142:143], v[60:61], v[128:129], v[142:143] op_sel_hi:[1,0,1]
	v_pk_fma_f32 v[140:141], v[12:13], v[112:113], v[140:141] op_sel:[0,1,0]
	v_pk_fma_f32 v[142:143], v[12:13], v[128:129], v[142:143] op_sel:[0,1,0]
	v_pk_fma_f32 v[140:141], v[62:63], v[114:115], v[140:141] op_sel_hi:[1,0,1]
	v_pk_fma_f32 v[142:143], v[62:63], v[130:131], v[142:143] op_sel_hi:[1,0,1]
	v_pk_fma_f32 v[140:141], v[14:15], v[114:115], v[140:141] op_sel:[0,1,0]
	v_pk_fma_f32 v[142:143], v[14:15], v[130:131], v[142:143] op_sel:[0,1,0]
	ds_read_b128 v[112:115], v79 offset:672
	ds_read_b128 v[128:131], v79 offset:736
	s_waitcnt lgkmcnt(11)
	s_waitcnt lgkmcnt(10)
; __device__ __forceinline__ bf f2bf(float f) { return (bf)(pk2(f, 0.f) & 0xFFFFu); }
; __device__ __forceinline__ void s5_pass2(const Params& p, int layer, int task, char* sm) {
;     ...
;       for (int l = 0; l < 32; l++) {
;         S5_STEP(sU + l * 16)
;         sS[l * 136 + lane] = f2bf(sr); sS[l * 136 + 64 + lane] = f2bf(si);
;       }
	v_pk_fma_f32 v[140:141], v[64:65], v[116:117], v[140:141] op_sel_hi:[1,0,1]
	v_pk_fma_f32 v[142:143], v[64:65], v[132:133], v[142:143] op_sel_hi:[1,0,1]
	v_pk_fma_f32 v[140:141], v[8:9], v[116:117], v[140:141] op_sel:[0,1,0]
	v_pk_fma_f32 v[142:143], v[8:9], v[132:133], v[142:143] op_sel:[0,1,0]
	v_pk_fma_f32 v[140:141], v[66:67], v[118:119], v[140:141] op_sel_hi:[1,0,1]
	v_pk_fma_f32 v[142:143], v[66:67], v[134:135], v[142:143] op_sel_hi:[1,0,1]
	v_pk_fma_f32 v[140:141], v[10:11], v[118:119], v[140:141] op_sel:[0,1,0]
	v_pk_fma_f32 v[142:143], v[10:11], v[134:135], v[142:143] op_sel:[0,1,0]
	ds_read_b128 v[116:119], v79 offset:688
	ds_read_b128 v[132:135], v79 offset:752
	s_waitcnt lgkmcnt(9)
	s_waitcnt lgkmcnt(8)
	v_pk_mul_f32 v[136:137], v[20:21], v[104:105] op_sel:[0,1]
	v_pk_mul_f32 v[138:139], v[20:21], v[120:121] op_sel:[0,1]
	v_pk_mul_f32 v[76:77], v[74:75], v[70:71] op_sel:[0,1]
	v_pk_fma_f32 v[136:137], v[52:53], v[104:105], v[136:137] op_sel_hi:[1,0,1]
	v_pk_fma_f32 v[138:139], v[52:53], v[120:121], v[138:139] op_sel_hi:[1,0,1]
	v_pk_fma_f32 v[146:147], v[68:69], v[70:71], v[76:77] op_sel_hi:[1,0,1] neg_lo:[0,0,1]
	v_pk_fma_f32 v[136:137], v[54:55], v[106:107], v[136:137] op_sel_hi:[1,0,1]
	v_pk_fma_f32 v[138:139], v[54:55], v[122:123], v[138:139] op_sel_hi:[1,0,1]
	v_pk_add_f32 v[42:43], v[146:147], v[140:141]
	v_pk_fma_f32 v[136:137], v[22:23], v[106:107], v[136:137] op_sel:[0,1,0]
	v_pk_fma_f32 v[138:139], v[22:23], v[122:123], v[138:139] op_sel:[0,1,0]
	v_cvt_pk_bf16_f32 v150, v42, v43
	ds_write_b16 v103, v150 offset:2176
	ds_write_b16_d16_hi v103, v150 offset:2304
	ds_read_b128 v[104:107], v79 offset:768
	ds_read_b128 v[120:123], v79 offset:832
	s_waitcnt lgkmcnt(9)
	s_waitcnt lgkmcnt(8)
	v_pk_fma_f32 v[136:137], v[56:57], v[108:109], v[136:137] op_sel_hi:[1,0,1]
	v_pk_fma_f32 v[138:139], v[56:57], v[124:125], v[138:139] op_sel_hi:[1,0,1]
	v_pk_mul_f32 v[76:77], v[74:75], v[42:43] op_sel:[0,1]
	v_pk_fma_f32 v[136:137], v[16:17], v[108:109], v[136:137] op_sel:[0,1,0]
	v_pk_fma_f32 v[138:139], v[16:17], v[124:125], v[138:139] op_sel:[0,1,0]
	v_pk_fma_f32 v[146:147], v[68:69], v[42:43], v[76:77] op_sel_hi:[1,0,1] neg_lo:[0,0,1]
	v_pk_fma_f32 v[136:137], v[58:59], v[110:111], v[136:137] op_sel_hi:[1,0,1]
	v_pk_fma_f32 v[138:139], v[58:59], v[126:127], v[138:139] op_sel_hi:[1,0,1]
	v_pk_add_f32 v[70:71], v[146:147], v[142:143]
	v_pk_fma_f32 v[136:137], v[18:19], v[110:111], v[136:137] op_sel:[0,1,0]
	v_pk_fma_f32 v[138:139], v[18:19], v[126:127], v[138:139] op_sel:[0,1,0]
	v_cvt_pk_bf16_f32 v150, v70, v71
	ds_write_b16 v103, v150 offset:2448
	ds_write_b16_d16_hi v103, v150 offset:2576
	ds_read_b128 v[108:111], v79 offset:784
	ds_read_b128 v[124:127], v79 offset:848
	s_waitcnt lgkmcnt(11)
	s_waitcnt lgkmcnt(10)
	v_pk_fma_f32 v[136:137], v[60:61], v[112:113], v[136:137] op_sel_hi:[1,0,1]
	v_pk_fma_f32 v[138:139], v[60:61], v[128:129], v[138:139] op_sel_hi:[1,0,1]
	v_pk_fma_f32 v[136:137], v[12:13], v[112:113], v[136:137] op_sel:[0,1,0]
	v_pk_fma_f32 v[138:139], v[12:13], v[128:129], v[138:139] op_sel:[0,1,0]
	v_pk_fma_f32 v[136:137], v[62:63], v[114:115], v[136:137] op_sel_hi:[1,0,1]
	v_pk_fma_f32 v[138:139], v[62:63], v[130:131], v[138:139] op_sel_hi:[1,0,1]
	v_pk_fma_f32 v[136:137], v[14:15], v[114:115], v[136:137] op_sel:[0,1,0]
	v_pk_fma_f32 v[138:139], v[14:15], v[130:131], v[138:139] op_sel:[0,1,0]
	ds_read_b128 v[112:115], v79 offset:800
	ds_read_b128 v[128:131], v79 offset:864
	s_waitcnt lgkmcnt(11)
	s_waitcnt lgkmcnt(10)
	v_pk_fma_f32 v[136:137], v[64:65], v[116:117], v[136:137] op_sel_hi:[1,0,1]
	v_pk_fma_f32 v[138:139], v[64:65], v[132:133], v[138:139] op_sel_hi:[1,0,1]
	v_pk_fma_f32 v[136:137], v[8:9], v[116:117], v[136:137] op_sel:[0,1,0]
	v_pk_fma_f32 v[138:139], v[8:9], v[132:133], v[138:139] op_sel:[0,1,0]
	v_pk_fma_f32 v[136:137], v[66:67], v[118:119], v[136:137] op_sel_hi:[1,0,1]
	v_pk_fma_f32 v[138:139], v[66:67], v[134:135], v[138:139] op_sel_hi:[1,0,1]
	v_pk_fma_f32 v[136:137], v[10:11], v[118:119], v[136:137] op_sel:[0,1,0]
	v_pk_fma_f32 v[138:139], v[10:11], v[134:135], v[138:139] op_sel:[0,1,0]
	ds_read_b128 v[116:119], v79 offset:816
	ds_read_b128 v[132:135], v79 offset:880
	s_waitcnt lgkmcnt(9)
	s_waitcnt lgkmcnt(8)
	v_pk_mul_f32 v[140:141], v[20:21], v[104:105] op_sel:[0,1]
	v_pk_mul_f32 v[142:143], v[20:21], v[120:121] op_sel:[0,1]
	v_pk_mul_f32 v[76:77], v[74:75], v[70:71] op_sel:[0,1]
	v_pk_fma_f32 v[140:141], v[52:53], v[104:105], v[140:141] op_sel_hi:[1,0,1]
	v_pk_fma_f32 v[142:143], v[52:53], v[120:121], v[142:143] op_sel_hi:[1,0,1]
	v_pk_fma_f32 v[146:147], v[68:69], v[70:71], v[76:77] op_sel_hi:[1,0,1] neg_lo:[0,0,1]
	v_pk_fma_f32 v[140:141], v[54:55], v[106:107], v[140:141] op_sel_hi:[1,0,1]
	v_pk_fma_f32 v[142:143], v[54:55], v[122:123], v[142:143] op_sel_hi:[1,0,1]
	v_pk_add_f32 v[42:43], v[146:147], v[136:137]
	v_pk_fma_f32 v[140:141], v[22:23], v[106:107], v[140:141] op_sel:[0,1,0]
	v_pk_fma_f32 v[142:143], v[22:23], v[122:123], v[142:143] op_sel:[0,1,0]
	v_cvt_pk_bf16_f32 v150, v42, v43
	ds_write_b16 v103, v150 offset:2720
	ds_write_b16_d16_hi v103, v150 offset:2848
	ds_read_b128 v[104:107], v79 offset:896
	ds_read_b128 v[120:123], v79 offset:960
	s_waitcnt lgkmcnt(9)
	s_waitcnt lgkmcnt(8)
; __device__ __forceinline__ bf f2bf(float f) { return (bf)(pk2(f, 0.f) & 0xFFFFu); }
; __device__ __forceinline__ void s5_pass2(const Params& p, int layer, int task, char* sm) {
;     ...
;       for (int l = 0; l < 32; l++) {
;         S5_STEP(sU + l * 16)
;         sS[l * 136 + lane] = f2bf(sr); sS[l * 136 + 64 + lane] = f2bf(si);
;       }
	v_pk_fma_f32 v[140:141], v[56:57], v[108:109], v[140:141] op_sel_hi:[1,0,1]
	v_pk_fma_f32 v[142:143], v[56:57], v[124:125], v[142:143] op_sel_hi:[1,0,1]
	v_pk_mul_f32 v[76:77], v[74:75], v[42:43] op_sel:[0,1]
	v_pk_fma_f32 v[140:141], v[16:17], v[108:109], v[140:141] op_sel:[0,1,0]
	v_pk_fma_f32 v[142:143], v[16:17], v[124:125], v[142:143] op_sel:[0,1,0]
	v_pk_fma_f32 v[146:147], v[68:69], v[42:43], v[76:77] op_sel_hi:[1,0,1] neg_lo:[0,0,1]
	v_pk_fma_f32 v[140:141], v[58:59], v[110:111], v[140:141] op_sel_hi:[1,0,1]
	v_pk_fma_f32 v[142:143], v[58:59], v[126:127], v[142:143] op_sel_hi:[1,0,1]
	v_pk_add_f32 v[70:71], v[146:147], v[138:139]
	v_pk_fma_f32 v[140:141], v[18:19], v[110:111], v[140:141] op_sel:[0,1,0]
	v_pk_fma_f32 v[142:143], v[18:19], v[126:127], v[142:143] op_sel:[0,1,0]
	v_cvt_pk_bf16_f32 v150, v70, v71
	ds_write_b16 v103, v150 offset:2992
	ds_write_b16_d16_hi v103, v150 offset:3120
	ds_read_b128 v[108:111], v79 offset:912
	ds_read_b128 v[124:127], v79 offset:976
	s_waitcnt lgkmcnt(11)
	s_waitcnt lgkmcnt(10)
	v_pk_fma_f32 v[140:141], v[60:61], v[112:113], v[140:141] op_sel_hi:[1,0,1]
	v_pk_fma_f32 v[142:143], v[60:61], v[128:129], v[142:143] op_sel_hi:[1,0,1]
	v_pk_fma_f32 v[140:141], v[12:13], v[112:113], v[140:141] op_sel:[0,1,0]
	v_pk_fma_f32 v[142:143], v[12:13], v[128:129], v[142:143] op_sel:[0,1,0]
	v_pk_fma_f32 v[140:141], v[62:63], v[114:115], v[140:141] op_sel_hi:[1,0,1]
	v_pk_fma_f32 v[142:143], v[62:63], v[130:131], v[142:143] op_sel_hi:[1,0,1]
	v_pk_fma_f32 v[140:141], v[14:15], v[114:115], v[140:141] op_sel:[0,1,0]
	v_pk_fma_f32 v[142:143], v[14:15], v[130:131], v[142:143] op_sel:[0,1,0]
	ds_read_b128 v[112:115], v79 offset:928
	ds_read_b128 v[128:131], v79 offset:992
	s_waitcnt lgkmcnt(11)
	s_waitcnt lgkmcnt(10)
	v_pk_fma_f32 v[140:141], v[64:65], v[116:117], v[140:141] op_sel_hi:[1,0,1]
	v_pk_fma_f32 v[142:143], v[64:65], v[132:133], v[142:143] op_sel_hi:[1,0,1]
	v_pk_fma_f32 v[140:141], v[8:9], v[116:117], v[140:141] op_sel:[0,1,0]
	v_pk_fma_f32 v[142:143], v[8:9], v[132:133], v[142:143] op_sel:[0,1,0]
	v_pk_fma_f32 v[140:141], v[66:67], v[118:119], v[140:141] op_sel_hi:[1,0,1]
	v_pk_fma_f32 v[142:143], v[66:67], v[134:135], v[142:143] op_sel_hi:[1,0,1]
	v_pk_fma_f32 v[140:141], v[10:11], v[118:119], v[140:141] op_sel:[0,1,0]
	v_pk_fma_f32 v[142:143], v[10:11], v[134:135], v[142:143] op_sel:[0,1,0]
	ds_read_b128 v[116:119], v79 offset:944
	ds_read_b128 v[132:135], v79 offset:1008
	s_waitcnt lgkmcnt(9)
	s_waitcnt lgkmcnt(8)
	v_pk_mul_f32 v[136:137], v[20:21], v[104:105] op_sel:[0,1]
	v_pk_mul_f32 v[138:139], v[20:21], v[120:121] op_sel:[0,1]
	v_pk_mul_f32 v[76:77], v[74:75], v[70:71] op_sel:[0,1]
	v_pk_fma_f32 v[136:137], v[52:53], v[104:105], v[136:137] op_sel_hi:[1,0,1]
	v_pk_fma_f32 v[138:139], v[52:53], v[120:121], v[138:139] op_sel_hi:[1,0,1]
	v_pk_fma_f32 v[146:147], v[68:69], v[70:71], v[76:77] op_sel_hi:[1,0,1] neg_lo:[0,0,1]
	v_pk_fma_f32 v[136:137], v[54:55], v[106:107], v[136:137] op_sel_hi:[1,0,1]
	v_pk_fma_f32 v[138:139], v[54:55], v[122:123], v[138:139] op_sel_hi:[1,0,1]
	v_pk_add_f32 v[42:43], v[146:147], v[140:141]
	v_pk_fma_f32 v[136:137], v[22:23], v[106:107], v[136:137] op_sel:[0,1,0]
	v_pk_fma_f32 v[138:139], v[22:23], v[122:123], v[138:139] op_sel:[0,1,0]
	v_cvt_pk_bf16_f32 v150, v42, v43
	ds_write_b16 v103, v150 offset:3264
	ds_write_b16_d16_hi v103, v150 offset:3392
	ds_read_b128 v[104:107], v79 offset:1024
	ds_read_b128 v[120:123], v79 offset:1088
	s_waitcnt lgkmcnt(9)
	s_waitcnt lgkmcnt(8)
	v_pk_fma_f32 v[136:137], v[56:57], v[108:109], v[136:137] op_sel_hi:[1,0,1]
	v_pk_fma_f32 v[138:139], v[56:57], v[124:125], v[138:139] op_sel_hi:[1,0,1]
	v_pk_mul_f32 v[76:77], v[74:75], v[42:43] op_sel:[0,1]
	v_pk_fma_f32 v[136:137], v[16:17], v[108:109], v[136:137] op_sel:[0,1,0]
	v_pk_fma_f32 v[138:139], v[16:17], v[124:125], v[138:139] op_sel:[0,1,0]
	v_pk_fma_f32 v[146:147], v[68:69], v[42:43], v[76:77] op_sel_hi:[1,0,1] neg_lo:[0,0,1]
	v_pk_fma_f32 v[136:137], v[58:59], v[110:111], v[136:137] op_sel_hi:[1,0,1]
	v_pk_fma_f32 v[138:139], v[58:59], v[126:127], v[138:139] op_sel_hi:[1,0,1]
	v_pk_add_f32 v[70:71], v[146:147], v[142:143]
	v_pk_fma_f32 v[136:137], v[18:19], v[110:111], v[136:137] op_sel:[0,1,0]
	v_pk_fma_f32 v[138:139], v[18:19], v[126:127], v[138:139] op_sel:[0,1,0]
	v_cvt_pk_bf16_f32 v150, v70, v71
	ds_write_b16 v103, v150 offset:3536
	ds_write_b16_d16_hi v103, v150 offset:3664
	ds_read_b128 v[108:111], v79 offset:1040
	ds_read_b128 v[124:127], v79 offset:1104
	s_waitcnt lgkmcnt(11)
	s_waitcnt lgkmcnt(10)
	v_pk_fma_f32 v[136:137], v[60:61], v[112:113], v[136:137] op_sel_hi:[1,0,1]
	v_pk_fma_f32 v[138:139], v[60:61], v[128:129], v[138:139] op_sel_hi:[1,0,1]
	v_pk_fma_f32 v[136:137], v[12:13], v[112:113], v[136:137] op_sel:[0,1,0]
	v_pk_fma_f32 v[138:139], v[12:13], v[128:129], v[138:139] op_sel:[0,1,0]
	v_pk_fma_f32 v[136:137], v[62:63], v[114:115], v[136:137] op_sel_hi:[1,0,1]
	v_pk_fma_f32 v[138:139], v[62:63], v[130:131], v[138:139] op_sel_hi:[1,0,1]
	v_pk_fma_f32 v[136:137], v[14:15], v[114:115], v[136:137] op_sel:[0,1,0]
	v_pk_fma_f32 v[138:139], v[14:15], v[130:131], v[138:139] op_sel:[0,1,0]
	ds_read_b128 v[112:115], v79 offset:1056
	ds_read_b128 v[128:131], v79 offset:1120
	s_waitcnt lgkmcnt(11)
	s_waitcnt lgkmcnt(10)
	v_pk_fma_f32 v[136:137], v[64:65], v[116:117], v[136:137] op_sel_hi:[1,0,1]
	v_pk_fma_f32 v[138:139], v[64:65], v[132:133], v[138:139] op_sel_hi:[1,0,1]
	v_pk_fma_f32 v[136:137], v[8:9], v[116:117], v[136:137] op_sel:[0,1,0]
	v_pk_fma_f32 v[138:139], v[8:9], v[132:133], v[138:139] op_sel:[0,1,0]
	v_pk_fma_f32 v[136:137], v[66:67], v[118:119], v[136:137] op_sel_hi:[1,0,1]
	v_pk_fma_f32 v[138:139], v[66:67], v[134:135], v[138:139] op_sel_hi:[1,0,1]
	v_pk_fma_f32 v[136:137], v[10:11], v[118:119], v[136:137] op_sel:[0,1,0]
	v_pk_fma_f32 v[138:139], v[10:11], v[134:135], v[138:139] op_sel:[0,1,0]
	ds_read_b128 v[116:119], v79 offset:1072
	ds_read_b128 v[132:135], v79 offset:1136
	s_waitcnt lgkmcnt(9)
; __device__ __forceinline__ bf f2bf(float f) { return (bf)(pk2(f, 0.f) & 0xFFFFu); }
; __device__ __forceinline__ void s5_pass2(const Params& p, int layer, int task, char* sm) {
;     ...
;       for (int l = 0; l < 32; l++) {
;         S5_STEP(sU + l * 16)
;         sS[l * 136 + lane] = f2bf(sr); sS[l * 136 + 64 + lane] = f2bf(si);
;       }
	s_waitcnt lgkmcnt(8)
	v_pk_mul_f32 v[140:141], v[20:21], v[104:105] op_sel:[0,1]
	v_pk_mul_f32 v[142:143], v[20:21], v[120:121] op_sel:[0,1]
	v_pk_mul_f32 v[76:77], v[74:75], v[70:71] op_sel:[0,1]
	v_pk_fma_f32 v[140:141], v[52:53], v[104:105], v[140:141] op_sel_hi:[1,0,1]
	v_pk_fma_f32 v[142:143], v[52:53], v[120:121], v[142:143] op_sel_hi:[1,0,1]
	v_pk_fma_f32 v[146:147], v[68:69], v[70:71], v[76:77] op_sel_hi:[1,0,1] neg_lo:[0,0,1]
	v_pk_fma_f32 v[140:141], v[54:55], v[106:107], v[140:141] op_sel_hi:[1,0,1]
	v_pk_fma_f32 v[142:143], v[54:55], v[122:123], v[142:143] op_sel_hi:[1,0,1]
	v_pk_add_f32 v[42:43], v[146:147], v[136:137]
	v_pk_fma_f32 v[140:141], v[22:23], v[106:107], v[140:141] op_sel:[0,1,0]
	v_pk_fma_f32 v[142:143], v[22:23], v[122:123], v[142:143] op_sel:[0,1,0]
	v_cvt_pk_bf16_f32 v150, v42, v43
	ds_write_b16 v103, v150 offset:3808
	ds_write_b16_d16_hi v103, v150 offset:3936
	ds_read_b128 v[104:107], v79 offset:1152
	ds_read_b128 v[120:123], v79 offset:1216
	s_waitcnt lgkmcnt(9)
	s_waitcnt lgkmcnt(8)
	v_pk_fma_f32 v[140:141], v[56:57], v[108:109], v[140:141] op_sel_hi:[1,0,1]
	v_pk_fma_f32 v[142:143], v[56:57], v[124:125], v[142:143] op_sel_hi:[1,0,1]
	v_pk_mul_f32 v[76:77], v[74:75], v[42:43] op_sel:[0,1]
	v_pk_fma_f32 v[140:141], v[16:17], v[108:109], v[140:141] op_sel:[0,1,0]
	v_pk_fma_f32 v[142:143], v[16:17], v[124:125], v[142:143] op_sel:[0,1,0]
	v_pk_fma_f32 v[146:147], v[68:69], v[42:43], v[76:77] op_sel_hi:[1,0,1] neg_lo:[0,0,1]
	v_pk_fma_f32 v[140:141], v[58:59], v[110:111], v[140:141] op_sel_hi:[1,0,1]
	v_pk_fma_f32 v[142:143], v[58:59], v[126:127], v[142:143] op_sel_hi:[1,0,1]
	v_pk_add_f32 v[70:71], v[146:147], v[138:139]
	v_pk_fma_f32 v[140:141], v[18:19], v[110:111], v[140:141] op_sel:[0,1,0]
	v_pk_fma_f32 v[142:143], v[18:19], v[126:127], v[142:143] op_sel:[0,1,0]
	v_cvt_pk_bf16_f32 v150, v70, v71
	ds_write_b16 v103, v150 offset:4080
	ds_write_b16_d16_hi v103, v150 offset:4208
	ds_read_b128 v[108:111], v79 offset:1168
	ds_read_b128 v[124:127], v79 offset:1232
	s_waitcnt lgkmcnt(11)
	s_waitcnt lgkmcnt(10)
	v_pk_fma_f32 v[140:141], v[60:61], v[112:113], v[140:141] op_sel_hi:[1,0,1]
	v_pk_fma_f32 v[142:143], v[60:61], v[128:129], v[142:143] op_sel_hi:[1,0,1]
	v_pk_fma_f32 v[140:141], v[12:13], v[112:113], v[140:141] op_sel:[0,1,0]
	v_pk_fma_f32 v[142:143], v[12:13], v[128:129], v[142:143] op_sel:[0,1,0]
	v_pk_fma_f32 v[140:141], v[62:63], v[114:115], v[140:141] op_sel_hi:[1,0,1]
	v_pk_fma_f32 v[142:143], v[62:63], v[130:131], v[142:143] op_sel_hi:[1,0,1]
	v_pk_fma_f32 v[140:141], v[14:15], v[114:115], v[140:141] op_sel:[0,1,0]
	v_pk_fma_f32 v[142:143], v[14:15], v[130:131], v[142:143] op_sel:[0,1,0]
	ds_read_b128 v[112:115], v79 offset:1184
	ds_read_b128 v[128:131], v79 offset:1248
	s_waitcnt lgkmcnt(11)
	s_waitcnt lgkmcnt(10)
	v_pk_fma_f32 v[140:141], v[64:65], v[116:117], v[140:141] op_sel_hi:[1,0,1]
	v_pk_fma_f32 v[142:143], v[64:65], v[132:133], v[142:143] op_sel_hi:[1,0,1]
	v_pk_fma_f32 v[140:141], v[8:9], v[116:117], v[140:141] op_sel:[0,1,0]
	v_pk_fma_f32 v[142:143], v[8:9], v[132:133], v[142:143] op_sel:[0,1,0]
	v_pk_fma_f32 v[140:141], v[66:67], v[118:119], v[140:141] op_sel_hi:[1,0,1]
	v_pk_fma_f32 v[142:143], v[66:67], v[134:135], v[142:143] op_sel_hi:[1,0,1]
	v_pk_fma_f32 v[140:141], v[10:11], v[118:119], v[140:141] op_sel:[0,1,0]
	v_pk_fma_f32 v[142:143], v[10:11], v[134:135], v[142:143] op_sel:[0,1,0]
	ds_read_b128 v[116:119], v79 offset:1200
	ds_read_b128 v[132:135], v79 offset:1264
	s_waitcnt lgkmcnt(9)
	s_waitcnt lgkmcnt(8)
	v_pk_mul_f32 v[136:137], v[20:21], v[104:105] op_sel:[0,1]
	v_pk_mul_f32 v[138:139], v[20:21], v[120:121] op_sel:[0,1]
	v_pk_mul_f32 v[76:77], v[74:75], v[70:71] op_sel:[0,1]
	v_pk_fma_f32 v[136:137], v[52:53], v[104:105], v[136:137] op_sel_hi:[1,0,1]
	v_pk_fma_f32 v[138:139], v[52:53], v[120:121], v[138:139] op_sel_hi:[1,0,1]
	v_pk_fma_f32 v[146:147], v[68:69], v[70:71], v[76:77] op_sel_hi:[1,0,1] neg_lo:[0,0,1]
	v_pk_fma_f32 v[136:137], v[54:55], v[106:107], v[136:137] op_sel_hi:[1,0,1]
	v_pk_fma_f32 v[138:139], v[54:55], v[122:123], v[138:139] op_sel_hi:[1,0,1]
	v_pk_add_f32 v[42:43], v[146:147], v[140:141]
	v_pk_fma_f32 v[136:137], v[22:23], v[106:107], v[136:137] op_sel:[0,1,0]
	v_pk_fma_f32 v[138:139], v[22:23], v[122:123], v[138:139] op_sel:[0,1,0]
	v_cvt_pk_bf16_f32 v150, v42, v43
	ds_write_b16 v103, v150 offset:4352
	ds_write_b16_d16_hi v103, v150 offset:4480
	ds_read_b128 v[104:107], v79 offset:1280
	ds_read_b128 v[120:123], v79 offset:1344
	s_waitcnt lgkmcnt(9)
	s_waitcnt lgkmcnt(8)
	v_pk_fma_f32 v[136:137], v[56:57], v[108:109], v[136:137] op_sel_hi:[1,0,1]
	v_pk_fma_f32 v[138:139], v[56:57], v[124:125], v[138:139] op_sel_hi:[1,0,1]
	v_pk_mul_f32 v[76:77], v[74:75], v[42:43] op_sel:[0,1]
	v_pk_fma_f32 v[136:137], v[16:17], v[108:109], v[136:137] op_sel:[0,1,0]
	v_pk_fma_f32 v[138:139], v[16:17], v[124:125], v[138:139] op_sel:[0,1,0]
	v_pk_fma_f32 v[146:147], v[68:69], v[42:43], v[76:77] op_sel_hi:[1,0,1] neg_lo:[0,0,1]
	v_pk_fma_f32 v[136:137], v[58:59], v[110:111], v[136:137] op_sel_hi:[1,0,1]
	v_pk_fma_f32 v[138:139], v[58:59], v[126:127], v[138:139] op_sel_hi:[1,0,1]
	v_pk_add_f32 v[70:71], v[146:147], v[142:143]
	v_pk_fma_f32 v[136:137], v[18:19], v[110:111], v[136:137] op_sel:[0,1,0]
	v_pk_fma_f32 v[138:139], v[18:19], v[126:127], v[138:139] op_sel:[0,1,0]
	v_cvt_pk_bf16_f32 v150, v70, v71
	ds_write_b16 v103, v150 offset:4624
	ds_write_b16_d16_hi v103, v150 offset:4752
	ds_read_b128 v[108:111], v79 offset:1296
	ds_read_b128 v[124:127], v79 offset:1360
	s_waitcnt lgkmcnt(11)
	s_waitcnt lgkmcnt(10)
; __device__ __forceinline__ bf f2bf(float f) { return (bf)(pk2(f, 0.f) & 0xFFFFu); }
; __device__ __forceinline__ void s5_pass2(const Params& p, int layer, int task, char* sm) {
;     ...
;       for (int l = 0; l < 32; l++) {
;         S5_STEP(sU + l * 16)
;         sS[l * 136 + lane] = f2bf(sr); sS[l * 136 + 64 + lane] = f2bf(si);
;       }
	v_pk_fma_f32 v[136:137], v[60:61], v[112:113], v[136:137] op_sel_hi:[1,0,1]
	v_pk_fma_f32 v[138:139], v[60:61], v[128:129], v[138:139] op_sel_hi:[1,0,1]
	v_pk_fma_f32 v[136:137], v[12:13], v[112:113], v[136:137] op_sel:[0,1,0]
	v_pk_fma_f32 v[138:139], v[12:13], v[128:129], v[138:139] op_sel:[0,1,0]
	v_pk_fma_f32 v[136:137], v[62:63], v[114:115], v[136:137] op_sel_hi:[1,0,1]
	v_pk_fma_f32 v[138:139], v[62:63], v[130:131], v[138:139] op_sel_hi:[1,0,1]
	v_pk_fma_f32 v[136:137], v[14:15], v[114:115], v[136:137] op_sel:[0,1,0]
	v_pk_fma_f32 v[138:139], v[14:15], v[130:131], v[138:139] op_sel:[0,1,0]
	ds_read_b128 v[112:115], v79 offset:1312
	ds_read_b128 v[128:131], v79 offset:1376
	s_waitcnt lgkmcnt(11)
	s_waitcnt lgkmcnt(10)
	v_pk_fma_f32 v[136:137], v[64:65], v[116:117], v[136:137] op_sel_hi:[1,0,1]
	v_pk_fma_f32 v[138:139], v[64:65], v[132:133], v[138:139] op_sel_hi:[1,0,1]
	v_pk_fma_f32 v[136:137], v[8:9], v[116:117], v[136:137] op_sel:[0,1,0]
	v_pk_fma_f32 v[138:139], v[8:9], v[132:133], v[138:139] op_sel:[0,1,0]
	v_pk_fma_f32 v[136:137], v[66:67], v[118:119], v[136:137] op_sel_hi:[1,0,1]
	v_pk_fma_f32 v[138:139], v[66:67], v[134:135], v[138:139] op_sel_hi:[1,0,1]
	v_pk_fma_f32 v[136:137], v[10:11], v[118:119], v[136:137] op_sel:[0,1,0]
	v_pk_fma_f32 v[138:139], v[10:11], v[134:135], v[138:139] op_sel:[0,1,0]
	ds_read_b128 v[116:119], v79 offset:1328
	ds_read_b128 v[132:135], v79 offset:1392
	s_waitcnt lgkmcnt(9)
	s_waitcnt lgkmcnt(8)
	v_pk_mul_f32 v[140:141], v[20:21], v[104:105] op_sel:[0,1]
	v_pk_mul_f32 v[142:143], v[20:21], v[120:121] op_sel:[0,1]
	v_pk_mul_f32 v[76:77], v[74:75], v[70:71] op_sel:[0,1]
	v_pk_fma_f32 v[140:141], v[52:53], v[104:105], v[140:141] op_sel_hi:[1,0,1]
	v_pk_fma_f32 v[142:143], v[52:53], v[120:121], v[142:143] op_sel_hi:[1,0,1]
	v_pk_fma_f32 v[146:147], v[68:69], v[70:71], v[76:77] op_sel_hi:[1,0,1] neg_lo:[0,0,1]
	v_pk_fma_f32 v[140:141], v[54:55], v[106:107], v[140:141] op_sel_hi:[1,0,1]
	v_pk_fma_f32 v[142:143], v[54:55], v[122:123], v[142:143] op_sel_hi:[1,0,1]
	v_pk_add_f32 v[42:43], v[146:147], v[136:137]
	v_pk_fma_f32 v[140:141], v[22:23], v[106:107], v[140:141] op_sel:[0,1,0]
	v_pk_fma_f32 v[142:143], v[22:23], v[122:123], v[142:143] op_sel:[0,1,0]
	v_cvt_pk_bf16_f32 v150, v42, v43
	ds_write_b16 v103, v150 offset:4896
	ds_write_b16_d16_hi v103, v150 offset:5024
	ds_read_b128 v[104:107], v79 offset:1408
	ds_read_b128 v[120:123], v79 offset:1472
	s_waitcnt lgkmcnt(9)
	s_waitcnt lgkmcnt(8)
	v_pk_fma_f32 v[140:141], v[56:57], v[108:109], v[140:141] op_sel_hi:[1,0,1]
	v_pk_fma_f32 v[142:143], v[56:57], v[124:125], v[142:143] op_sel_hi:[1,0,1]
	v_pk_mul_f32 v[76:77], v[74:75], v[42:43] op_sel:[0,1]
	v_pk_fma_f32 v[140:141], v[16:17], v[108:109], v[140:141] op_sel:[0,1,0]
	v_pk_fma_f32 v[142:143], v[16:17], v[124:125], v[142:143] op_sel:[0,1,0]
	v_pk_fma_f32 v[146:147], v[68:69], v[42:43], v[76:77] op_sel_hi:[1,0,1] neg_lo:[0,0,1]
	v_pk_fma_f32 v[140:141], v[58:59], v[110:111], v[140:141] op_sel_hi:[1,0,1]
	v_pk_fma_f32 v[142:143], v[58:59], v[126:127], v[142:143] op_sel_hi:[1,0,1]
	v_pk_add_f32 v[70:71], v[146:147], v[138:139]
	v_pk_fma_f32 v[140:141], v[18:19], v[110:111], v[140:141] op_sel:[0,1,0]
	v_pk_fma_f32 v[142:143], v[18:19], v[126:127], v[142:143] op_sel:[0,1,0]
	v_cvt_pk_bf16_f32 v150, v70, v71
	ds_write_b16 v103, v150 offset:5168
	ds_write_b16_d16_hi v103, v150 offset:5296
	ds_read_b128 v[108:111], v79 offset:1424
	ds_read_b128 v[124:127], v79 offset:1488
	s_waitcnt lgkmcnt(11)
	s_waitcnt lgkmcnt(10)
	v_pk_fma_f32 v[140:141], v[60:61], v[112:113], v[140:141] op_sel_hi:[1,0,1]
	v_pk_fma_f32 v[142:143], v[60:61], v[128:129], v[142:143] op_sel_hi:[1,0,1]
	v_pk_fma_f32 v[140:141], v[12:13], v[112:113], v[140:141] op_sel:[0,1,0]
	v_pk_fma_f32 v[142:143], v[12:13], v[128:129], v[142:143] op_sel:[0,1,0]
	v_pk_fma_f32 v[140:141], v[62:63], v[114:115], v[140:141] op_sel_hi:[1,0,1]
	v_pk_fma_f32 v[142:143], v[62:63], v[130:131], v[142:143] op_sel_hi:[1,0,1]
	v_pk_fma_f32 v[140:141], v[14:15], v[114:115], v[140:141] op_sel:[0,1,0]
	v_pk_fma_f32 v[142:143], v[14:15], v[130:131], v[142:143] op_sel:[0,1,0]
	ds_read_b128 v[112:115], v79 offset:1440
	ds_read_b128 v[128:131], v79 offset:1504
	s_waitcnt lgkmcnt(11)
	s_waitcnt lgkmcnt(10)
	v_pk_fma_f32 v[140:141], v[64:65], v[116:117], v[140:141] op_sel_hi:[1,0,1]
	v_pk_fma_f32 v[142:143], v[64:65], v[132:133], v[142:143] op_sel_hi:[1,0,1]
	v_pk_fma_f32 v[140:141], v[8:9], v[116:117], v[140:141] op_sel:[0,1,0]
	v_pk_fma_f32 v[142:143], v[8:9], v[132:133], v[142:143] op_sel:[0,1,0]
	v_pk_fma_f32 v[140:141], v[66:67], v[118:119], v[140:141] op_sel_hi:[1,0,1]
	v_pk_fma_f32 v[142:143], v[66:67], v[134:135], v[142:143] op_sel_hi:[1,0,1]
	v_pk_fma_f32 v[140:141], v[10:11], v[118:119], v[140:141] op_sel:[0,1,0]
	v_pk_fma_f32 v[142:143], v[10:11], v[134:135], v[142:143] op_sel:[0,1,0]
	ds_read_b128 v[116:119], v79 offset:1456
	ds_read_b128 v[132:135], v79 offset:1520
	s_waitcnt lgkmcnt(9)
	s_waitcnt lgkmcnt(8)
	v_pk_mul_f32 v[136:137], v[20:21], v[104:105] op_sel:[0,1]
	v_pk_mul_f32 v[138:139], v[20:21], v[120:121] op_sel:[0,1]
	v_pk_mul_f32 v[76:77], v[74:75], v[70:71] op_sel:[0,1]
	v_pk_fma_f32 v[136:137], v[52:53], v[104:105], v[136:137] op_sel_hi:[1,0,1]
	v_pk_fma_f32 v[138:139], v[52:53], v[120:121], v[138:139] op_sel_hi:[1,0,1]
	v_pk_fma_f32 v[146:147], v[68:69], v[70:71], v[76:77] op_sel_hi:[1,0,1] neg_lo:[0,0,1]
	v_pk_fma_f32 v[136:137], v[54:55], v[106:107], v[136:137] op_sel_hi:[1,0,1]
	v_pk_fma_f32 v[138:139], v[54:55], v[122:123], v[138:139] op_sel_hi:[1,0,1]
	v_pk_add_f32 v[42:43], v[146:147], v[140:141]
	v_pk_fma_f32 v[136:137], v[22:23], v[106:107], v[136:137] op_sel:[0,1,0]
	v_pk_fma_f32 v[138:139], v[22:23], v[122:123], v[138:139] op_sel:[0,1,0]
	v_cvt_pk_bf16_f32 v150, v42, v43
	ds_write_b16 v103, v150 offset:5440
	ds_write_b16_d16_hi v103, v150 offset:5568
	ds_read_b128 v[104:107], v79 offset:1536
	ds_read_b128 v[120:123], v79 offset:1600
	s_waitcnt lgkmcnt(9)
; __device__ __forceinline__ bf f2bf(float f) { return (bf)(pk2(f, 0.f) & 0xFFFFu); }
; __device__ __forceinline__ void s5_pass2(const Params& p, int layer, int task, char* sm) {
;     ...
;       for (int l = 0; l < 32; l++) {
;         S5_STEP(sU + l * 16)
;         sS[l * 136 + lane] = f2bf(sr); sS[l * 136 + 64 + lane] = f2bf(si);
;       }
	s_waitcnt lgkmcnt(8)
	v_pk_fma_f32 v[136:137], v[56:57], v[108:109], v[136:137] op_sel_hi:[1,0,1]
	v_pk_fma_f32 v[138:139], v[56:57], v[124:125], v[138:139] op_sel_hi:[1,0,1]
	v_pk_mul_f32 v[76:77], v[74:75], v[42:43] op_sel:[0,1]
	v_pk_fma_f32 v[136:137], v[16:17], v[108:109], v[136:137] op_sel:[0,1,0]
	v_pk_fma_f32 v[138:139], v[16:17], v[124:125], v[138:139] op_sel:[0,1,0]
	v_pk_fma_f32 v[146:147], v[68:69], v[42:43], v[76:77] op_sel_hi:[1,0,1] neg_lo:[0,0,1]
	v_pk_fma_f32 v[136:137], v[58:59], v[110:111], v[136:137] op_sel_hi:[1,0,1]
	v_pk_fma_f32 v[138:139], v[58:59], v[126:127], v[138:139] op_sel_hi:[1,0,1]
	v_pk_add_f32 v[70:71], v[146:147], v[142:143]
	v_pk_fma_f32 v[136:137], v[18:19], v[110:111], v[136:137] op_sel:[0,1,0]
	v_pk_fma_f32 v[138:139], v[18:19], v[126:127], v[138:139] op_sel:[0,1,0]
	v_cvt_pk_bf16_f32 v150, v70, v71
	ds_write_b16 v103, v150 offset:5712
	ds_write_b16_d16_hi v103, v150 offset:5840
	ds_read_b128 v[108:111], v79 offset:1552
	ds_read_b128 v[124:127], v79 offset:1616
	s_waitcnt lgkmcnt(11)
	s_waitcnt lgkmcnt(10)
	v_pk_fma_f32 v[136:137], v[60:61], v[112:113], v[136:137] op_sel_hi:[1,0,1]
	v_pk_fma_f32 v[138:139], v[60:61], v[128:129], v[138:139] op_sel_hi:[1,0,1]
	v_pk_fma_f32 v[136:137], v[12:13], v[112:113], v[136:137] op_sel:[0,1,0]
	v_pk_fma_f32 v[138:139], v[12:13], v[128:129], v[138:139] op_sel:[0,1,0]
	v_pk_fma_f32 v[136:137], v[62:63], v[114:115], v[136:137] op_sel_hi:[1,0,1]
	v_pk_fma_f32 v[138:139], v[62:63], v[130:131], v[138:139] op_sel_hi:[1,0,1]
	v_pk_fma_f32 v[136:137], v[14:15], v[114:115], v[136:137] op_sel:[0,1,0]
	v_pk_fma_f32 v[138:139], v[14:15], v[130:131], v[138:139] op_sel:[0,1,0]
	ds_read_b128 v[112:115], v79 offset:1568
	ds_read_b128 v[128:131], v79 offset:1632
	s_waitcnt lgkmcnt(11)
	s_waitcnt lgkmcnt(10)
	v_pk_fma_f32 v[136:137], v[64:65], v[116:117], v[136:137] op_sel_hi:[1,0,1]
	v_pk_fma_f32 v[138:139], v[64:65], v[132:133], v[138:139] op_sel_hi:[1,0,1]
	v_pk_fma_f32 v[136:137], v[8:9], v[116:117], v[136:137] op_sel:[0,1,0]
	v_pk_fma_f32 v[138:139], v[8:9], v[132:133], v[138:139] op_sel:[0,1,0]
	v_pk_fma_f32 v[136:137], v[66:67], v[118:119], v[136:137] op_sel_hi:[1,0,1]
	v_pk_fma_f32 v[138:139], v[66:67], v[134:135], v[138:139] op_sel_hi:[1,0,1]
	v_pk_fma_f32 v[136:137], v[10:11], v[118:119], v[136:137] op_sel:[0,1,0]
	v_pk_fma_f32 v[138:139], v[10:11], v[134:135], v[138:139] op_sel:[0,1,0]
	ds_read_b128 v[116:119], v79 offset:1584
	ds_read_b128 v[132:135], v79 offset:1648
	s_waitcnt lgkmcnt(9)
	s_waitcnt lgkmcnt(8)
	v_pk_mul_f32 v[140:141], v[20:21], v[104:105] op_sel:[0,1]
	v_pk_mul_f32 v[142:143], v[20:21], v[120:121] op_sel:[0,1]
	v_pk_mul_f32 v[76:77], v[74:75], v[70:71] op_sel:[0,1]
	v_pk_fma_f32 v[140:141], v[52:53], v[104:105], v[140:141] op_sel_hi:[1,0,1]
	v_pk_fma_f32 v[142:143], v[52:53], v[120:121], v[142:143] op_sel_hi:[1,0,1]
	v_pk_fma_f32 v[146:147], v[68:69], v[70:71], v[76:77] op_sel_hi:[1,0,1] neg_lo:[0,0,1]
	v_pk_fma_f32 v[140:141], v[54:55], v[106:107], v[140:141] op_sel_hi:[1,0,1]
	v_pk_fma_f32 v[142:143], v[54:55], v[122:123], v[142:143] op_sel_hi:[1,0,1]
	v_pk_add_f32 v[42:43], v[146:147], v[136:137]
	v_pk_fma_f32 v[140:141], v[22:23], v[106:107], v[140:141] op_sel:[0,1,0]
	v_pk_fma_f32 v[142:143], v[22:23], v[122:123], v[142:143] op_sel:[0,1,0]
	v_cvt_pk_bf16_f32 v150, v42, v43
	ds_write_b16 v103, v150 offset:5984
	ds_write_b16_d16_hi v103, v150 offset:6112
	ds_read_b128 v[104:107], v79 offset:1664
	ds_read_b128 v[120:123], v79 offset:1728
	s_waitcnt lgkmcnt(9)
	s_waitcnt lgkmcnt(8)
	v_pk_fma_f32 v[140:141], v[56:57], v[108:109], v[140:141] op_sel_hi:[1,0,1]
	v_pk_fma_f32 v[142:143], v[56:57], v[124:125], v[142:143] op_sel_hi:[1,0,1]
	v_pk_mul_f32 v[76:77], v[74:75], v[42:43] op_sel:[0,1]
	v_pk_fma_f32 v[140:141], v[16:17], v[108:109], v[140:141] op_sel:[0,1,0]
	v_pk_fma_f32 v[142:143], v[16:17], v[124:125], v[142:143] op_sel:[0,1,0]
	v_pk_fma_f32 v[146:147], v[68:69], v[42:43], v[76:77] op_sel_hi:[1,0,1] neg_lo:[0,0,1]
	v_pk_fma_f32 v[140:141], v[58:59], v[110:111], v[140:141] op_sel_hi:[1,0,1]
	v_pk_fma_f32 v[142:143], v[58:59], v[126:127], v[142:143] op_sel_hi:[1,0,1]
	v_pk_add_f32 v[70:71], v[146:147], v[138:139]
	v_pk_fma_f32 v[140:141], v[18:19], v[110:111], v[140:141] op_sel:[0,1,0]
	v_pk_fma_f32 v[142:143], v[18:19], v[126:127], v[142:143] op_sel:[0,1,0]
	v_cvt_pk_bf16_f32 v150, v70, v71
	ds_write_b16 v103, v150 offset:6256
	ds_write_b16_d16_hi v103, v150 offset:6384
	ds_read_b128 v[108:111], v79 offset:1680
	ds_read_b128 v[124:127], v79 offset:1744
	s_waitcnt lgkmcnt(11)
	s_waitcnt lgkmcnt(10)
	v_pk_fma_f32 v[140:141], v[60:61], v[112:113], v[140:141] op_sel_hi:[1,0,1]
	v_pk_fma_f32 v[142:143], v[60:61], v[128:129], v[142:143] op_sel_hi:[1,0,1]
	v_pk_fma_f32 v[140:141], v[12:13], v[112:113], v[140:141] op_sel:[0,1,0]
	v_pk_fma_f32 v[142:143], v[12:13], v[128:129], v[142:143] op_sel:[0,1,0]
	v_pk_fma_f32 v[140:141], v[62:63], v[114:115], v[140:141] op_sel_hi:[1,0,1]
	v_pk_fma_f32 v[142:143], v[62:63], v[130:131], v[142:143] op_sel_hi:[1,0,1]
	v_pk_fma_f32 v[140:141], v[14:15], v[114:115], v[140:141] op_sel:[0,1,0]
	v_pk_fma_f32 v[142:143], v[14:15], v[130:131], v[142:143] op_sel:[0,1,0]
	ds_read_b128 v[112:115], v79 offset:1696
	ds_read_b128 v[128:131], v79 offset:1760
	s_waitcnt lgkmcnt(11)
	s_waitcnt lgkmcnt(10)
; __device__ __forceinline__ bf f2bf(float f) { return (bf)(pk2(f, 0.f) & 0xFFFFu); }
; __device__ __forceinline__ void s5_pass2(const Params& p, int layer, int task, char* sm) {
;     ...
;       for (int l = 0; l < 32; l++) {
;         S5_STEP(sU + l * 16)
;         sS[l * 136 + lane] = f2bf(sr); sS[l * 136 + 64 + lane] = f2bf(si);
;       }
	v_pk_fma_f32 v[140:141], v[64:65], v[116:117], v[140:141] op_sel_hi:[1,0,1]
	v_pk_fma_f32 v[142:143], v[64:65], v[132:133], v[142:143] op_sel_hi:[1,0,1]
	v_pk_fma_f32 v[140:141], v[8:9], v[116:117], v[140:141] op_sel:[0,1,0]
	v_pk_fma_f32 v[142:143], v[8:9], v[132:133], v[142:143] op_sel:[0,1,0]
	v_pk_fma_f32 v[140:141], v[66:67], v[118:119], v[140:141] op_sel_hi:[1,0,1]
	v_pk_fma_f32 v[142:143], v[66:67], v[134:135], v[142:143] op_sel_hi:[1,0,1]
	v_pk_fma_f32 v[140:141], v[10:11], v[118:119], v[140:141] op_sel:[0,1,0]
	v_pk_fma_f32 v[142:143], v[10:11], v[134:135], v[142:143] op_sel:[0,1,0]
	ds_read_b128 v[116:119], v79 offset:1712
	ds_read_b128 v[132:135], v79 offset:1776
	s_waitcnt lgkmcnt(9)
	s_waitcnt lgkmcnt(8)
	v_pk_mul_f32 v[136:137], v[20:21], v[104:105] op_sel:[0,1]
	v_pk_mul_f32 v[138:139], v[20:21], v[120:121] op_sel:[0,1]
	v_pk_mul_f32 v[76:77], v[74:75], v[70:71] op_sel:[0,1]
	v_pk_fma_f32 v[136:137], v[52:53], v[104:105], v[136:137] op_sel_hi:[1,0,1]
	v_pk_fma_f32 v[138:139], v[52:53], v[120:121], v[138:139] op_sel_hi:[1,0,1]
	v_pk_fma_f32 v[146:147], v[68:69], v[70:71], v[76:77] op_sel_hi:[1,0,1] neg_lo:[0,0,1]
	v_pk_fma_f32 v[136:137], v[54:55], v[106:107], v[136:137] op_sel_hi:[1,0,1]
	v_pk_fma_f32 v[138:139], v[54:55], v[122:123], v[138:139] op_sel_hi:[1,0,1]
	v_pk_add_f32 v[42:43], v[146:147], v[140:141]
	v_pk_fma_f32 v[136:137], v[22:23], v[106:107], v[136:137] op_sel:[0,1,0]
	v_pk_fma_f32 v[138:139], v[22:23], v[122:123], v[138:139] op_sel:[0,1,0]
	v_cvt_pk_bf16_f32 v150, v42, v43
	ds_write_b16 v103, v150 offset:6528
	ds_write_b16_d16_hi v103, v150 offset:6656
	ds_read_b128 v[104:107], v79 offset:1792
	ds_read_b128 v[120:123], v79 offset:1856
	s_waitcnt lgkmcnt(9)
	s_waitcnt lgkmcnt(8)
	v_pk_fma_f32 v[136:137], v[56:57], v[108:109], v[136:137] op_sel_hi:[1,0,1]
	v_pk_fma_f32 v[138:139], v[56:57], v[124:125], v[138:139] op_sel_hi:[1,0,1]
	v_pk_mul_f32 v[76:77], v[74:75], v[42:43] op_sel:[0,1]
	v_pk_fma_f32 v[136:137], v[16:17], v[108:109], v[136:137] op_sel:[0,1,0]
	v_pk_fma_f32 v[138:139], v[16:17], v[124:125], v[138:139] op_sel:[0,1,0]
	v_pk_fma_f32 v[146:147], v[68:69], v[42:43], v[76:77] op_sel_hi:[1,0,1] neg_lo:[0,0,1]
	v_pk_fma_f32 v[136:137], v[58:59], v[110:111], v[136:137] op_sel_hi:[1,0,1]
	v_pk_fma_f32 v[138:139], v[58:59], v[126:127], v[138:139] op_sel_hi:[1,0,1]
	v_pk_add_f32 v[70:71], v[146:147], v[142:143]
	v_pk_fma_f32 v[136:137], v[18:19], v[110:111], v[136:137] op_sel:[0,1,0]
	v_pk_fma_f32 v[138:139], v[18:19], v[126:127], v[138:139] op_sel:[0,1,0]
	v_cvt_pk_bf16_f32 v150, v70, v71
	ds_write_b16 v103, v150 offset:6800
	ds_write_b16_d16_hi v103, v150 offset:6928
	ds_read_b128 v[108:111], v79 offset:1808
	ds_read_b128 v[124:127], v79 offset:1872
	s_waitcnt lgkmcnt(11)
	s_waitcnt lgkmcnt(10)
	v_pk_fma_f32 v[136:137], v[60:61], v[112:113], v[136:137] op_sel_hi:[1,0,1]
	v_pk_fma_f32 v[138:139], v[60:61], v[128:129], v[138:139] op_sel_hi:[1,0,1]
	v_pk_fma_f32 v[136:137], v[12:13], v[112:113], v[136:137] op_sel:[0,1,0]
	v_pk_fma_f32 v[138:139], v[12:13], v[128:129], v[138:139] op_sel:[0,1,0]
	v_pk_fma_f32 v[136:137], v[62:63], v[114:115], v[136:137] op_sel_hi:[1,0,1]
	v_pk_fma_f32 v[138:139], v[62:63], v[130:131], v[138:139] op_sel_hi:[1,0,1]
	v_pk_fma_f32 v[136:137], v[14:15], v[114:115], v[136:137] op_sel:[0,1,0]
	v_pk_fma_f32 v[138:139], v[14:15], v[130:131], v[138:139] op_sel:[0,1,0]
	ds_read_b128 v[112:115], v79 offset:1824
	ds_read_b128 v[128:131], v79 offset:1888
	s_waitcnt lgkmcnt(11)
	s_waitcnt lgkmcnt(10)
	v_pk_fma_f32 v[136:137], v[64:65], v[116:117], v[136:137] op_sel_hi:[1,0,1]
	v_pk_fma_f32 v[138:139], v[64:65], v[132:133], v[138:139] op_sel_hi:[1,0,1]
	v_pk_fma_f32 v[136:137], v[8:9], v[116:117], v[136:137] op_sel:[0,1,0]
	v_pk_fma_f32 v[138:139], v[8:9], v[132:133], v[138:139] op_sel:[0,1,0]
	v_pk_fma_f32 v[136:137], v[66:67], v[118:119], v[136:137] op_sel_hi:[1,0,1]
	v_pk_fma_f32 v[138:139], v[66:67], v[134:135], v[138:139] op_sel_hi:[1,0,1]
	v_pk_fma_f32 v[136:137], v[10:11], v[118:119], v[136:137] op_sel:[0,1,0]
	v_pk_fma_f32 v[138:139], v[10:11], v[134:135], v[138:139] op_sel:[0,1,0]
	ds_read_b128 v[116:119], v79 offset:1840
	ds_read_b128 v[132:135], v79 offset:1904
	s_waitcnt lgkmcnt(9)
	s_waitcnt lgkmcnt(8)
	v_pk_mul_f32 v[140:141], v[20:21], v[104:105] op_sel:[0,1]
	v_pk_mul_f32 v[142:143], v[20:21], v[120:121] op_sel:[0,1]
	v_pk_mul_f32 v[76:77], v[74:75], v[70:71] op_sel:[0,1]
	v_pk_fma_f32 v[140:141], v[52:53], v[104:105], v[140:141] op_sel_hi:[1,0,1]
	v_pk_fma_f32 v[142:143], v[52:53], v[120:121], v[142:143] op_sel_hi:[1,0,1]
	v_pk_fma_f32 v[146:147], v[68:69], v[70:71], v[76:77] op_sel_hi:[1,0,1] neg_lo:[0,0,1]
	v_pk_fma_f32 v[140:141], v[54:55], v[106:107], v[140:141] op_sel_hi:[1,0,1]
	v_pk_fma_f32 v[142:143], v[54:55], v[122:123], v[142:143] op_sel_hi:[1,0,1]
	v_pk_add_f32 v[42:43], v[146:147], v[136:137]
	v_pk_fma_f32 v[140:141], v[22:23], v[106:107], v[140:141] op_sel:[0,1,0]
	v_pk_fma_f32 v[142:143], v[22:23], v[122:123], v[142:143] op_sel:[0,1,0]
	v_cvt_pk_bf16_f32 v150, v42, v43
	ds_write_b16 v103, v150 offset:7072
	ds_write_b16_d16_hi v103, v150 offset:7200
	ds_read_b128 v[104:107], v79 offset:1920
	ds_read_b128 v[120:123], v79 offset:1984
	s_waitcnt lgkmcnt(9)
	s_waitcnt lgkmcnt(8)
; __device__ __forceinline__ bf f2bf(float f) { return (bf)(pk2(f, 0.f) & 0xFFFFu); }
; __device__ __forceinline__ void s5_pass2(const Params& p, int layer, int task, char* sm) {
;     ...
;       for (int l = 0; l < 32; l++) {
;         S5_STEP(sU + l * 16)
;         sS[l * 136 + lane] = f2bf(sr); sS[l * 136 + 64 + lane] = f2bf(si);
;       }
	v_pk_fma_f32 v[140:141], v[56:57], v[108:109], v[140:141] op_sel_hi:[1,0,1]
	v_pk_fma_f32 v[142:143], v[56:57], v[124:125], v[142:143] op_sel_hi:[1,0,1]
	v_pk_mul_f32 v[76:77], v[74:75], v[42:43] op_sel:[0,1]
	v_pk_fma_f32 v[140:141], v[16:17], v[108:109], v[140:141] op_sel:[0,1,0]
	v_pk_fma_f32 v[142:143], v[16:17], v[124:125], v[142:143] op_sel:[0,1,0]
	v_pk_fma_f32 v[146:147], v[68:69], v[42:43], v[76:77] op_sel_hi:[1,0,1] neg_lo:[0,0,1]
	v_pk_fma_f32 v[140:141], v[58:59], v[110:111], v[140:141] op_sel_hi:[1,0,1]
	v_pk_fma_f32 v[142:143], v[58:59], v[126:127], v[142:143] op_sel_hi:[1,0,1]
	v_pk_add_f32 v[70:71], v[146:147], v[138:139]
	v_pk_fma_f32 v[140:141], v[18:19], v[110:111], v[140:141] op_sel:[0,1,0]
	v_pk_fma_f32 v[142:143], v[18:19], v[126:127], v[142:143] op_sel:[0,1,0]
	v_cvt_pk_bf16_f32 v150, v70, v71
	ds_write_b16 v103, v150 offset:7344
	ds_write_b16_d16_hi v103, v150 offset:7472
	ds_read_b128 v[108:111], v79 offset:1936
	ds_read_b128 v[124:127], v79 offset:2000
	s_waitcnt lgkmcnt(11)
	s_waitcnt lgkmcnt(10)
	v_pk_fma_f32 v[140:141], v[60:61], v[112:113], v[140:141] op_sel_hi:[1,0,1]
	v_pk_fma_f32 v[142:143], v[60:61], v[128:129], v[142:143] op_sel_hi:[1,0,1]
	v_pk_fma_f32 v[140:141], v[12:13], v[112:113], v[140:141] op_sel:[0,1,0]
	v_pk_fma_f32 v[142:143], v[12:13], v[128:129], v[142:143] op_sel:[0,1,0]
	v_pk_fma_f32 v[140:141], v[62:63], v[114:115], v[140:141] op_sel_hi:[1,0,1]
	v_pk_fma_f32 v[142:143], v[62:63], v[130:131], v[142:143] op_sel_hi:[1,0,1]
	v_pk_fma_f32 v[140:141], v[14:15], v[114:115], v[140:141] op_sel:[0,1,0]
	v_pk_fma_f32 v[142:143], v[14:15], v[130:131], v[142:143] op_sel:[0,1,0]
	ds_read_b128 v[112:115], v79 offset:1952
	ds_read_b128 v[128:131], v79 offset:2016
	s_waitcnt lgkmcnt(11)
	s_waitcnt lgkmcnt(10)
	v_pk_fma_f32 v[140:141], v[64:65], v[116:117], v[140:141] op_sel_hi:[1,0,1]
	v_pk_fma_f32 v[142:143], v[64:65], v[132:133], v[142:143] op_sel_hi:[1,0,1]
	v_pk_fma_f32 v[140:141], v[8:9], v[116:117], v[140:141] op_sel:[0,1,0]
	v_pk_fma_f32 v[142:143], v[8:9], v[132:133], v[142:143] op_sel:[0,1,0]
	v_pk_fma_f32 v[140:141], v[66:67], v[118:119], v[140:141] op_sel_hi:[1,0,1]
	v_pk_fma_f32 v[142:143], v[66:67], v[134:135], v[142:143] op_sel_hi:[1,0,1]
	v_pk_fma_f32 v[140:141], v[10:11], v[118:119], v[140:141] op_sel:[0,1,0]
	v_pk_fma_f32 v[142:143], v[10:11], v[134:135], v[142:143] op_sel:[0,1,0]
	ds_read_b128 v[116:119], v79 offset:1968
	ds_read_b128 v[132:135], v79 offset:2032
	s_waitcnt lgkmcnt(9)
	s_waitcnt lgkmcnt(8)
	v_pk_mul_f32 v[136:137], v[20:21], v[104:105] op_sel:[0,1]
	v_pk_mul_f32 v[138:139], v[20:21], v[120:121] op_sel:[0,1]
	v_pk_mul_f32 v[76:77], v[74:75], v[70:71] op_sel:[0,1]
	v_pk_fma_f32 v[136:137], v[52:53], v[104:105], v[136:137] op_sel_hi:[1,0,1]
	v_pk_fma_f32 v[138:139], v[52:53], v[120:121], v[138:139] op_sel_hi:[1,0,1]
	v_pk_fma_f32 v[146:147], v[68:69], v[70:71], v[76:77] op_sel_hi:[1,0,1] neg_lo:[0,0,1]
	v_pk_fma_f32 v[136:137], v[54:55], v[106:107], v[136:137] op_sel_hi:[1,0,1]
	v_pk_fma_f32 v[138:139], v[54:55], v[122:123], v[138:139] op_sel_hi:[1,0,1]
	v_pk_add_f32 v[42:43], v[146:147], v[140:141]
	v_pk_fma_f32 v[136:137], v[22:23], v[106:107], v[136:137] op_sel:[0,1,0]
	v_pk_fma_f32 v[138:139], v[22:23], v[122:123], v[138:139] op_sel:[0,1,0]
	v_cvt_pk_bf16_f32 v150, v42, v43
	ds_write_b16 v103, v150 offset:7616
	ds_write_b16_d16_hi v103, v150 offset:7744
	s_waitcnt lgkmcnt(7)
	s_waitcnt lgkmcnt(6)
	v_pk_fma_f32 v[136:137], v[56:57], v[108:109], v[136:137] op_sel_hi:[1,0,1]
	v_pk_fma_f32 v[138:139], v[56:57], v[124:125], v[138:139] op_sel_hi:[1,0,1]
	v_pk_mul_f32 v[76:77], v[74:75], v[42:43] op_sel:[0,1]
	v_pk_fma_f32 v[136:137], v[16:17], v[108:109], v[136:137] op_sel:[0,1,0]
	v_pk_fma_f32 v[138:139], v[16:17], v[124:125], v[138:139] op_sel:[0,1,0]
	v_pk_fma_f32 v[146:147], v[68:69], v[42:43], v[76:77] op_sel_hi:[1,0,1] neg_lo:[0,0,1]
	v_pk_fma_f32 v[136:137], v[58:59], v[110:111], v[136:137] op_sel_hi:[1,0,1]
	v_pk_fma_f32 v[138:139], v[58:59], v[126:127], v[138:139] op_sel_hi:[1,0,1]
	v_pk_add_f32 v[70:71], v[146:147], v[142:143]
	v_pk_fma_f32 v[136:137], v[18:19], v[110:111], v[136:137] op_sel:[0,1,0]
	v_pk_fma_f32 v[138:139], v[18:19], v[126:127], v[138:139] op_sel:[0,1,0]
	v_cvt_pk_bf16_f32 v150, v70, v71
	ds_write_b16 v103, v150 offset:7888
	ds_write_b16_d16_hi v103, v150 offset:8016
	s_waitcnt lgkmcnt(7)
	s_waitcnt lgkmcnt(6)
	v_pk_fma_f32 v[136:137], v[60:61], v[112:113], v[136:137] op_sel_hi:[1,0,1]
	v_pk_fma_f32 v[138:139], v[60:61], v[128:129], v[138:139] op_sel_hi:[1,0,1]
	v_pk_fma_f32 v[136:137], v[12:13], v[112:113], v[136:137] op_sel:[0,1,0]
	v_pk_fma_f32 v[138:139], v[12:13], v[128:129], v[138:139] op_sel:[0,1,0]
	v_pk_fma_f32 v[136:137], v[62:63], v[114:115], v[136:137] op_sel_hi:[1,0,1]
	v_pk_fma_f32 v[138:139], v[62:63], v[130:131], v[138:139] op_sel_hi:[1,0,1]
	v_pk_fma_f32 v[136:137], v[14:15], v[114:115], v[136:137] op_sel:[0,1,0]
	v_pk_fma_f32 v[138:139], v[14:15], v[130:131], v[138:139] op_sel:[0,1,0]
	s_waitcnt lgkmcnt(5)
	s_waitcnt lgkmcnt(4)
; __device__ __forceinline__ float ozero() { float z = 0.f; asm volatile("" : "+v"(z)); return z; }
; __device__ __forceinline__ bf f2bf(float f) { return (bf)(pk2(f, 0.f) & 0xFFFFu); }
; __device__ __forceinline__ f32x4 mfma16(bf16x8 a, bf16x8 b, f32x4 c) { return __builtin_amdgcn_mfma_f32_16x16x32_bf16(a, b, c, 0, 0, 0); }
; __device__ __forceinline__ void s5_pass2(const Params& p, int layer, int task, char* sm) {
;     ...
;       for (int l = 0; l < 32; l++) {
;         S5_STEP(sU + l * 16)
;         sS[l * 136 + lane] = f2bf(sr); sS[l * 136 + 64 + lane] = f2bf(si);
;       }
;       __builtin_amdgcn_wave_barrier();
; #pragma unroll
;       for (int mb = 0; mb < 2; mb++) {
;         const float z_ = ozero(); f32x4 acc = {z_, z_, z_, z_};
; #pragma unroll
;         for (int ks = 0; ks < 4; ks++) {
;           bf16x8 af = *(const bf16x8*)(sS + (16 * mb + (lane & 15)) * 136 + ks * 32 + 8 * (lane >> 4));
;           acc = mfma16(af, cf[ks], acc);
;         }
; #pragma unroll
;         for (int r = 0; r < 4; r++) {
;           const int l = 16 * mb + 4 * (lane >> 4) + r;
;           float y = acc[r] + dsk * sU[l * 16 + (lane & 15)];
;           p.YG[(tok0 + sub * 32 + l) * 512 + g * 16 + (lane & 15)] = f2bf(geluf_(y));
;         }
	v_pk_fma_f32 v[136:137], v[64:65], v[116:117], v[136:137] op_sel_hi:[1,0,1]
	v_pk_fma_f32 v[138:139], v[64:65], v[132:133], v[138:139] op_sel_hi:[1,0,1]
	v_pk_fma_f32 v[136:137], v[8:9], v[116:117], v[136:137] op_sel:[0,1,0]
	v_pk_fma_f32 v[138:139], v[8:9], v[132:133], v[138:139] op_sel:[0,1,0]
	v_pk_fma_f32 v[136:137], v[66:67], v[118:119], v[136:137] op_sel_hi:[1,0,1]
	v_pk_fma_f32 v[138:139], v[66:67], v[134:135], v[138:139] op_sel_hi:[1,0,1]
	v_pk_fma_f32 v[136:137], v[10:11], v[118:119], v[136:137] op_sel:[0,1,0]
	v_pk_fma_f32 v[138:139], v[10:11], v[134:135], v[138:139] op_sel:[0,1,0]
	v_pk_mul_f32 v[76:77], v[74:75], v[70:71] op_sel:[0,1]
	s_nop 0
	v_pk_fma_f32 v[146:147], v[68:69], v[70:71], v[76:77] op_sel_hi:[1,0,1] neg_lo:[0,0,1]
	s_nop 0
	v_pk_add_f32 v[42:43], v[146:147], v[136:137]
	s_nop 0
	v_cvt_pk_bf16_f32 v150, v42, v43
	s_nop 0
	ds_write_b16 v103, v150 offset:8160
	ds_write_b16_d16_hi v103, v150 offset:8288
	v_pk_mul_f32 v[76:77], v[74:75], v[42:43] op_sel:[0,1]
	s_nop 0
	v_pk_fma_f32 v[146:147], v[68:69], v[42:43], v[76:77] op_sel_hi:[1,0,1] neg_lo:[0,0,1]
	s_nop 0
	v_pk_add_f32 v[70:71], v[146:147], v[138:139]
	s_nop 0
	v_cvt_pk_bf16_f32 v150, v70, v71
	s_nop 0
	ds_write_b16 v103, v150 offset:8432
	ds_write_b16_d16_hi v103, v150 offset:8560
	s_waitcnt lgkmcnt(0)
	v_mov_b32_e32 v40, v145
	ds_read_b128 v[104:107], v100 offset:2048
	ds_read_b32 v76, v83
	v_mov_b32_e32 v41, v40
	v_mov_b32_e32 v42, v40
	v_mov_b32_e32 v43, v40
	s_lshl_b32 s9, s12, 5
	v_mov_b32_e32 v77, s5
	s_cmp_eq_u32 s8, 4
	s_waitcnt vmcnt(4) lgkmcnt(1)
	v_mfma_f32_16x16x32_bf16 v[40:43], v[104:107], v[24:27], v[40:43]
	ds_read_b128 v[104:107], v100 offset:2112
	s_waitcnt vmcnt(3) lgkmcnt(0)
	v_mfma_f32_16x16x32_bf16 v[40:43], v[104:107], v[28:31], v[40:43]
	ds_read_b128 v[104:107], v100 offset:2176
	s_waitcnt vmcnt(2) lgkmcnt(0)
	v_mfma_f32_16x16x32_bf16 v[40:43], v[104:107], v[32:35], v[40:43]
	ds_read_b128 v[104:107], v100 offset:2240
	s_waitcnt vmcnt(1) lgkmcnt(0)
	v_mfma_f32_16x16x32_bf16 v[40:43], v[104:107], v[36:39], v[40:43]
	s_waitcnt vmcnt(0)
	s_nop 6
	v_fma_f32 v40, v102, v76, v40
	v_mul_f32_e32 v76, 0x3d372713, v40
	v_mul_f32_e32 v76, v40, v76
	v_fma_f32 v76, v40, v76, v40
	v_mul_f32_e32 v76, 0x3f4c422a, v76
	v_add_f32_e32 v76, v76, v76
	v_mul_f32_e32 v76, 0x3fb8aa3b, v76
	v_exp_f32_e32 v76, v76
	v_mul_f32_e32 v40, 0.5, v40
	v_add_f32_e32 v76, 1.0, v76
	v_rcp_f32_e32 v76, v76
	s_nop 0
	v_fma_f32 v76, v76, -2.0, 1.0
	v_add_f32_e32 v76, 1.0, v76
	v_mul_f32_e32 v40, v40, v76
	v_or_b32_e32 v76, s9, v82
	v_or_b32_e32 v76, s4, v76
	v_lshlrev_b64 v[104:105], 10, v[76:77]
	v_cvt_pk_bf16_f32 v40, v40, s0
	v_lshl_add_u64 v[104:105], v[72:73], 0, v[104:105]
	global_store_short v[104:105], v40, off
	ds_read_b32 v40, v85
	s_waitcnt lgkmcnt(0)
	v_fma_f32 v40, v102, v40, v41
	v_mul_f32_e32 v41, 0x3d372713, v40
	v_mul_f32_e32 v41, v40, v41
	v_fma_f32 v41, v40, v41, v40
	v_mul_f32_e32 v41, 0x3f4c422a, v41
	v_add_f32_e32 v41, v41, v41
	v_mul_f32_e32 v41, 0x3fb8aa3b, v41
	v_exp_f32_e32 v41, v41
	v_mul_f32_e32 v40, 0.5, v40
	v_add_f32_e32 v41, 1.0, v41
	v_rcp_f32_e32 v41, v41
	s_nop 0
	v_fma_f32 v41, v41, -2.0, 1.0
	v_add_f32_e32 v41, 1.0, v41
	v_mul_f32_e32 v40, v40, v41
	v_cvt_pk_bf16_f32 v103, v40, s0
	v_or_b32_e32 v40, s9, v84
	v_or_b32_e32 v76, s4, v40
	v_lshlrev_b64 v[40:41], 10, v[76:77]
	v_lshl_add_u64 v[40:41], v[72:73], 0, v[40:41]
	global_store_short v[40:41], v103, off
	ds_read_b32 v40, v87
	s_waitcnt lgkmcnt(0)
	v_fma_f32 v40, v102, v40, v42
	v_mul_f32_e32 v41, 0x3d372713, v40
	v_mul_f32_e32 v41, v40, v41
	v_fma_f32 v41, v40, v41, v40
	v_mul_f32_e32 v41, 0x3f4c422a, v41
	v_add_f32_e32 v41, v41, v41
	v_mul_f32_e32 v41, 0x3fb8aa3b, v41
	v_exp_f32_e32 v41, v41
	v_mul_f32_e32 v40, 0.5, v40
	v_add_f32_e32 v41, 1.0, v41
	v_rcp_f32_e32 v41, v41
	s_nop 0
	v_fma_f32 v41, v41, -2.0, 1.0
	v_add_f32_e32 v41, 1.0, v41
	v_mul_f32_e32 v40, v40, v41
	v_cvt_pk_bf16_f32 v42, v40, s0
	v_or_b32_e32 v40, s9, v86
	v_or_b32_e32 v76, s4, v40
	v_lshlrev_b64 v[40:41], 10, v[76:77]
	v_lshl_add_u64 v[40:41], v[72:73], 0, v[40:41]
	global_store_short v[40:41], v42, off
	ds_read_b32 v40, v89
	s_waitcnt lgkmcnt(0)
; __device__ __forceinline__ float ozero() { float z = 0.f; asm volatile("" : "+v"(z)); return z; }
; __device__ __forceinline__ bf f2bf(float f) { return (bf)(pk2(f, 0.f) & 0xFFFFu); }
; __device__ __forceinline__ f32x4 mfma16(bf16x8 a, bf16x8 b, f32x4 c) { return __builtin_amdgcn_mfma_f32_16x16x32_bf16(a, b, c, 0, 0, 0); }
; __device__ __forceinline__ void s5_pass2(const Params& p, int layer, int task, char* sm) {
;     ...
;     for (int sub = 0; sub < 4; sub++) {
;     ...
;       for (int mb = 0; mb < 2; mb++) {
;         const float z_ = ozero(); f32x4 acc = {z_, z_, z_, z_};
; #pragma unroll
;         for (int ks = 0; ks < 4; ks++) {
;           bf16x8 af = *(const bf16x8*)(sS + (16 * mb + (lane & 15)) * 136 + ks * 32 + 8 * (lane >> 4));
;           acc = mfma16(af, cf[ks], acc);
;         }
; #pragma unroll
;         for (int r = 0; r < 4; r++) {
;           const int l = 16 * mb + 4 * (lane >> 4) + r;
;           float y = acc[r] + dsk * sU[l * 16 + (lane & 15)];
;           p.YG[(tok0 + sub * 32 + l) * 512 + g * 16 + (lane & 15)] = f2bf(geluf_(y));
;         }
;       }
	v_fmac_f32_e32 v43, v102, v40
	v_mul_f32_e32 v40, 0x3d372713, v43
	v_mul_f32_e32 v40, v43, v40
	v_fma_f32 v40, v43, v40, v43
	v_mul_f32_e32 v40, 0x3f4c422a, v40
	v_add_f32_e32 v40, v40, v40
	v_mul_f32_e32 v40, 0x3fb8aa3b, v40
	v_exp_f32_e32 v40, v40
	v_mul_f32_e32 v41, 0.5, v43
	v_add_f32_e32 v40, 1.0, v40
	v_rcp_f32_e32 v40, v40
	s_nop 0
	v_fma_f32 v40, v40, -2.0, 1.0
	v_add_f32_e32 v40, 1.0, v40
	v_mul_f32_e32 v40, v41, v40
	v_cvt_pk_bf16_f32 v42, v40, s0
	v_or_b32_e32 v40, s9, v88
	v_or_b32_e32 v76, s4, v40
	v_lshlrev_b64 v[40:41], 10, v[76:77]
	v_lshl_add_u64 v[40:41], v[72:73], 0, v[40:41]
	global_store_short v[40:41], v42, off
	v_mov_b32_e32 v40, v145
	ds_read_b128 v[104:107], v100 offset:6400
	ds_read_b32 v76, v91
	v_mov_b32_e32 v41, v40
	v_mov_b32_e32 v42, v40
	v_mov_b32_e32 v43, v40
	s_waitcnt lgkmcnt(1)
	s_nop 0
	v_mfma_f32_16x16x32_bf16 v[40:43], v[104:107], v[24:27], v[40:43]
	ds_read_b128 v[104:107], v100 offset:6464
	s_waitcnt lgkmcnt(0)
	v_mfma_f32_16x16x32_bf16 v[40:43], v[104:107], v[28:31], v[40:43]
	ds_read_b128 v[104:107], v100 offset:6528
	s_waitcnt lgkmcnt(0)
	v_mfma_f32_16x16x32_bf16 v[40:43], v[104:107], v[32:35], v[40:43]
	ds_read_b128 v[104:107], v100 offset:6592
	s_waitcnt lgkmcnt(0)
	v_mfma_f32_16x16x32_bf16 v[40:43], v[104:107], v[36:39], v[40:43]
	s_nop 7
	v_fma_f32 v40, v102, v76, v40
	v_mul_f32_e32 v76, 0x3d372713, v40
	v_mul_f32_e32 v76, v40, v76
	v_fma_f32 v76, v40, v76, v40
	v_mul_f32_e32 v76, 0x3f4c422a, v76
	v_add_f32_e32 v76, v76, v76
	v_mul_f32_e32 v76, 0x3fb8aa3b, v76
	v_exp_f32_e32 v76, v76
	v_mul_f32_e32 v40, 0.5, v40
	v_add_f32_e32 v76, 1.0, v76
	v_rcp_f32_e32 v76, v76
	s_nop 0
	v_fma_f32 v76, v76, -2.0, 1.0
	v_add_f32_e32 v76, 1.0, v76
	v_mul_f32_e32 v40, v40, v76
	v_or_b32_e32 v76, s9, v90
	v_or_b32_e32 v76, s4, v76
	v_lshlrev_b64 v[104:105], 10, v[76:77]
	v_cvt_pk_bf16_f32 v40, v40, s0
	v_lshl_add_u64 v[104:105], v[72:73], 0, v[104:105]
	global_store_short v[104:105], v40, off
	ds_read_b32 v40, v93
	s_waitcnt lgkmcnt(0)
	v_fma_f32 v40, v102, v40, v41
	v_mul_f32_e32 v41, 0x3d372713, v40
	v_mul_f32_e32 v41, v40, v41
	v_fma_f32 v41, v40, v41, v40
	v_mul_f32_e32 v41, 0x3f4c422a, v41
	v_add_f32_e32 v41, v41, v41
	v_mul_f32_e32 v41, 0x3fb8aa3b, v41
	v_exp_f32_e32 v41, v41
	v_mul_f32_e32 v40, 0.5, v40
	v_add_f32_e32 v41, 1.0, v41
	v_rcp_f32_e32 v41, v41
	s_nop 0
	v_fma_f32 v41, v41, -2.0, 1.0
	v_add_f32_e32 v41, 1.0, v41
	v_mul_f32_e32 v40, v40, v41
	v_cvt_pk_bf16_f32 v103, v40, s0
	v_or_b32_e32 v40, s9, v92
	v_or_b32_e32 v76, s4, v40
	v_lshlrev_b64 v[40:41], 10, v[76:77]
	v_lshl_add_u64 v[40:41], v[72:73], 0, v[40:41]
	global_store_short v[40:41], v103, off
	ds_read_b32 v40, v95
	s_waitcnt lgkmcnt(0)
	v_fma_f32 v40, v102, v40, v42
	v_mul_f32_e32 v41, 0x3d372713, v40
	v_mul_f32_e32 v41, v40, v41
	v_fma_f32 v41, v40, v41, v40
	v_mul_f32_e32 v41, 0x3f4c422a, v41
	v_add_f32_e32 v41, v41, v41
	v_mul_f32_e32 v41, 0x3fb8aa3b, v41
	v_exp_f32_e32 v41, v41
	v_mul_f32_e32 v40, 0.5, v40
	v_add_f32_e32 v41, 1.0, v41
	v_rcp_f32_e32 v41, v41
	s_nop 0
	v_fma_f32 v41, v41, -2.0, 1.0
	v_add_f32_e32 v41, 1.0, v41
	v_mul_f32_e32 v40, v40, v41
	v_cvt_pk_bf16_f32 v42, v40, s0
	v_or_b32_e32 v40, s9, v94
	v_or_b32_e32 v76, s4, v40
	v_lshlrev_b64 v[40:41], 10, v[76:77]
	v_lshl_add_u64 v[40:41], v[72:73], 0, v[40:41]
	global_store_short v[40:41], v42, off
	ds_read_b32 v40, v97
	s_waitcnt lgkmcnt(0)
	v_fmac_f32_e32 v43, v102, v40
	v_mul_f32_e32 v40, 0x3d372713, v43
	v_mul_f32_e32 v40, v43, v40
	v_fma_f32 v40, v43, v40, v43
	v_mul_f32_e32 v40, 0x3f4c422a, v40
	v_add_f32_e32 v40, v40, v40
	v_mul_f32_e32 v40, 0x3fb8aa3b, v40
	v_exp_f32_e32 v40, v40
	v_mul_f32_e32 v41, 0.5, v43
	v_add_f32_e32 v40, 1.0, v40
	v_rcp_f32_e32 v40, v40
	s_nop 0
	v_fma_f32 v40, v40, -2.0, 1.0
	v_add_f32_e32 v40, 1.0, v40
	v_mul_f32_e32 v40, v41, v40
	v_cvt_pk_bf16_f32 v42, v40, s0
	v_or_b32_e32 v40, s9, v96
	v_or_b32_e32 v76, s4, v40
	v_lshlrev_b64 v[40:41], 10, v[76:77]
	v_lshl_add_u64 v[40:41], v[72:73], 0, v[40:41]
	global_store_short v[40:41], v42, off
	s_cbranch_scc1 .LBB0_2053
	s_mov_b32 s12, s8
	s_branch .LBB0_2055
